# GEMM K-loops: priority inverted (load segments at prio 1, MFMA blocks at prio 0), on top of v24
# baseline (speedup 1.0000x reference)
.LBB0_220:
	ds_read_b128 v[148:151], v173
	ds_read_b128 v[152:155], v173 offset:1024
	ds_read_b128 v[156:159], v173 offset:2048
	ds_read_b128 v[160:163], v173 offset:3072
	ds_read_b128 v[164:167], v174
	ds_read_b128 v[180:183], v174 offset:1024
	ds_read_b128 v[184:187], v174 offset:2048
	ds_read_b128 v[188:191], v174 offset:3072
	s_add_u32 s52, s50, 0xfffc0080
	s_addc_u32 s53, s51, -1
	s_cmp_eq_u32 s66, 12
	s_cselect_b32 s55, s9, s53
	s_cselect_b32 s54, s11, s52
	s_cselect_b32 s53, s20, s45
	s_cselect_b32 s52, s33, s43
	v_lshl_add_u64 v[168:169], s[50:51], 0, v[140:141]
	s_add_i32 m0, s35, 0xc000
	ds_read_b128 v[192:195], v175
	ds_read_b128 v[196:199], v175 offset:1024
	ds_read_b128 v[204:207], v175 offset:2048
	ds_read_b128 v[208:211], v175 offset:3072
	ds_read_b128 v[212:215], v175 offset:4096
	ds_read_b128 v[216:219], v175 offset:5120
	ds_read_b128 v[220:223], v175 offset:6144
	ds_read_b128 v[224:227], v175 offset:7168
	global_load_lds_dwordx4 v[168:169], off
	v_lshl_add_u64 v[168:169], s[50:51], 0, v[142:143]
	s_add_i32 m0, s35, 0xe000
	s_nop 0
	global_load_lds_dwordx4 v[168:169], off
	s_waitcnt vmcnt(8)
	s_waitcnt lgkmcnt(0)
	s_barrier
	s_setprio 0
	s_waitcnt lgkmcnt(0)
	v_mfma_f32_16x16x32_bf16 v[124:127], v[148:151], v[192:195], v[124:127]
	v_mfma_f32_16x16x32_bf16 v[120:123], v[156:159], v[192:195], v[120:123]
	v_mfma_f32_16x16x32_bf16 v[108:111], v[148:151], v[204:207], v[108:111]
	v_mfma_f32_16x16x32_bf16 v[104:107], v[156:159], v[204:207], v[104:107]
	v_mfma_f32_16x16x32_bf16 v[92:95], v[148:151], v[212:215], v[92:95]
	v_mfma_f32_16x16x32_bf16 v[88:91], v[156:159], v[212:215], v[88:91]
	v_mfma_f32_16x16x32_bf16 v[76:79], v[148:151], v[220:223], v[76:79]
	v_mfma_f32_16x16x32_bf16 v[72:75], v[156:159], v[220:223], v[72:75]
	v_mfma_f32_16x16x32_bf16 v[124:127], v[152:155], v[196:199], v[124:127]
	v_mfma_f32_16x16x32_bf16 v[120:123], v[160:163], v[196:199], v[120:123]
	v_mfma_f32_16x16x32_bf16 v[108:111], v[152:155], v[208:211], v[108:111]
	v_mfma_f32_16x16x32_bf16 v[104:107], v[160:163], v[208:211], v[104:107]
	v_mfma_f32_16x16x32_bf16 v[92:95], v[152:155], v[216:219], v[92:95]
	v_mfma_f32_16x16x32_bf16 v[88:91], v[160:163], v[216:219], v[88:91]
	v_mfma_f32_16x16x32_bf16 v[76:79], v[152:155], v[224:227], v[76:79]
	v_mfma_f32_16x16x32_bf16 v[72:75], v[160:163], v[224:227], v[72:75]
	v_mfma_f32_16x16x32_bf16 v[116:119], v[164:167], v[192:195], v[116:119]
	v_mfma_f32_16x16x32_bf16 v[112:115], v[184:187], v[192:195], v[112:115]
	v_mfma_f32_16x16x32_bf16 v[100:103], v[164:167], v[204:207], v[100:103]
	v_mfma_f32_16x16x32_bf16 v[96:99], v[184:187], v[204:207], v[96:99]
	v_mfma_f32_16x16x32_bf16 v[84:87], v[164:167], v[212:215], v[84:87]
	v_mfma_f32_16x16x32_bf16 v[80:83], v[184:187], v[212:215], v[80:83]
	v_mfma_f32_16x16x32_bf16 v[68:71], v[164:167], v[220:223], v[68:71]
	v_mfma_f32_16x16x32_bf16 v[64:67], v[184:187], v[220:223], v[64:67]
	v_mfma_f32_16x16x32_bf16 v[116:119], v[180:183], v[196:199], v[116:119]
	v_mfma_f32_16x16x32_bf16 v[112:115], v[188:191], v[196:199], v[112:115]
	v_mfma_f32_16x16x32_bf16 v[100:103], v[180:183], v[208:211], v[100:103]
	v_mfma_f32_16x16x32_bf16 v[96:99], v[188:191], v[208:211], v[96:99]
	v_mfma_f32_16x16x32_bf16 v[84:87], v[180:183], v[216:219], v[84:87]
	v_mfma_f32_16x16x32_bf16 v[80:83], v[188:191], v[216:219], v[80:83]
	v_mfma_f32_16x16x32_bf16 v[68:71], v[180:183], v[224:227], v[68:71]
	v_mfma_f32_16x16x32_bf16 v[64:67], v[188:191], v[224:227], v[64:67]
	s_setprio 1
	s_barrier
	s_add_i32 s67, s63, s31
	v_lshl_add_u64 v[168:169], s[52:53], 0, v[130:131]
	s_mov_b32 m0, s67
	ds_read_b128 v[192:195], v175 offset:16384
	ds_read_b128 v[196:199], v175 offset:17408
	ds_read_b128 v[204:207], v175 offset:18432
	ds_read_b128 v[208:211], v175 offset:19456
	ds_read_b128 v[212:215], v175 offset:20480
	ds_read_b128 v[216:219], v175 offset:21504
	ds_read_b128 v[220:223], v175 offset:22528
	ds_read_b128 v[224:227], v175 offset:23552
	global_load_lds_dwordx4 v[168:169], off
	s_add_i32 m0, s67, 0x2000
	s_add_u32 s68, s52, 0x40000
	v_lshl_add_u64 v[200:201], s[52:53], 0, v[134:135]
	s_addc_u32 s69, s53, 0
	s_add_i32 s67, s64, s31
	global_load_lds_dwordx4 v[200:201], off
	v_lshl_add_u64 v[228:229], s[68:69], 0, v[130:131]
	s_mov_b32 m0, s67
	v_lshl_add_u64 v[230:231], s[54:55], 0, v[132:133]
	global_load_lds_dwordx4 v[228:229], off
	v_lshl_add_u64 v[228:229], s[68:69], 0, v[134:135]
	s_add_i32 m0, s67, 0x2000
	s_nop 0
	global_load_lds_dwordx4 v[228:229], off
	v_lshl_add_u64 v[228:229], s[54:55], 0, v[128:129]
	s_mov_b32 m0, s35
	s_nop 0
	global_load_lds_dwordx4 v[228:229], off
	s_mov_b32 m0, s37
	s_nop 0
	global_load_lds_dwordx4 v[230:231], off
	s_waitcnt vmcnt(8)
	s_waitcnt lgkmcnt(0)
	s_barrier
	s_setprio 0
	s_waitcnt lgkmcnt(0)
	v_mfma_f32_16x16x32_bf16 v[60:63], v[148:151], v[192:195], v[60:63]
	v_mfma_f32_16x16x32_bf16 v[56:59], v[156:159], v[192:195], v[56:59]
	v_mfma_f32_16x16x32_bf16 v[44:47], v[148:151], v[204:207], v[44:47]
	v_mfma_f32_16x16x32_bf16 v[40:43], v[156:159], v[204:207], v[40:43]
	v_mfma_f32_16x16x32_bf16 v[28:31], v[148:151], v[212:215], v[28:31]
	v_mfma_f32_16x16x32_bf16 v[24:27], v[156:159], v[212:215], v[24:27]
	v_mfma_f32_16x16x32_bf16 v[12:15], v[148:151], v[220:223], v[12:15]
	v_mfma_f32_16x16x32_bf16 v[8:11], v[156:159], v[220:223], v[8:11]
	v_mfma_f32_16x16x32_bf16 v[60:63], v[152:155], v[196:199], v[60:63]
	v_mfma_f32_16x16x32_bf16 v[56:59], v[160:163], v[196:199], v[56:59]
	v_mfma_f32_16x16x32_bf16 v[44:47], v[152:155], v[208:211], v[44:47]
	v_mfma_f32_16x16x32_bf16 v[40:43], v[160:163], v[208:211], v[40:43]
	v_mfma_f32_16x16x32_bf16 v[28:31], v[152:155], v[216:219], v[28:31]
	v_mfma_f32_16x16x32_bf16 v[24:27], v[160:163], v[216:219], v[24:27]
	v_mfma_f32_16x16x32_bf16 v[12:15], v[152:155], v[224:227], v[12:15]
	v_mfma_f32_16x16x32_bf16 v[8:11], v[160:163], v[224:227], v[8:11]
	v_mfma_f32_16x16x32_bf16 v[52:55], v[164:167], v[192:195], v[52:55]
	v_mfma_f32_16x16x32_bf16 v[48:51], v[184:187], v[192:195], v[48:51]
	v_mfma_f32_16x16x32_bf16 v[36:39], v[164:167], v[204:207], v[36:39]
	v_mfma_f32_16x16x32_bf16 v[32:35], v[184:187], v[204:207], v[32:35]
	v_mfma_f32_16x16x32_bf16 v[20:23], v[164:167], v[212:215], v[20:23]
	v_mfma_f32_16x16x32_bf16 v[16:19], v[184:187], v[212:215], v[16:19]
	v_mfma_f32_16x16x32_bf16 v[4:7], v[164:167], v[220:223], v[4:7]
	v_mfma_f32_16x16x32_bf16 v[0:3], v[184:187], v[220:223], v[0:3]
	v_mfma_f32_16x16x32_bf16 v[52:55], v[180:183], v[196:199], v[52:55]
	v_mfma_f32_16x16x32_bf16 v[48:51], v[188:191], v[196:199], v[48:51]
	v_mfma_f32_16x16x32_bf16 v[36:39], v[180:183], v[208:211], v[36:39]
	v_mfma_f32_16x16x32_bf16 v[32:35], v[188:191], v[208:211], v[32:35]
	v_mfma_f32_16x16x32_bf16 v[20:23], v[180:183], v[216:219], v[20:23]
	v_mfma_f32_16x16x32_bf16 v[16:19], v[188:191], v[216:219], v[16:19]
	v_mfma_f32_16x16x32_bf16 v[4:7], v[180:183], v[224:227], v[4:7]
	v_mfma_f32_16x16x32_bf16 v[0:3], v[188:191], v[224:227], v[0:3]
	s_setprio 1
	s_barrier
	s_add_i32 s67, 0, 0x18000
	v_add_u32_e32 v137, s67, v171
	s_add_i32 s68, 0, 0x1c000
	ds_read_b128 v[148:151], v137
	ds_read_b128 v[152:155], v137 offset:1024
	ds_read_b128 v[156:159], v137 offset:2048
	ds_read_b128 v[160:163], v137 offset:3072
	v_add_u32_e32 v137, s68, v171
	ds_read_b128 v[164:167], v137
	ds_read_b128 v[180:183], v137 offset:1024
	ds_read_b128 v[184:187], v137 offset:2048
	ds_read_b128 v[188:191], v137 offset:3072
	s_add_u32 s54, s54, 0x40000
	s_addc_u32 s55, s55, 0
	s_mov_b32 m0, s39
	v_lshl_add_u64 v[232:233], s[54:55], 0, v[128:129]
	ds_read_b128 v[192:195], v175 offset:32768
	ds_read_b128 v[196:199], v175 offset:33792
	ds_read_b128 v[204:207], v175 offset:34816
	ds_read_b128 v[208:211], v175 offset:35840
	ds_read_b128 v[212:215], v175 offset:36864
	ds_read_b128 v[216:219], v175 offset:37888
	ds_read_b128 v[220:223], v175 offset:38912
	ds_read_b128 v[224:227], v175 offset:39936
	global_load_lds_dwordx4 v[232:233], off
	v_lshl_add_u64 v[232:233], s[54:55], 0, v[132:133]
	s_mov_b32 m0, s41
	s_nop 0
	global_load_lds_dwordx4 v[232:233], off
	s_waitcnt vmcnt(8)
	s_waitcnt lgkmcnt(0)
	s_barrier
	s_setprio 0
	s_waitcnt lgkmcnt(0)
	v_mfma_f32_16x16x32_bf16 v[124:127], v[148:151], v[192:195], v[124:127]
	v_mfma_f32_16x16x32_bf16 v[120:123], v[156:159], v[192:195], v[120:123]
	v_mfma_f32_16x16x32_bf16 v[108:111], v[148:151], v[204:207], v[108:111]
	v_mfma_f32_16x16x32_bf16 v[104:107], v[156:159], v[204:207], v[104:107]
	v_mfma_f32_16x16x32_bf16 v[92:95], v[148:151], v[212:215], v[92:95]
	v_mfma_f32_16x16x32_bf16 v[88:91], v[156:159], v[212:215], v[88:91]
	v_mfma_f32_16x16x32_bf16 v[76:79], v[148:151], v[220:223], v[76:79]
	v_mfma_f32_16x16x32_bf16 v[72:75], v[156:159], v[220:223], v[72:75]
	v_mfma_f32_16x16x32_bf16 v[124:127], v[152:155], v[196:199], v[124:127]
	v_mfma_f32_16x16x32_bf16 v[120:123], v[160:163], v[196:199], v[120:123]
	v_mfma_f32_16x16x32_bf16 v[108:111], v[152:155], v[208:211], v[108:111]
	v_mfma_f32_16x16x32_bf16 v[104:107], v[160:163], v[208:211], v[104:107]
	v_mfma_f32_16x16x32_bf16 v[92:95], v[152:155], v[216:219], v[92:95]
	v_mfma_f32_16x16x32_bf16 v[88:91], v[160:163], v[216:219], v[88:91]
	v_mfma_f32_16x16x32_bf16 v[76:79], v[152:155], v[224:227], v[76:79]
	v_mfma_f32_16x16x32_bf16 v[72:75], v[160:163], v[224:227], v[72:75]
	v_mfma_f32_16x16x32_bf16 v[116:119], v[164:167], v[192:195], v[116:119]
	v_mfma_f32_16x16x32_bf16 v[112:115], v[184:187], v[192:195], v[112:115]
	v_mfma_f32_16x16x32_bf16 v[100:103], v[164:167], v[204:207], v[100:103]
	v_mfma_f32_16x16x32_bf16 v[96:99], v[184:187], v[204:207], v[96:99]
	v_mfma_f32_16x16x32_bf16 v[84:87], v[164:167], v[212:215], v[84:87]
	v_mfma_f32_16x16x32_bf16 v[80:83], v[184:187], v[212:215], v[80:83]
	v_mfma_f32_16x16x32_bf16 v[68:71], v[164:167], v[220:223], v[68:71]
	v_mfma_f32_16x16x32_bf16 v[64:67], v[184:187], v[220:223], v[64:67]
	v_mfma_f32_16x16x32_bf16 v[116:119], v[180:183], v[196:199], v[116:119]
	v_mfma_f32_16x16x32_bf16 v[112:115], v[188:191], v[196:199], v[112:115]
	v_mfma_f32_16x16x32_bf16 v[100:103], v[180:183], v[208:211], v[100:103]
	v_mfma_f32_16x16x32_bf16 v[96:99], v[188:191], v[208:211], v[96:99]
	v_mfma_f32_16x16x32_bf16 v[84:87], v[180:183], v[216:219], v[84:87]
	v_mfma_f32_16x16x32_bf16 v[80:83], v[188:191], v[216:219], v[80:83]
	v_mfma_f32_16x16x32_bf16 v[68:71], v[180:183], v[224:227], v[68:71]
	v_mfma_f32_16x16x32_bf16 v[64:67], v[188:191], v[224:227], v[64:67]
	s_setprio 1
	s_barrier
	s_add_i32 s54, s67, s31
	v_lshl_add_u64 v[168:169], v[168:169], 0, s[22:23]
	s_mov_b32 m0, s54
	ds_read_b128 v[192:195], v175 offset:49152
	ds_read_b128 v[196:199], v175 offset:50176
	ds_read_b128 v[204:207], v175 offset:51200
	ds_read_b128 v[208:211], v175 offset:52224
	ds_read_b128 v[212:215], v175 offset:53248
	ds_read_b128 v[216:219], v175 offset:54272
	ds_read_b128 v[220:223], v175 offset:55296
	ds_read_b128 v[224:227], v175 offset:56320
	global_load_lds_dwordx4 v[168:169], off
	s_add_i32 m0, s54, 0x2000
	s_add_u32 s52, s52, 0x40080
	v_lshl_add_u64 v[168:169], v[200:201], 0, s[22:23]
	s_addc_u32 s53, s53, 0
	s_add_i32 s54, s68, s31
	global_load_lds_dwordx4 v[168:169], off
	v_lshl_add_u64 v[168:169], s[52:53], 0, v[130:131]
	s_mov_b32 m0, s54
	s_nop 0
	global_load_lds_dwordx4 v[168:169], off
	v_lshl_add_u64 v[168:169], s[52:53], 0, v[134:135]
	s_add_i32 m0, s54, 0x2000
	s_nop 0
	global_load_lds_dwordx4 v[168:169], off
	v_lshl_add_u64 v[168:169], v[228:229], 0, s[22:23]
	s_mov_b32 m0, s60
	s_nop 0
	global_load_lds_dwordx4 v[168:169], off
	v_lshl_add_u64 v[168:169], v[230:231], 0, s[22:23]
	s_mov_b32 m0, s61
	s_nop 0
	global_load_lds_dwordx4 v[168:169], off
	s_waitcnt vmcnt(8)
	s_waitcnt lgkmcnt(0)
	s_barrier
	s_setprio 0
	s_waitcnt lgkmcnt(0)
	v_mfma_f32_16x16x32_bf16 v[60:63], v[148:151], v[192:195], v[60:63]
	v_mfma_f32_16x16x32_bf16 v[56:59], v[156:159], v[192:195], v[56:59]
	v_mfma_f32_16x16x32_bf16 v[44:47], v[148:151], v[204:207], v[44:47]
	v_mfma_f32_16x16x32_bf16 v[40:43], v[156:159], v[204:207], v[40:43]
	v_mfma_f32_16x16x32_bf16 v[28:31], v[148:151], v[212:215], v[28:31]
	v_mfma_f32_16x16x32_bf16 v[24:27], v[156:159], v[212:215], v[24:27]
	v_mfma_f32_16x16x32_bf16 v[12:15], v[148:151], v[220:223], v[12:15]
	v_mfma_f32_16x16x32_bf16 v[8:11], v[156:159], v[220:223], v[8:11]
	v_mfma_f32_16x16x32_bf16 v[60:63], v[152:155], v[196:199], v[60:63]
	v_mfma_f32_16x16x32_bf16 v[56:59], v[160:163], v[196:199], v[56:59]
	v_mfma_f32_16x16x32_bf16 v[44:47], v[152:155], v[208:211], v[44:47]
	v_mfma_f32_16x16x32_bf16 v[40:43], v[160:163], v[208:211], v[40:43]
	v_mfma_f32_16x16x32_bf16 v[28:31], v[152:155], v[216:219], v[28:31]
	v_mfma_f32_16x16x32_bf16 v[24:27], v[160:163], v[216:219], v[24:27]
	v_mfma_f32_16x16x32_bf16 v[12:15], v[152:155], v[224:227], v[12:15]
	v_mfma_f32_16x16x32_bf16 v[8:11], v[160:163], v[224:227], v[8:11]
	v_mfma_f32_16x16x32_bf16 v[52:55], v[164:167], v[192:195], v[52:55]
	v_mfma_f32_16x16x32_bf16 v[48:51], v[184:187], v[192:195], v[48:51]
	v_mfma_f32_16x16x32_bf16 v[36:39], v[164:167], v[204:207], v[36:39]
	v_mfma_f32_16x16x32_bf16 v[32:35], v[184:187], v[204:207], v[32:35]
	v_mfma_f32_16x16x32_bf16 v[20:23], v[164:167], v[212:215], v[20:23]
	v_mfma_f32_16x16x32_bf16 v[16:19], v[184:187], v[212:215], v[16:19]
	v_mfma_f32_16x16x32_bf16 v[4:7], v[164:167], v[220:223], v[4:7]
	v_mfma_f32_16x16x32_bf16 v[0:3], v[184:187], v[220:223], v[0:3]
	v_mfma_f32_16x16x32_bf16 v[52:55], v[180:183], v[196:199], v[52:55]
	v_mfma_f32_16x16x32_bf16 v[48:51], v[188:191], v[196:199], v[48:51]
	v_mfma_f32_16x16x32_bf16 v[36:39], v[180:183], v[208:211], v[36:39]
	v_mfma_f32_16x16x32_bf16 v[32:35], v[188:191], v[208:211], v[32:35]
	v_mfma_f32_16x16x32_bf16 v[20:23], v[180:183], v[216:219], v[20:23]
	v_mfma_f32_16x16x32_bf16 v[16:19], v[188:191], v[216:219], v[16:19]
	v_mfma_f32_16x16x32_bf16 v[4:7], v[180:183], v[224:227], v[4:7]
	v_mfma_f32_16x16x32_bf16 v[0:3], v[188:191], v[224:227], v[0:3]
	s_setprio 1
	s_barrier
	s_add_i32 s66, s66, 2
	s_add_u32 s50, s50, 0x100
	s_addc_u32 s51, s51, 0
	s_add_u32 s43, s43, 0x100
	s_addc_u32 s45, s45, 0
	s_cmp_gt_u32 s66, 13
	s_cbranch_scc0 .LBB0_220
	s_and_b64 vcc, exec, s[24:25]
	s_cbranch_vccz .LBB0_223
	s_barrier
.LBB0_223:
	s_setprio 0
	v_lshl_add_u32 v164, s10, 8, v170
	v_ashrrev_i32_e32 v165, 31, v164
	v_or_b32_e32 v162, 16, v164
	v_lshlrev_b64 v[148:149], 6, v[164:165]
	v_ashrrev_i32_e32 v163, 31, v162
	v_or_b32_e32 v160, 32, v164
	v_lshl_add_u64 v[148:149], v[138:139], 0, v[148:149]
	v_lshlrev_b64 v[150:151], 6, v[162:163]
	v_ashrrev_i32_e32 v161, 31, v160
	v_or_b32_e32 v158, 48, v164
	v_lshl_add_u64 v[150:151], v[138:139], 0, v[150:151]
	global_load_dwordx4 v[166:169], v[148:149], off
	global_load_dwordx4 v[182:185], v[150:151], off
	v_lshlrev_b64 v[148:149], 6, v[160:161]
	v_ashrrev_i32_e32 v159, 31, v158
	v_lshl_add_u64 v[148:149], v[138:139], 0, v[148:149]
	v_lshlrev_b64 v[150:151], 6, v[158:159]
	v_lshl_add_u64 v[150:151], v[138:139], 0, v[150:151]
	global_load_dwordx4 v[186:189], v[148:149], off
	global_load_dwordx4 v[190:193], v[150:151], off
	v_add_u32_e32 v156, 0x80, v164
	v_ashrrev_i32_e32 v157, 31, v156
	v_lshlrev_b64 v[148:149], 6, v[156:157]
	v_add_u32_e32 v154, 0x90, v164
	v_lshl_add_u64 v[148:149], v[138:139], 0, v[148:149]
	v_ashrrev_i32_e32 v155, 31, v154
	global_load_dwordx4 v[194:197], v[148:149], off
	v_lshlrev_b64 v[148:149], 6, v[154:155]
	v_lshl_add_u64 v[148:149], v[138:139], 0, v[148:149]
	global_load_dwordx4 v[198:201], v[148:149], off
	v_and_b32_e32 v148, 64, v176
	v_xor_b32_e32 v137, 16, v176
	v_add_u32_e32 v151, 64, v148
	v_xor_b32_e32 v149, 32, v176
	v_add_u32_e32 v150, 0xa0, v164
	v_cmp_lt_i32_e32 vcc, v137, v151
	v_add_u32_e32 v148, 0xb0, v164
	s_cmp_gt_i32 s8, 7
	v_cndmask_b32_e32 v137, v176, v137, vcc
	v_cmp_lt_i32_e32 vcc, v149, v151
	v_ashrrev_i32_e32 v151, 31, v150
	v_lshlrev_b64 v[152:153], 6, v[150:151]
	v_lshl_add_u64 v[152:153], v[138:139], 0, v[152:153]
	global_load_dwordx4 v[204:207], v[152:153], off
	v_cndmask_b32_e32 v179, v176, v149, vcc
	v_ashrrev_i32_e32 v149, 31, v148
	v_lshlrev_b64 v[152:153], 6, v[148:149]
	v_lshl_add_u64 v[152:153], v[138:139], 0, v[152:153]
	global_load_dwordx4 v[208:211], v[152:153], off
	v_lshlrev_b32_e32 v180, 2, v137
	v_lshlrev_b32_e32 v179, 2, v179
	s_cselect_b64 s[10:11], -1, 0
	s_and_b64 s[50:51], s[10:11], exec
	s_cselect_b32 s20, -8, 0
	s_cselect_b32 s9, 0x8000000, 0
	s_add_i32 s20, s20, s8
	s_add_u32 s50, s58, s9
	s_addc_u32 s51, s59, 0
	s_cmp_lt_i32 s8, 8
	s_waitcnt vmcnt(0)
	v_mov_b32_e32 v152, v167
	v_mov_b32_e32 v153, v168
	v_mov_b32_e32 v167, v169
	v_pk_add_f32 v[152:153], v[152:153], v[166:167]
	v_add_f32_e32 v137, v182, v183
	v_add_f32_e32 v152, v152, v153
	v_add_f32_e32 v167, v186, v187
	v_add_f32_e32 v168, v188, v189
	v_add_f32_e32 v153, v167, v168
	ds_bpermute_b32 v168, v180, v152
	v_add_f32_e32 v166, v184, v185
	v_add_f32_e32 v169, v190, v191
	v_add_f32_e32 v181, v192, v193
	v_add_f32_e32 v137, v137, v166
	s_waitcnt lgkmcnt(0)
	v_add_f32_e32 v152, v152, v168
	v_add_f32_e32 v166, v169, v181
	ds_bpermute_b32 v181, v180, v137
	ds_bpermute_b32 v168, v179, v152
	v_add_f32_e32 v182, v194, v195
	v_add_f32_e32 v183, v196, v197
	v_add_f32_e32 v184, v198, v199
	s_waitcnt lgkmcnt(1)
	v_add_f32_e32 v193, v137, v181
	s_waitcnt lgkmcnt(0)
	v_add_f32_e32 v137, v152, v168
	v_fmamk_f32 v137, v137, 0x3a800000, v177
	v_add_f32_e32 v185, v200, v201
	v_add_f32_e32 v167, v182, v183
	ds_bpermute_b32 v182, v180, v153
	v_add_f32_e32 v169, v184, v185
	ds_bpermute_b32 v183, v180, v166
	ds_bpermute_b32 v184, v180, v167
	s_waitcnt lgkmcnt(2)
	v_add_f32_e32 v191, v153, v182
	v_mov_b64_e32 v[198:199], s[30:31]
	s_waitcnt lgkmcnt(1)
	v_add_f32_e32 v189, v166, v183
	s_waitcnt lgkmcnt(0)
	v_add_f32_e32 v187, v167, v184
	ds_bpermute_b32 v194, v179, v193
	ds_bpermute_b32 v192, v179, v191
	ds_bpermute_b32 v190, v179, v189
	ds_bpermute_b32 v188, v179, v187
	v_rsq_f32_e32 v168, v137
	s_nop 0
	v_pk_mul_f32 v[124:125], v[124:125], v[168:169] op_sel_hi:[1,0]
	v_add_f32_e32 v152, v204, v205
	v_and_b32_e32 v197, 0x7fffffff, v125
	v_and_b32_e32 v196, 0x7fffffff, v124
	v_pk_fma_f32 v[196:197], v[196:197], s[26:27], 1.0 op_sel_hi:[1,0,0]
	v_pk_mul_f32 v[204:205], v[124:125], v[124:125]
	v_rcp_f32_e32 v196, v196
	v_rcp_f32_e32 v197, v197
	v_pk_mul_f32 v[204:205], v[204:205], s[40:41] op_sel_hi:[1,0]
	v_pk_mul_f32 v[126:127], v[126:127], v[168:169] op_sel_hi:[1,0]
	v_exp_f32_e32 v204, v204
	v_pk_fma_f32 v[200:201], v[196:197], s[28:29], v[198:199] op_sel_hi:[1,0,0]
	v_exp_f32_e32 v205, v205
	v_pk_fma_f32 v[200:201], v[196:197], v[200:201], s[34:35] op_sel_hi:[1,1,0]
	ds_bpermute_b32 v137, v180, v169
	v_add_f32_e32 v153, v206, v207
	v_pk_fma_f32 v[200:201], v[196:197], v[200:201], s[36:37] op_sel_hi:[1,1,0]
	v_and_b32_e32 v207, 0x7fffffff, v127
	v_and_b32_e32 v206, 0x7fffffff, v126
	v_pk_fma_f32 v[200:201], v[196:197], v[200:201], s[38:39] op_sel_hi:[1,1,0]
	v_pk_fma_f32 v[206:207], v[206:207], s[26:27], 1.0 op_sel_hi:[1,0,0]
	v_pk_mul_f32 v[196:197], v[196:197], v[200:201]
	v_rcp_f32_e32 v206, v206
	v_rcp_f32_e32 v207, v207
	v_pk_mul_f32 v[196:197], v[204:205], v[196:197]
	v_cmp_gt_f32_e32 vcc, 0, v124
	v_pk_mul_f32 v[204:205], v[124:125], v[196:197]
	v_pk_fma_f32 v[196:197], v[124:125], v[196:197], v[124:125] neg_lo:[1,0,0] neg_hi:[1,0,0]
	s_waitcnt lgkmcnt(0)
	v_add_f32_e32 v185, v169, v137
	v_pk_mul_f32 v[200:201], v[126:127], v[126:127]
	v_cndmask_b32_e32 v137, v196, v204, vcc
	v_cmp_gt_f32_e32 vcc, 0, v125
	v_pk_mul_f32 v[122:123], v[122:123], v[168:169] op_sel_hi:[1,0]
	v_pk_mul_f32 v[120:121], v[120:121], v[168:169] op_sel_hi:[1,0]
	v_cndmask_b32_e32 v169, v197, v205, vcc
	v_pk_fma_f32 v[124:125], v[206:207], s[28:29], v[198:199] op_sel_hi:[1,0,0]
	v_pk_mul_f32 v[196:197], v[200:201], s[40:41] op_sel_hi:[1,0]
	v_pk_fma_f32 v[124:125], v[206:207], v[124:125], s[34:35] op_sel_hi:[1,1,0]
	v_exp_f32_e32 v196, v196
	v_exp_f32_e32 v197, v197
	v_pk_fma_f32 v[124:125], v[206:207], v[124:125], s[36:37] op_sel_hi:[1,1,0]
	v_and_b32_e32 v201, 0x7fffffff, v121
	v_and_b32_e32 v200, 0x7fffffff, v120
	v_pk_fma_f32 v[124:125], v[206:207], v[124:125], s[38:39] op_sel_hi:[1,1,0]
	v_pk_fma_f32 v[200:201], v[200:201], s[26:27], 1.0 op_sel_hi:[1,0,0]
	v_pk_mul_f32 v[124:125], v[206:207], v[124:125]
	v_rcp_f32_e32 v200, v200
	v_rcp_f32_e32 v201, v201
	v_pk_mul_f32 v[124:125], v[196:197], v[124:125]
	v_cmp_gt_f32_e32 vcc, 0, v126
	v_pk_mul_f32 v[196:197], v[126:127], v[124:125]
	v_pk_fma_f32 v[124:125], v[126:127], v[124:125], v[126:127] neg_lo:[1,0,0] neg_hi:[1,0,0]
	v_add_f32_e32 v166, v208, v209
	v_cndmask_b32_e32 v195, v124, v196, vcc
	v_cmp_gt_f32_e32 vcc, 0, v127
	v_pk_mul_f32 v[126:127], v[120:121], v[120:121]
	v_add_f32_e32 v167, v210, v211
	v_cndmask_b32_e32 v204, v125, v197, vcc
	v_pk_fma_f32 v[124:125], v[200:201], s[28:29], v[198:199] op_sel_hi:[1,0,0]
	v_pk_mul_f32 v[126:127], v[126:127], s[40:41] op_sel_hi:[1,0]
	v_pk_fma_f32 v[124:125], v[200:201], v[124:125], s[34:35] op_sel_hi:[1,1,0]
	v_exp_f32_e32 v126, v126
	v_pk_fma_f32 v[124:125], v[200:201], v[124:125], s[36:37] op_sel_hi:[1,1,0]
	v_exp_f32_e32 v127, v127
	v_pk_fma_f32 v[124:125], v[200:201], v[124:125], s[38:39] op_sel_hi:[1,1,0]
	v_add_f32_e32 v152, v152, v153
	v_pk_mul_f32 v[124:125], v[200:201], v[124:125]
	v_and_b32_e32 v201, 0x7fffffff, v123
	v_and_b32_e32 v200, 0x7fffffff, v122
	v_pk_fma_f32 v[200:201], v[200:201], s[26:27], 1.0 op_sel_hi:[1,0,0]
	v_pk_mul_f32 v[124:125], v[126:127], v[124:125]
	v_rcp_f32_e32 v200, v200
	v_rcp_f32_e32 v201, v201
	v_add_f32_e32 v166, v166, v167
	v_pk_mul_f32 v[126:127], v[120:121], v[124:125]
	v_pk_fma_f32 v[124:125], v[120:121], v[124:125], v[120:121] neg_lo:[1,0,0] neg_hi:[1,0,0]
	v_cmp_gt_f32_e32 vcc, 0, v120
	ds_bpermute_b32 v153, v180, v152
	ds_bpermute_b32 v167, v180, v166
	v_pk_mul_f32 v[196:197], v[122:123], v[122:123]
	v_cndmask_b32_e32 v126, v124, v126, vcc
	v_cmp_gt_f32_e32 vcc, 0, v121
	v_pk_fma_f32 v[120:121], v[200:201], s[28:29], v[198:199] op_sel_hi:[1,0,0]
	s_waitcnt lgkmcnt(1)
	v_add_f32_e32 v183, v152, v153
	v_cndmask_b32_e32 v127, v125, v127, vcc
	v_pk_mul_f32 v[124:125], v[196:197], s[40:41] op_sel_hi:[1,0]
	v_pk_fma_f32 v[120:121], v[200:201], v[120:121], s[34:35] op_sel_hi:[1,1,0]
	v_exp_f32_e32 v124, v124
	v_exp_f32_e32 v125, v125
	v_pk_fma_f32 v[120:121], v[200:201], v[120:121], s[36:37] op_sel_hi:[1,1,0]
	s_waitcnt lgkmcnt(0)
	v_add_f32_e32 v181, v166, v167
	v_pk_fma_f32 v[120:121], v[200:201], v[120:121], s[38:39] op_sel_hi:[1,1,0]
	ds_bpermute_b32 v186, v179, v185
	v_pk_mul_f32 v[120:121], v[200:201], v[120:121]
	ds_bpermute_b32 v184, v179, v183
	ds_bpermute_b32 v182, v179, v181
	v_pk_mul_f32 v[120:121], v[124:125], v[120:121]
	v_lshl_or_b32 v152, s20, 8, v172
	v_pk_mul_f32 v[124:125], v[122:123], v[120:121]
	v_pk_fma_f32 v[120:121], v[122:123], v[120:121], v[122:123] neg_lo:[1,0,0] neg_hi:[1,0,0]
	v_cmp_gt_f32_e32 vcc, 0, v122
	v_ashrrev_i32_e32 v153, 31, v152
	v_lshl_add_u64 v[152:153], v[152:153], 1, s[50:51]
	v_cndmask_b32_e32 v124, v120, v124, vcc
	v_cmp_gt_f32_e32 vcc, 0, v123
	v_lshlrev_b64 v[166:167], 12, v[164:165]
	v_lshl_add_u64 v[166:167], v[152:153], 0, v[166:167]
	v_cndmask_b32_e32 v123, v121, v125, vcc
	v_cvt_pk_bf16_f32 v120, v137, v169
	v_cvt_pk_bf16_f32 v121, v195, v204
	v_cvt_pk_bf16_f32 v122, v126, v127
	v_cvt_pk_bf16_f32 v123, v124, v123
	v_mov_b32_e32 v124, 0
	v_mov_b32_e32 v125, 0
	global_store_dwordx4 v[166:167], v[120:123], off
	s_cbranch_scc1 .LBB0_225
	v_and_b32_e32 v125, 16, v120
	v_and_b32_e32 v124, 0xffff0000, v120
	v_lshlrev_b32_e32 v197, 16, v121
	v_lshlrev_b32_e32 v196, 16, v122
	v_and_b32_e32 v126, 0xffff0000, v121
	v_mov_b32_e32 v127, v124
	v_pk_mov_b32 v[204:205], v[196:197], v[124:125] op_sel:[1,0]
	v_lshlrev_b32_e32 v120, 16, v120
	v_and_b32_e32 v198, 0xffff0000, v123
	v_mov_b32_e32 v199, v126
	v_and_b32_e32 v122, 0xffff0000, v122
	v_lshlrev_b32_e32 v200, 16, v123
	v_mov_b32_e32 v123, v197
	v_mov_b32_e32 v121, v126
	v_mov_b32_e32 v201, v126
	v_pk_add_f32 v[206:207], v[126:127], v[204:205]
	v_pk_mul_f32 v[126:127], v[126:127], v[204:205]
	v_pk_add_f32 v[124:125], v[120:121], v[124:125] op_sel_hi:[0,1]
	v_mov_b32_e32 v207, v127
	v_pk_add_f32 v[126:127], v[196:197], v[122:123]
	v_pk_mul_f32 v[204:205], v[196:197], v[196:197]
	v_mov_b32_e32 v123, v198
	v_mul_f32_e32 v125, v120, v120
	v_mov_b32_e32 v127, v205
	v_pk_add_f32 v[204:205], v[198:199], v[200:201]
	v_pk_mul_f32 v[120:121], v[198:199], v[120:121]
	v_mov_b32_e32 v197, v200
	v_pk_mul_f32 v[122:123], v[122:123], v[122:123]
	v_mov_b32_e32 v205, v121
	v_pk_fma_f32 v[122:123], v[196:197], v[196:197], v[122:123]
	v_pk_add_f32 v[124:125], v[124:125], v[206:207]
	v_pk_add_f32 v[120:121], v[126:127], v[204:205]
	v_pk_add_f32 v[122:123], v[122:123], v[122:123] op_sel_hi:[0,1]
	v_pk_add_f32 v[120:121], v[124:125], v[120:121]
	v_mov_b32_e32 v137, v123
	v_pk_add_f32 v[124:125], v[120:121], v[136:137]

.LBB0_401:
	ds_read_b128 v[128:131], v189
	ds_read_b128 v[132:135], v189 offset:1024
	ds_read_b128 v[136:139], v189 offset:2048
	ds_read_b128 v[140:143], v189 offset:3072
	ds_read_b128 v[144:147], v190
	ds_read_b128 v[148:151], v190 offset:1024
	ds_read_b128 v[168:171], v190 offset:2048
	ds_read_b128 v[172:175], v190 offset:3072
	s_add_u32 s4, s42, 0xfff80080
	s_addc_u32 s5, s43, -1
	s_cmp_eq_u32 s59, 28
	s_cselect_b32 s45, s35, s5
	s_cselect_b32 s44, s41, s4
	s_cselect_b32 s5, s31, s58
	s_cselect_b32 s4, s56, s57
	v_lshl_add_u64 v[184:185], s[42:43], 0, v[160:161]
	s_add_i32 m0, s47, 0xc000
	ds_read_b128 v[176:179], v191
	ds_read_b128 v[180:183], v191 offset:1024
	ds_read_b128 v[194:197], v191 offset:2048
	ds_read_b128 v[198:201], v191 offset:3072
	ds_read_b128 v[204:207], v191 offset:4096
	ds_read_b128 v[208:211], v191 offset:5120
	ds_read_b128 v[212:215], v191 offset:6144
	ds_read_b128 v[216:219], v191 offset:7168
	global_load_lds_dwordx4 v[184:185], off
	v_lshl_add_u64 v[184:185], s[42:43], 0, v[162:163]
	s_add_i32 m0, s47, 0xe000
	s_nop 0
	global_load_lds_dwordx4 v[184:185], off
	s_waitcnt vmcnt(8)
	s_waitcnt lgkmcnt(0)
	s_barrier
	s_setprio 0
	s_waitcnt lgkmcnt(0)
	v_mfma_f32_16x16x32_bf16 v[124:127], v[128:131], v[176:179], v[124:127]
	v_mfma_f32_16x16x32_bf16 v[120:123], v[136:139], v[176:179], v[120:123]
	v_mfma_f32_16x16x32_bf16 v[108:111], v[128:131], v[194:197], v[108:111]
	v_mfma_f32_16x16x32_bf16 v[104:107], v[136:139], v[194:197], v[104:107]
	v_mfma_f32_16x16x32_bf16 v[92:95], v[128:131], v[204:207], v[92:95]
	v_mfma_f32_16x16x32_bf16 v[88:91], v[136:139], v[204:207], v[88:91]
	v_mfma_f32_16x16x32_bf16 v[76:79], v[128:131], v[212:215], v[76:79]
	v_mfma_f32_16x16x32_bf16 v[72:75], v[136:139], v[212:215], v[72:75]
	v_mfma_f32_16x16x32_bf16 v[124:127], v[132:135], v[180:183], v[124:127]
	v_mfma_f32_16x16x32_bf16 v[120:123], v[140:143], v[180:183], v[120:123]
	v_mfma_f32_16x16x32_bf16 v[108:111], v[132:135], v[198:201], v[108:111]
	v_mfma_f32_16x16x32_bf16 v[104:107], v[140:143], v[198:201], v[104:107]
	v_mfma_f32_16x16x32_bf16 v[92:95], v[132:135], v[208:211], v[92:95]
	v_mfma_f32_16x16x32_bf16 v[88:91], v[140:143], v[208:211], v[88:91]
	v_mfma_f32_16x16x32_bf16 v[76:79], v[132:135], v[216:219], v[76:79]
	v_mfma_f32_16x16x32_bf16 v[72:75], v[140:143], v[216:219], v[72:75]
	v_mfma_f32_16x16x32_bf16 v[116:119], v[144:147], v[176:179], v[116:119]
	v_mfma_f32_16x16x32_bf16 v[112:115], v[168:171], v[176:179], v[112:115]
	v_mfma_f32_16x16x32_bf16 v[100:103], v[144:147], v[194:197], v[100:103]
	v_mfma_f32_16x16x32_bf16 v[96:99], v[168:171], v[194:197], v[96:99]
	v_mfma_f32_16x16x32_bf16 v[84:87], v[144:147], v[204:207], v[84:87]
	v_mfma_f32_16x16x32_bf16 v[80:83], v[168:171], v[204:207], v[80:83]
	v_mfma_f32_16x16x32_bf16 v[68:71], v[144:147], v[212:215], v[68:71]
	v_mfma_f32_16x16x32_bf16 v[64:67], v[168:171], v[212:215], v[64:67]
	v_mfma_f32_16x16x32_bf16 v[116:119], v[148:151], v[180:183], v[116:119]
	v_mfma_f32_16x16x32_bf16 v[112:115], v[172:175], v[180:183], v[112:115]
	v_mfma_f32_16x16x32_bf16 v[100:103], v[148:151], v[198:201], v[100:103]
	v_mfma_f32_16x16x32_bf16 v[96:99], v[172:175], v[198:201], v[96:99]
	v_mfma_f32_16x16x32_bf16 v[84:87], v[148:151], v[208:211], v[84:87]
	v_mfma_f32_16x16x32_bf16 v[80:83], v[172:175], v[208:211], v[80:83]
	v_mfma_f32_16x16x32_bf16 v[68:71], v[148:151], v[216:219], v[68:71]
	v_mfma_f32_16x16x32_bf16 v[64:67], v[172:175], v[216:219], v[64:67]
	s_setprio 1
	s_barrier
	s_add_i32 s60, s53, s46
	v_lshl_add_u64 v[184:185], s[4:5], 0, v[154:155]
	s_mov_b32 m0, s60
	ds_read_b128 v[176:179], v191 offset:16384
	ds_read_b128 v[180:183], v191 offset:17408
	ds_read_b128 v[194:197], v191 offset:18432
	ds_read_b128 v[198:201], v191 offset:19456
	ds_read_b128 v[204:207], v191 offset:20480
	ds_read_b128 v[208:211], v191 offset:21504
	ds_read_b128 v[212:215], v191 offset:22528
	ds_read_b128 v[216:219], v191 offset:23552
	global_load_lds_dwordx4 v[184:185], off
	s_add_i32 m0, s60, 0x2000
	s_add_u32 s60, s4, 0x80000
	v_lshl_add_u64 v[220:221], s[4:5], 0, v[158:159]
	s_addc_u32 s61, s5, 0
	s_add_i32 s62, s54, s46
	global_load_lds_dwordx4 v[220:221], off
	v_lshl_add_u64 v[222:223], s[60:61], 0, v[154:155]
	s_mov_b32 m0, s62
	v_lshl_add_u64 v[224:225], s[44:45], 0, v[156:157]
	global_load_lds_dwordx4 v[222:223], off
	v_lshl_add_u64 v[222:223], s[60:61], 0, v[158:159]
	s_add_i32 m0, s62, 0x2000
	s_nop 0
	global_load_lds_dwordx4 v[222:223], off
	v_lshl_add_u64 v[222:223], s[44:45], 0, v[152:153]
	s_mov_b32 m0, s47
	s_nop 0
	global_load_lds_dwordx4 v[222:223], off
	s_mov_b32 m0, s48
	s_nop 0
	global_load_lds_dwordx4 v[224:225], off
	s_waitcnt vmcnt(8)
	s_waitcnt lgkmcnt(0)
	s_barrier
	s_setprio 0
	s_waitcnt lgkmcnt(0)
	v_mfma_f32_16x16x32_bf16 v[60:63], v[128:131], v[176:179], v[60:63]
	v_mfma_f32_16x16x32_bf16 v[56:59], v[136:139], v[176:179], v[56:59]
	v_mfma_f32_16x16x32_bf16 v[44:47], v[128:131], v[194:197], v[44:47]
	v_mfma_f32_16x16x32_bf16 v[40:43], v[136:139], v[194:197], v[40:43]
	v_mfma_f32_16x16x32_bf16 v[28:31], v[128:131], v[204:207], v[28:31]
	v_mfma_f32_16x16x32_bf16 v[24:27], v[136:139], v[204:207], v[24:27]
	v_mfma_f32_16x16x32_bf16 v[12:15], v[128:131], v[212:215], v[12:15]
	v_mfma_f32_16x16x32_bf16 v[8:11], v[136:139], v[212:215], v[8:11]
	v_mfma_f32_16x16x32_bf16 v[60:63], v[132:135], v[180:183], v[60:63]
	v_mfma_f32_16x16x32_bf16 v[56:59], v[140:143], v[180:183], v[56:59]
	v_mfma_f32_16x16x32_bf16 v[44:47], v[132:135], v[198:201], v[44:47]
	v_mfma_f32_16x16x32_bf16 v[40:43], v[140:143], v[198:201], v[40:43]
	v_mfma_f32_16x16x32_bf16 v[28:31], v[132:135], v[208:211], v[28:31]
	v_mfma_f32_16x16x32_bf16 v[24:27], v[140:143], v[208:211], v[24:27]
	v_mfma_f32_16x16x32_bf16 v[12:15], v[132:135], v[216:219], v[12:15]
	v_mfma_f32_16x16x32_bf16 v[8:11], v[140:143], v[216:219], v[8:11]
	v_mfma_f32_16x16x32_bf16 v[52:55], v[144:147], v[176:179], v[52:55]
	v_mfma_f32_16x16x32_bf16 v[48:51], v[168:171], v[176:179], v[48:51]
	v_mfma_f32_16x16x32_bf16 v[36:39], v[144:147], v[194:197], v[36:39]
	v_mfma_f32_16x16x32_bf16 v[32:35], v[168:171], v[194:197], v[32:35]
	v_mfma_f32_16x16x32_bf16 v[20:23], v[144:147], v[204:207], v[20:23]
	v_mfma_f32_16x16x32_bf16 v[16:19], v[168:171], v[204:207], v[16:19]
	v_mfma_f32_16x16x32_bf16 v[4:7], v[144:147], v[212:215], v[4:7]
	v_mfma_f32_16x16x32_bf16 v[0:3], v[168:171], v[212:215], v[0:3]
	v_mfma_f32_16x16x32_bf16 v[52:55], v[148:151], v[180:183], v[52:55]
	v_mfma_f32_16x16x32_bf16 v[48:51], v[172:175], v[180:183], v[48:51]
	v_mfma_f32_16x16x32_bf16 v[36:39], v[148:151], v[198:201], v[36:39]
	v_mfma_f32_16x16x32_bf16 v[32:35], v[172:175], v[198:201], v[32:35]
	v_mfma_f32_16x16x32_bf16 v[20:23], v[148:151], v[208:211], v[20:23]
	v_mfma_f32_16x16x32_bf16 v[16:19], v[172:175], v[208:211], v[16:19]
	v_mfma_f32_16x16x32_bf16 v[4:7], v[148:151], v[216:219], v[4:7]
	v_mfma_f32_16x16x32_bf16 v[0:3], v[172:175], v[216:219], v[0:3]
	s_setprio 1
	s_barrier
	s_add_i32 s60, 0, 0x18000
	s_add_i32 s61, 0, 0x1c000
	v_add_u32_e32 v140, s60, v187
	v_add_u32_e32 v172, s61, v187
	ds_read_b128 v[128:131], v140
	ds_read_b128 v[132:135], v140 offset:1024
	ds_read_b128 v[136:139], v140 offset:2048
	ds_read_b128 v[140:143], v140 offset:3072
	ds_read_b128 v[144:147], v172
	ds_read_b128 v[148:151], v172 offset:1024
	ds_read_b128 v[168:171], v172 offset:2048
	ds_read_b128 v[172:175], v172 offset:3072
	s_add_u32 s44, s44, 0x80000
	s_addc_u32 s45, s45, 0
	s_mov_b32 m0, s49
	v_lshl_add_u64 v[226:227], s[44:45], 0, v[152:153]
	ds_read_b128 v[176:179], v191 offset:32768
	ds_read_b128 v[180:183], v191 offset:33792
	ds_read_b128 v[194:197], v191 offset:34816
	ds_read_b128 v[198:201], v191 offset:35840
	ds_read_b128 v[204:207], v191 offset:36864
	ds_read_b128 v[208:211], v191 offset:37888
	ds_read_b128 v[212:215], v191 offset:38912
	ds_read_b128 v[216:219], v191 offset:39936
	global_load_lds_dwordx4 v[226:227], off
	v_lshl_add_u64 v[226:227], s[44:45], 0, v[156:157]
	s_mov_b32 m0, s50
	s_nop 0
	global_load_lds_dwordx4 v[226:227], off
	s_waitcnt vmcnt(8)
	s_waitcnt lgkmcnt(0)
	s_barrier
	s_setprio 0
	s_waitcnt lgkmcnt(0)
	v_mfma_f32_16x16x32_bf16 v[124:127], v[128:131], v[176:179], v[124:127]
	v_mfma_f32_16x16x32_bf16 v[120:123], v[136:139], v[176:179], v[120:123]
	v_mfma_f32_16x16x32_bf16 v[108:111], v[128:131], v[194:197], v[108:111]
	v_mfma_f32_16x16x32_bf16 v[104:107], v[136:139], v[194:197], v[104:107]
	v_mfma_f32_16x16x32_bf16 v[92:95], v[128:131], v[204:207], v[92:95]
	v_mfma_f32_16x16x32_bf16 v[88:91], v[136:139], v[204:207], v[88:91]
	v_mfma_f32_16x16x32_bf16 v[76:79], v[128:131], v[212:215], v[76:79]
	v_mfma_f32_16x16x32_bf16 v[72:75], v[136:139], v[212:215], v[72:75]
	v_mfma_f32_16x16x32_bf16 v[124:127], v[132:135], v[180:183], v[124:127]
	v_mfma_f32_16x16x32_bf16 v[120:123], v[140:143], v[180:183], v[120:123]
	v_mfma_f32_16x16x32_bf16 v[108:111], v[132:135], v[198:201], v[108:111]
	v_mfma_f32_16x16x32_bf16 v[104:107], v[140:143], v[198:201], v[104:107]
	v_mfma_f32_16x16x32_bf16 v[92:95], v[132:135], v[208:211], v[92:95]
	v_mfma_f32_16x16x32_bf16 v[88:91], v[140:143], v[208:211], v[88:91]
	v_mfma_f32_16x16x32_bf16 v[76:79], v[132:135], v[216:219], v[76:79]
	v_mfma_f32_16x16x32_bf16 v[72:75], v[140:143], v[216:219], v[72:75]
	v_mfma_f32_16x16x32_bf16 v[116:119], v[144:147], v[176:179], v[116:119]
	v_mfma_f32_16x16x32_bf16 v[112:115], v[168:171], v[176:179], v[112:115]
	v_mfma_f32_16x16x32_bf16 v[100:103], v[144:147], v[194:197], v[100:103]
	v_mfma_f32_16x16x32_bf16 v[96:99], v[168:171], v[194:197], v[96:99]
	v_mfma_f32_16x16x32_bf16 v[84:87], v[144:147], v[204:207], v[84:87]
	v_mfma_f32_16x16x32_bf16 v[80:83], v[168:171], v[204:207], v[80:83]
	v_mfma_f32_16x16x32_bf16 v[68:71], v[144:147], v[212:215], v[68:71]
	v_mfma_f32_16x16x32_bf16 v[64:67], v[168:171], v[212:215], v[64:67]
	v_mfma_f32_16x16x32_bf16 v[116:119], v[148:151], v[180:183], v[116:119]
	v_mfma_f32_16x16x32_bf16 v[112:115], v[172:175], v[180:183], v[112:115]
	v_mfma_f32_16x16x32_bf16 v[100:103], v[148:151], v[198:201], v[100:103]
	v_mfma_f32_16x16x32_bf16 v[96:99], v[172:175], v[198:201], v[96:99]
	v_mfma_f32_16x16x32_bf16 v[84:87], v[148:151], v[208:211], v[84:87]
	v_mfma_f32_16x16x32_bf16 v[80:83], v[172:175], v[208:211], v[80:83]
	v_mfma_f32_16x16x32_bf16 v[68:71], v[148:151], v[216:219], v[68:71]
	v_mfma_f32_16x16x32_bf16 v[64:67], v[172:175], v[216:219], v[64:67]
	s_setprio 1
	s_barrier
	s_add_i32 s44, s60, s46
	v_lshl_add_u64 v[184:185], v[184:185], 0, s[26:27]
	s_mov_b32 m0, s44
	ds_read_b128 v[176:179], v191 offset:49152
	ds_read_b128 v[180:183], v191 offset:50176
	ds_read_b128 v[194:197], v191 offset:51200
	ds_read_b128 v[198:201], v191 offset:52224
	ds_read_b128 v[204:207], v191 offset:53248
	ds_read_b128 v[208:211], v191 offset:54272
	ds_read_b128 v[212:215], v191 offset:55296
	ds_read_b128 v[216:219], v191 offset:56320
	global_load_lds_dwordx4 v[184:185], off
	s_add_i32 m0, s44, 0x2000
	s_add_u32 s4, s4, 0x80080
	v_lshl_add_u64 v[184:185], v[220:221], 0, s[26:27]
	s_addc_u32 s5, s5, 0
	s_add_i32 s44, s61, s46
	global_load_lds_dwordx4 v[184:185], off
	v_lshl_add_u64 v[184:185], s[4:5], 0, v[154:155]
	s_mov_b32 m0, s44
	s_nop 0
	global_load_lds_dwordx4 v[184:185], off
	v_lshl_add_u64 v[184:185], s[4:5], 0, v[158:159]
	s_add_i32 m0, s44, 0x2000
	s_nop 0
	global_load_lds_dwordx4 v[184:185], off
	v_lshl_add_u64 v[184:185], v[222:223], 0, s[26:27]
	s_mov_b32 m0, s33
	s_nop 0
	global_load_lds_dwordx4 v[184:185], off
	v_lshl_add_u64 v[184:185], v[224:225], 0, s[26:27]
	s_mov_b32 m0, s52
	s_nop 0
	global_load_lds_dwordx4 v[184:185], off
	s_waitcnt vmcnt(8)
	s_waitcnt lgkmcnt(0)
	s_barrier
	s_setprio 0
	s_waitcnt lgkmcnt(0)
	v_mfma_f32_16x16x32_bf16 v[60:63], v[128:131], v[176:179], v[60:63]
	v_mfma_f32_16x16x32_bf16 v[56:59], v[136:139], v[176:179], v[56:59]
	v_mfma_f32_16x16x32_bf16 v[44:47], v[128:131], v[194:197], v[44:47]
	v_mfma_f32_16x16x32_bf16 v[40:43], v[136:139], v[194:197], v[40:43]
	v_mfma_f32_16x16x32_bf16 v[28:31], v[128:131], v[204:207], v[28:31]
	v_mfma_f32_16x16x32_bf16 v[24:27], v[136:139], v[204:207], v[24:27]
	v_mfma_f32_16x16x32_bf16 v[12:15], v[128:131], v[212:215], v[12:15]
	v_mfma_f32_16x16x32_bf16 v[8:11], v[136:139], v[212:215], v[8:11]
	v_mfma_f32_16x16x32_bf16 v[60:63], v[132:135], v[180:183], v[60:63]
	v_mfma_f32_16x16x32_bf16 v[56:59], v[140:143], v[180:183], v[56:59]
	v_mfma_f32_16x16x32_bf16 v[44:47], v[132:135], v[198:201], v[44:47]
	v_mfma_f32_16x16x32_bf16 v[40:43], v[140:143], v[198:201], v[40:43]
	v_mfma_f32_16x16x32_bf16 v[28:31], v[132:135], v[208:211], v[28:31]
	v_mfma_f32_16x16x32_bf16 v[24:27], v[140:143], v[208:211], v[24:27]
	v_mfma_f32_16x16x32_bf16 v[12:15], v[132:135], v[216:219], v[12:15]
	v_mfma_f32_16x16x32_bf16 v[8:11], v[140:143], v[216:219], v[8:11]
	v_mfma_f32_16x16x32_bf16 v[52:55], v[144:147], v[176:179], v[52:55]
	v_mfma_f32_16x16x32_bf16 v[48:51], v[168:171], v[176:179], v[48:51]
	v_mfma_f32_16x16x32_bf16 v[36:39], v[144:147], v[194:197], v[36:39]
	v_mfma_f32_16x16x32_bf16 v[32:35], v[168:171], v[194:197], v[32:35]
	v_mfma_f32_16x16x32_bf16 v[20:23], v[144:147], v[204:207], v[20:23]
	v_mfma_f32_16x16x32_bf16 v[16:19], v[168:171], v[204:207], v[16:19]
	v_mfma_f32_16x16x32_bf16 v[4:7], v[144:147], v[212:215], v[4:7]
	v_mfma_f32_16x16x32_bf16 v[0:3], v[168:171], v[212:215], v[0:3]
	v_mfma_f32_16x16x32_bf16 v[52:55], v[148:151], v[180:183], v[52:55]
	v_mfma_f32_16x16x32_bf16 v[48:51], v[172:175], v[180:183], v[48:51]
	v_mfma_f32_16x16x32_bf16 v[36:39], v[148:151], v[198:201], v[36:39]
	v_mfma_f32_16x16x32_bf16 v[32:35], v[172:175], v[198:201], v[32:35]
	v_mfma_f32_16x16x32_bf16 v[20:23], v[148:151], v[208:211], v[20:23]
	v_mfma_f32_16x16x32_bf16 v[16:19], v[172:175], v[208:211], v[16:19]
	v_mfma_f32_16x16x32_bf16 v[4:7], v[148:151], v[216:219], v[4:7]
	v_mfma_f32_16x16x32_bf16 v[0:3], v[172:175], v[216:219], v[0:3]
	s_setprio 1
	s_barrier
	s_add_i32 s59, s59, 2
	s_add_u32 s42, s42, 0x100
	s_addc_u32 s43, s43, 0
	s_add_u32 s57, s57, 0x100
	s_addc_u32 s58, s58, 0
	s_cmp_gt_u32 s59, 29
	s_cbranch_scc0 .LBB0_401
	s_and_b64 vcc, exec, s[28:29]
	s_cbranch_vccz .LBB0_404
	s_barrier
.LBB0_404:
	s_setprio 0
	v_lshl_or_b32 v168, s10, 8, v188
	v_lshl_add_u32 v172, s40, 8, v186
	v_ashrrev_i32_e32 v169, 31, v168
	v_lshlrev_b64 v[204:205], 1, v[168:169]
	v_ashrrev_i32_e32 v173, 31, v172
	v_lshl_add_u64 v[170:171], s[16:17], 0, v[204:205]
	v_lshlrev_b64 v[206:207], 11, v[172:173]
	v_lshl_add_u64 v[128:129], v[170:171], 0, v[206:207]
	global_load_dwordx4 v[194:197], v[128:129], off
	global_load_dwordx4 v[198:201], v[128:129], off offset:256
	v_or_b32_e32 v182, 16, v172
	v_or_b32_e32 v178, 32, v172
	v_or_b32_e32 v174, 48, v172
	v_ashrrev_i32_e32 v183, 31, v182
	v_ashrrev_i32_e32 v179, 31, v178
	v_ashrrev_i32_e32 v175, 31, v174
	v_lshlrev_b64 v[184:185], 11, v[182:183]
	v_lshlrev_b64 v[180:181], 11, v[178:179]
	v_lshlrev_b64 v[176:177], 11, v[174:175]
	v_lshl_add_u64 v[128:129], v[170:171], 0, v[184:185]
	v_lshl_add_u64 v[130:131], v[170:171], 0, v[180:181]
	v_lshl_add_u64 v[208:209], v[170:171], 0, v[176:177]
	global_load_dwordx4 v[148:151], v[128:129], off
	global_load_dwordx4 v[144:147], v[128:129], off offset:256
	global_load_dwordx4 v[140:143], v[130:131], off
	global_load_dwordx4 v[136:139], v[130:131], off offset:256
	global_load_dwordx4 v[132:135], v[208:209], off
	s_nop 0
	global_load_dwordx4 v[128:131], v[208:209], off offset:256
	v_and_b32_e32 v208, 64, v192
	v_xor_b32_e32 v193, 16, v192
	v_add_u32_e32 v208, 64, v208
	v_xor_b32_e32 v209, 32, v192
	v_cmp_lt_i32_e32 vcc, v193, v208
	v_lshl_add_u64 v[206:207], s[16:17], 0, v[206:207]
	v_lshl_add_u64 v[204:205], v[206:207], 0, v[204:205]
	v_cndmask_b32_e32 v193, v192, v193, vcc
	v_cmp_lt_i32_e32 vcc, v209, v208
	v_lshlrev_b32_e32 v193, 2, v193
	s_lshl_b32 s40, s10, 2
	v_cndmask_b32_e32 v214, v192, v209, vcc
	s_ashr_i32 s41, s40, 31
	s_waitcnt vmcnt(0)
	v_lshlrev_b32_e32 v206, 16, v194
	v_and_b32_e32 v207, 0xffff0000, v194
	v_lshlrev_b32_e32 v194, 16, v195
	v_and_b32_e32 v195, 0xffff0000, v195
	v_lshlrev_b32_e32 v208, 16, v196
	v_and_b32_e32 v209, 0xffff0000, v196
	v_lshlrev_b32_e32 v196, 16, v197
	v_and_b32_e32 v197, 0xffff0000, v197
	v_lshlrev_b32_e32 v210, 16, v198
	v_and_b32_e32 v211, 0xffff0000, v198
	v_lshlrev_b32_e32 v198, 16, v199
	v_and_b32_e32 v199, 0xffff0000, v199
	v_lshlrev_b32_e32 v212, 16, v200
	v_and_b32_e32 v213, 0xffff0000, v200
	v_lshlrev_b32_e32 v200, 16, v201
	v_and_b32_e32 v201, 0xffff0000, v201
	v_pk_add_f32 v[126:127], v[126:127], v[194:195]
	v_pk_add_f32 v[124:125], v[124:125], v[206:207]
	v_pk_add_f32 v[122:123], v[122:123], v[196:197]
	v_pk_add_f32 v[120:121], v[120:121], v[208:209]
	v_pk_add_f32 v[118:119], v[118:119], v[198:199]
	v_pk_add_f32 v[116:117], v[116:117], v[210:211]
	v_pk_add_f32 v[194:195], v[114:115], v[200:201]
	v_pk_add_f32 v[196:197], v[112:113], v[212:213]
	v_mul_f32_e32 v114, v125, v125
	v_mul_f32_e32 v115, v127, v127
	v_mul_f32_e32 v198, v121, v121
	v_mul_f32_e32 v199, v123, v123
	v_cvt_pk_bf16_f32 v112, v124, v125
	v_cvt_pk_bf16_f32 v113, v126, v127
	v_mul_f32_e32 v125, v117, v117
	v_mul_f32_e32 v127, v119, v119
	v_mul_f32_e32 v200, v197, v197
	v_mul_f32_e32 v201, v195, v195
	v_fmac_f32_e32 v114, v124, v124
	v_fmac_f32_e32 v115, v126, v126
	v_fmac_f32_e32 v198, v120, v120
	v_fmac_f32_e32 v199, v122, v122
	v_fmac_f32_e32 v125, v116, v116
	v_fmac_f32_e32 v127, v118, v118
	v_fmac_f32_e32 v200, v196, v196
	v_fmac_f32_e32 v201, v194, v194
	v_add_f32_e32 v114, v114, v115
	v_add_f32_e32 v115, v198, v199
	v_add_f32_e32 v124, v125, v127
	v_add_f32_e32 v125, v200, v201
	v_add_f32_e32 v114, v114, v115
	v_add_f32_e32 v115, v124, v125
	v_add_f32_e32 v124, v114, v115
	ds_bpermute_b32 v125, v193, v124
	v_cvt_pk_bf16_f32 v114, v120, v121
	v_cvt_pk_bf16_f32 v115, v122, v123
	global_store_dwordx4 v[204:205], v[112:115], off
	v_cvt_pk_bf16_f32 v116, v116, v117
	v_cvt_pk_bf16_f32 v117, v118, v119
	v_cvt_pk_bf16_f32 v118, v196, v197
	v_cvt_pk_bf16_f32 v119, v194, v195
	global_store_dwordx4 v[204:205], v[116:119], off offset:256
	s_waitcnt lgkmcnt(0)
	v_add_f32_e32 v113, v124, v125
	v_lshlrev_b32_e32 v112, 2, v214
	ds_bpermute_b32 v114, v112, v113
	s_and_saveexec_b64 s[4:5], s[6:7]
	s_cbranch_execz .LBB0_406
	v_lshlrev_b64 v[116:117], 6, v[172:173]
	v_lshl_add_u64 v[116:117], s[22:23], 0, v[116:117]
	v_lshl_add_u64 v[116:117], s[40:41], 2, v[116:117]
	s_lshl_b32 s10, s51, 2
	v_lshl_add_u64 v[116:117], v[116:117], 0, s[10:11]
	s_waitcnt lgkmcnt(0)
	v_add_f32_e32 v113, v113, v114
	global_store_dword v[116:117], v113, off

.LBB0_483:
	ds_read_b128 v[146:149], v169
	ds_read_b128 v[150:153], v169 offset:1024
	ds_read_b128 v[154:157], v169 offset:2048
	ds_read_b128 v[160:163], v169 offset:3072
	ds_read_b128 v[180:183], v171
	ds_read_b128 v[184:187], v171 offset:1024
	ds_read_b128 v[188:191], v171 offset:2048
	ds_read_b128 v[192:195], v171 offset:3072
	s_add_u32 s4, s10, 0xfffc0080
	s_addc_u32 s5, s11, -1
	s_cmp_eq_u32 s56, 12
	s_cselect_b32 s13, s9, s5
	s_cselect_b32 s12, s37, s4
	s_cselect_b32 s5, s35, s55
	s_cselect_b32 s4, s53, s54
	v_lshl_add_u64 v[200:201], s[10:11], 0, v[138:139]
	s_add_i32 m0, s42, 0xc000
	ds_read_b128 v[196:199], v173
	ds_read_b128 v[204:207], v173 offset:1024
	ds_read_b128 v[208:211], v173 offset:2048
	ds_read_b128 v[212:215], v173 offset:3072
	ds_read_b128 v[216:219], v173 offset:4096
	ds_read_b128 v[220:223], v173 offset:5120
	ds_read_b128 v[224:227], v173 offset:6144
	ds_read_b128 v[228:231], v173 offset:7168
	global_load_lds_dwordx4 v[200:201], off
	v_lshl_add_u64 v[200:201], s[10:11], 0, v[140:141]
	s_add_i32 m0, s42, 0xe000
	s_nop 0
	global_load_lds_dwordx4 v[200:201], off
	s_waitcnt vmcnt(8)
	s_waitcnt lgkmcnt(0)
	s_barrier
	s_setprio 0
	s_waitcnt lgkmcnt(0)
	v_mfma_f32_16x16x32_bf16 v[124:127], v[146:149], v[196:199], v[124:127]
	v_mfma_f32_16x16x32_bf16 v[116:119], v[154:157], v[196:199], v[116:119]
	v_mfma_f32_16x16x32_bf16 v[108:111], v[146:149], v[208:211], v[108:111]
	v_mfma_f32_16x16x32_bf16 v[100:103], v[154:157], v[208:211], v[100:103]
	v_mfma_f32_16x16x32_bf16 v[92:95], v[146:149], v[216:219], v[92:95]
	v_mfma_f32_16x16x32_bf16 v[84:87], v[154:157], v[216:219], v[84:87]
	v_mfma_f32_16x16x32_bf16 v[76:79], v[146:149], v[224:227], v[76:79]
	v_mfma_f32_16x16x32_bf16 v[68:71], v[154:157], v[224:227], v[68:71]
	v_mfma_f32_16x16x32_bf16 v[124:127], v[150:153], v[204:207], v[124:127]
	v_mfma_f32_16x16x32_bf16 v[116:119], v[160:163], v[204:207], v[116:119]
	v_mfma_f32_16x16x32_bf16 v[108:111], v[150:153], v[212:215], v[108:111]
	v_mfma_f32_16x16x32_bf16 v[100:103], v[160:163], v[212:215], v[100:103]
	v_mfma_f32_16x16x32_bf16 v[92:95], v[150:153], v[220:223], v[92:95]
	v_mfma_f32_16x16x32_bf16 v[84:87], v[160:163], v[220:223], v[84:87]
	v_mfma_f32_16x16x32_bf16 v[76:79], v[150:153], v[228:231], v[76:79]
	v_mfma_f32_16x16x32_bf16 v[68:71], v[160:163], v[228:231], v[68:71]
	v_mfma_f32_16x16x32_bf16 v[120:123], v[180:183], v[196:199], v[120:123]
	v_mfma_f32_16x16x32_bf16 v[112:115], v[188:191], v[196:199], v[112:115]
	v_mfma_f32_16x16x32_bf16 v[104:107], v[180:183], v[208:211], v[104:107]
	v_mfma_f32_16x16x32_bf16 v[96:99], v[188:191], v[208:211], v[96:99]
	v_mfma_f32_16x16x32_bf16 v[88:91], v[180:183], v[216:219], v[88:91]
	v_mfma_f32_16x16x32_bf16 v[80:83], v[188:191], v[216:219], v[80:83]
	v_mfma_f32_16x16x32_bf16 v[72:75], v[180:183], v[224:227], v[72:75]
	v_mfma_f32_16x16x32_bf16 v[64:67], v[188:191], v[224:227], v[64:67]
	v_mfma_f32_16x16x32_bf16 v[120:123], v[184:187], v[204:207], v[120:123]
	v_mfma_f32_16x16x32_bf16 v[112:115], v[192:195], v[204:207], v[112:115]
	v_mfma_f32_16x16x32_bf16 v[104:107], v[184:187], v[212:215], v[104:107]
	v_mfma_f32_16x16x32_bf16 v[96:99], v[192:195], v[212:215], v[96:99]
	v_mfma_f32_16x16x32_bf16 v[88:91], v[184:187], v[220:223], v[88:91]
	v_mfma_f32_16x16x32_bf16 v[80:83], v[192:195], v[220:223], v[80:83]
	v_mfma_f32_16x16x32_bf16 v[72:75], v[184:187], v[228:231], v[72:75]
	v_mfma_f32_16x16x32_bf16 v[64:67], v[192:195], v[228:231], v[64:67]
	s_setprio 1
	s_barrier
	s_add_i32 s57, s49, s23
	v_lshl_add_u64 v[200:201], s[4:5], 0, v[132:133]
	s_mov_b32 m0, s57
	ds_read_b128 v[196:199], v173 offset:16384
	ds_read_b128 v[204:207], v173 offset:17408
	ds_read_b128 v[208:211], v173 offset:18432
	ds_read_b128 v[212:215], v173 offset:19456
	ds_read_b128 v[216:219], v173 offset:20480
	ds_read_b128 v[220:223], v173 offset:21504
	ds_read_b128 v[224:227], v173 offset:22528
	ds_read_b128 v[228:231], v173 offset:23552
	global_load_lds_dwordx4 v[200:201], off
	s_add_i32 m0, s57, 0x2000
	s_add_u32 s58, s4, 0x40000
	v_lshl_add_u64 v[232:233], s[4:5], 0, v[128:129]
	s_addc_u32 s59, s5, 0
	s_add_i32 s57, s50, s23
	global_load_lds_dwordx4 v[232:233], off
	v_lshl_add_u64 v[234:235], s[58:59], 0, v[132:133]
	s_mov_b32 m0, s57
	v_lshl_add_u64 v[236:237], s[12:13], 0, v[130:131]
	global_load_lds_dwordx4 v[234:235], off
	v_lshl_add_u64 v[234:235], s[58:59], 0, v[128:129]
	s_add_i32 m0, s57, 0x2000
	s_nop 0
	global_load_lds_dwordx4 v[234:235], off
	v_lshl_add_u64 v[234:235], s[12:13], 0, v[134:135]
	s_mov_b32 m0, s42
	s_nop 0
	global_load_lds_dwordx4 v[234:235], off
	s_mov_b32 m0, s43
	s_nop 0
	global_load_lds_dwordx4 v[236:237], off
	s_waitcnt vmcnt(8)
	s_waitcnt lgkmcnt(0)
	s_barrier
	s_setprio 0
	s_waitcnt lgkmcnt(0)
	v_mfma_f32_16x16x32_bf16 v[60:63], v[146:149], v[196:199], v[60:63]
	v_mfma_f32_16x16x32_bf16 v[52:55], v[154:157], v[196:199], v[52:55]
	v_mfma_f32_16x16x32_bf16 v[44:47], v[146:149], v[208:211], v[44:47]
	v_mfma_f32_16x16x32_bf16 v[36:39], v[154:157], v[208:211], v[36:39]
	v_mfma_f32_16x16x32_bf16 v[28:31], v[146:149], v[216:219], v[28:31]
	v_mfma_f32_16x16x32_bf16 v[20:23], v[154:157], v[216:219], v[20:23]
	v_mfma_f32_16x16x32_bf16 v[12:15], v[146:149], v[224:227], v[12:15]
	v_mfma_f32_16x16x32_bf16 v[4:7], v[154:157], v[224:227], v[4:7]
	v_mfma_f32_16x16x32_bf16 v[60:63], v[150:153], v[204:207], v[60:63]
	v_mfma_f32_16x16x32_bf16 v[52:55], v[160:163], v[204:207], v[52:55]
	v_mfma_f32_16x16x32_bf16 v[44:47], v[150:153], v[212:215], v[44:47]
	v_mfma_f32_16x16x32_bf16 v[36:39], v[160:163], v[212:215], v[36:39]
	v_mfma_f32_16x16x32_bf16 v[28:31], v[150:153], v[220:223], v[28:31]
	v_mfma_f32_16x16x32_bf16 v[20:23], v[160:163], v[220:223], v[20:23]
	v_mfma_f32_16x16x32_bf16 v[12:15], v[150:153], v[228:231], v[12:15]
	v_mfma_f32_16x16x32_bf16 v[4:7], v[160:163], v[228:231], v[4:7]
	v_mfma_f32_16x16x32_bf16 v[56:59], v[180:183], v[196:199], v[56:59]
	v_mfma_f32_16x16x32_bf16 v[48:51], v[188:191], v[196:199], v[48:51]
	v_mfma_f32_16x16x32_bf16 v[40:43], v[180:183], v[208:211], v[40:43]
	v_mfma_f32_16x16x32_bf16 v[32:35], v[188:191], v[208:211], v[32:35]
	v_mfma_f32_16x16x32_bf16 v[24:27], v[180:183], v[216:219], v[24:27]
	v_mfma_f32_16x16x32_bf16 v[16:19], v[188:191], v[216:219], v[16:19]
	v_mfma_f32_16x16x32_bf16 v[8:11], v[180:183], v[224:227], v[8:11]
	v_mfma_f32_16x16x32_bf16 v[0:3], v[188:191], v[224:227], v[0:3]
	v_mfma_f32_16x16x32_bf16 v[56:59], v[184:187], v[204:207], v[56:59]
	v_mfma_f32_16x16x32_bf16 v[48:51], v[192:195], v[204:207], v[48:51]
	v_mfma_f32_16x16x32_bf16 v[40:43], v[184:187], v[212:215], v[40:43]
	v_mfma_f32_16x16x32_bf16 v[32:35], v[192:195], v[212:215], v[32:35]
	v_mfma_f32_16x16x32_bf16 v[24:27], v[184:187], v[220:223], v[24:27]
	v_mfma_f32_16x16x32_bf16 v[16:19], v[192:195], v[220:223], v[16:19]
	v_mfma_f32_16x16x32_bf16 v[8:11], v[184:187], v[228:231], v[8:11]
	v_mfma_f32_16x16x32_bf16 v[0:3], v[192:195], v[228:231], v[0:3]
	s_setprio 1
	s_barrier
	s_add_i32 s57, 0, 0x18000
	v_add_u32_e32 v158, s57, v165
	s_add_i32 s58, 0, 0x1c000
	ds_read_b128 v[146:149], v158
	ds_read_b128 v[150:153], v158 offset:1024
	ds_read_b128 v[154:157], v158 offset:2048
	ds_read_b128 v[160:163], v158 offset:3072
	v_add_u32_e32 v158, s58, v165
	ds_read_b128 v[180:183], v158
	ds_read_b128 v[184:187], v158 offset:1024
	ds_read_b128 v[188:191], v158 offset:2048
	ds_read_b128 v[192:195], v158 offset:3072
	s_add_u32 s12, s12, 0x40000
	s_addc_u32 s13, s13, 0
	s_mov_b32 m0, s44
	v_lshl_add_u64 v[238:239], s[12:13], 0, v[134:135]
	ds_read_b128 v[196:199], v173 offset:32768
	ds_read_b128 v[204:207], v173 offset:33792
	ds_read_b128 v[208:211], v173 offset:34816
	ds_read_b128 v[212:215], v173 offset:35840
	ds_read_b128 v[216:219], v173 offset:36864
	ds_read_b128 v[220:223], v173 offset:37888
	ds_read_b128 v[224:227], v173 offset:38912
	ds_read_b128 v[228:231], v173 offset:39936
	global_load_lds_dwordx4 v[238:239], off
	v_lshl_add_u64 v[238:239], s[12:13], 0, v[130:131]
	s_mov_b32 m0, s45
	s_nop 0
	global_load_lds_dwordx4 v[238:239], off
	s_waitcnt vmcnt(8)
	s_waitcnt lgkmcnt(0)
	s_barrier
	s_setprio 0
	s_waitcnt lgkmcnt(0)
	v_mfma_f32_16x16x32_bf16 v[124:127], v[146:149], v[196:199], v[124:127]
	v_mfma_f32_16x16x32_bf16 v[116:119], v[154:157], v[196:199], v[116:119]
	v_mfma_f32_16x16x32_bf16 v[108:111], v[146:149], v[208:211], v[108:111]
	v_mfma_f32_16x16x32_bf16 v[100:103], v[154:157], v[208:211], v[100:103]
	v_mfma_f32_16x16x32_bf16 v[92:95], v[146:149], v[216:219], v[92:95]
	v_mfma_f32_16x16x32_bf16 v[84:87], v[154:157], v[216:219], v[84:87]
	v_mfma_f32_16x16x32_bf16 v[76:79], v[146:149], v[224:227], v[76:79]
	v_mfma_f32_16x16x32_bf16 v[68:71], v[154:157], v[224:227], v[68:71]
	v_mfma_f32_16x16x32_bf16 v[124:127], v[150:153], v[204:207], v[124:127]
	v_mfma_f32_16x16x32_bf16 v[116:119], v[160:163], v[204:207], v[116:119]
	v_mfma_f32_16x16x32_bf16 v[108:111], v[150:153], v[212:215], v[108:111]
	v_mfma_f32_16x16x32_bf16 v[100:103], v[160:163], v[212:215], v[100:103]
	v_mfma_f32_16x16x32_bf16 v[92:95], v[150:153], v[220:223], v[92:95]
	v_mfma_f32_16x16x32_bf16 v[84:87], v[160:163], v[220:223], v[84:87]
	v_mfma_f32_16x16x32_bf16 v[76:79], v[150:153], v[228:231], v[76:79]
	v_mfma_f32_16x16x32_bf16 v[68:71], v[160:163], v[228:231], v[68:71]
	v_mfma_f32_16x16x32_bf16 v[120:123], v[180:183], v[196:199], v[120:123]
	v_mfma_f32_16x16x32_bf16 v[112:115], v[188:191], v[196:199], v[112:115]
	v_mfma_f32_16x16x32_bf16 v[104:107], v[180:183], v[208:211], v[104:107]
	v_mfma_f32_16x16x32_bf16 v[96:99], v[188:191], v[208:211], v[96:99]
	v_mfma_f32_16x16x32_bf16 v[88:91], v[180:183], v[216:219], v[88:91]
	v_mfma_f32_16x16x32_bf16 v[80:83], v[188:191], v[216:219], v[80:83]
	v_mfma_f32_16x16x32_bf16 v[72:75], v[180:183], v[224:227], v[72:75]
	v_mfma_f32_16x16x32_bf16 v[64:67], v[188:191], v[224:227], v[64:67]
	v_mfma_f32_16x16x32_bf16 v[120:123], v[184:187], v[204:207], v[120:123]
	v_mfma_f32_16x16x32_bf16 v[112:115], v[192:195], v[204:207], v[112:115]
	v_mfma_f32_16x16x32_bf16 v[104:107], v[184:187], v[212:215], v[104:107]
	v_mfma_f32_16x16x32_bf16 v[96:99], v[192:195], v[212:215], v[96:99]
	v_mfma_f32_16x16x32_bf16 v[88:91], v[184:187], v[220:223], v[88:91]
	v_mfma_f32_16x16x32_bf16 v[80:83], v[192:195], v[220:223], v[80:83]
	v_mfma_f32_16x16x32_bf16 v[72:75], v[184:187], v[228:231], v[72:75]
	v_mfma_f32_16x16x32_bf16 v[64:67], v[192:195], v[228:231], v[64:67]
	s_setprio 1
	s_barrier
	s_add_i32 s12, s57, s23
	v_lshl_add_u64 v[200:201], v[200:201], 0, s[28:29]
	s_mov_b32 m0, s12
	ds_read_b128 v[196:199], v173 offset:49152
	ds_read_b128 v[204:207], v173 offset:50176
	ds_read_b128 v[208:211], v173 offset:51200
	ds_read_b128 v[212:215], v173 offset:52224
	ds_read_b128 v[216:219], v173 offset:53248
	ds_read_b128 v[220:223], v173 offset:54272
	ds_read_b128 v[224:227], v173 offset:55296
	ds_read_b128 v[228:231], v173 offset:56320
	global_load_lds_dwordx4 v[200:201], off
	s_add_i32 m0, s12, 0x2000
	s_add_u32 s4, s4, 0x40080
	v_lshl_add_u64 v[200:201], v[232:233], 0, s[28:29]
	s_addc_u32 s5, s5, 0
	s_add_i32 s12, s58, s23
	global_load_lds_dwordx4 v[200:201], off
	v_lshl_add_u64 v[200:201], s[4:5], 0, v[132:133]
	s_mov_b32 m0, s12
	s_nop 0
	global_load_lds_dwordx4 v[200:201], off
	v_lshl_add_u64 v[200:201], s[4:5], 0, v[128:129]
	s_add_i32 m0, s12, 0x2000
	s_nop 0
	global_load_lds_dwordx4 v[200:201], off
	v_lshl_add_u64 v[200:201], v[234:235], 0, s[28:29]
	s_mov_b32 m0, s47
	s_nop 0
	global_load_lds_dwordx4 v[200:201], off
	v_lshl_add_u64 v[200:201], v[236:237], 0, s[28:29]
	s_mov_b32 m0, s48
	s_nop 0
	global_load_lds_dwordx4 v[200:201], off
	s_waitcnt vmcnt(8)
	s_waitcnt lgkmcnt(0)
	s_barrier
	s_setprio 0
	s_waitcnt lgkmcnt(0)
	v_mfma_f32_16x16x32_bf16 v[60:63], v[146:149], v[196:199], v[60:63]
	v_mfma_f32_16x16x32_bf16 v[52:55], v[154:157], v[196:199], v[52:55]
	v_mfma_f32_16x16x32_bf16 v[44:47], v[146:149], v[208:211], v[44:47]
	v_mfma_f32_16x16x32_bf16 v[36:39], v[154:157], v[208:211], v[36:39]
	v_mfma_f32_16x16x32_bf16 v[28:31], v[146:149], v[216:219], v[28:31]
	v_mfma_f32_16x16x32_bf16 v[20:23], v[154:157], v[216:219], v[20:23]
	v_mfma_f32_16x16x32_bf16 v[12:15], v[146:149], v[224:227], v[12:15]
	v_mfma_f32_16x16x32_bf16 v[4:7], v[154:157], v[224:227], v[4:7]
	v_mfma_f32_16x16x32_bf16 v[60:63], v[150:153], v[204:207], v[60:63]
	v_mfma_f32_16x16x32_bf16 v[52:55], v[160:163], v[204:207], v[52:55]
	v_mfma_f32_16x16x32_bf16 v[44:47], v[150:153], v[212:215], v[44:47]
	v_mfma_f32_16x16x32_bf16 v[36:39], v[160:163], v[212:215], v[36:39]
	v_mfma_f32_16x16x32_bf16 v[28:31], v[150:153], v[220:223], v[28:31]
	v_mfma_f32_16x16x32_bf16 v[20:23], v[160:163], v[220:223], v[20:23]
	v_mfma_f32_16x16x32_bf16 v[12:15], v[150:153], v[228:231], v[12:15]
	v_mfma_f32_16x16x32_bf16 v[4:7], v[160:163], v[228:231], v[4:7]
	v_mfma_f32_16x16x32_bf16 v[56:59], v[180:183], v[196:199], v[56:59]
	v_mfma_f32_16x16x32_bf16 v[48:51], v[188:191], v[196:199], v[48:51]
	v_mfma_f32_16x16x32_bf16 v[40:43], v[180:183], v[208:211], v[40:43]
	v_mfma_f32_16x16x32_bf16 v[32:35], v[188:191], v[208:211], v[32:35]
	v_mfma_f32_16x16x32_bf16 v[24:27], v[180:183], v[216:219], v[24:27]
	v_mfma_f32_16x16x32_bf16 v[16:19], v[188:191], v[216:219], v[16:19]
	v_mfma_f32_16x16x32_bf16 v[8:11], v[180:183], v[224:227], v[8:11]
	v_mfma_f32_16x16x32_bf16 v[0:3], v[188:191], v[224:227], v[0:3]
	v_mfma_f32_16x16x32_bf16 v[56:59], v[184:187], v[204:207], v[56:59]
	v_mfma_f32_16x16x32_bf16 v[48:51], v[192:195], v[204:207], v[48:51]
	v_mfma_f32_16x16x32_bf16 v[40:43], v[184:187], v[212:215], v[40:43]
	v_mfma_f32_16x16x32_bf16 v[32:35], v[192:195], v[212:215], v[32:35]
	v_mfma_f32_16x16x32_bf16 v[24:27], v[184:187], v[220:223], v[24:27]
	v_mfma_f32_16x16x32_bf16 v[16:19], v[192:195], v[220:223], v[16:19]
	v_mfma_f32_16x16x32_bf16 v[8:11], v[184:187], v[228:231], v[8:11]
	v_mfma_f32_16x16x32_bf16 v[0:3], v[192:195], v[228:231], v[0:3]
	s_setprio 1
	s_barrier
	s_add_i32 s56, s56, 2
	s_add_u32 s10, s10, 0x100
	s_addc_u32 s11, s11, 0
	s_add_u32 s54, s54, 0x100
	s_addc_u32 s55, s55, 0
	s_cmp_gt_u32 s56, 13
	s_cbranch_scc0 .LBB0_483
	s_and_b64 vcc, exec, s[30:31]
	s_cbranch_vccz .LBB0_486
	s_barrier
.LBB0_486:
	s_setprio 0
	v_lshl_add_u32 v162, s8, 8, v159
	s_mov_b64 s[60:61], 0x2000
	v_lshlrev_b32_e32 v204, 6, v162
	v_mov_b32_e32 v205, 0
	v_mbcnt_lo_u32_b32 v248, -1, 0
	v_mbcnt_hi_u32_b32 v248, -1, v248
	v_xor_b32_e32 v248, 16, v248
	v_lshl_add_u64 v[204:205], v[136:137], 0, v[204:205]
	v_lshlrev_b32_e32 v248, 2, v248
	v_lshl_add_u64 v[206:207], v[204:205], 0, s[60:61]
	global_load_dwordx4 v[208:211], v[204:205], off
	global_load_dwordx4 v[212:215], v[204:205], off offset:1024
	global_load_dwordx4 v[216:219], v[204:205], off offset:2048
	global_load_dwordx4 v[220:223], v[204:205], off offset:3072
	global_load_dwordx4 v[224:227], v[206:207], off
	global_load_dwordx4 v[228:231], v[206:207], off offset:1024
	global_load_dwordx4 v[232:235], v[206:207], off offset:2048
	global_load_dwordx4 v[236:239], v[206:207], off offset:3072
	s_waitcnt vmcnt(0)
	v_add_f32_e32 v208, v208, v209
	v_add_f32_e32 v210, v210, v211
	v_add_f32_e32 v212, v212, v213
	v_add_f32_e32 v214, v214, v215
	v_add_f32_e32 v216, v216, v217
	v_add_f32_e32 v218, v218, v219
	v_add_f32_e32 v220, v220, v221
	v_add_f32_e32 v222, v222, v223
	v_add_f32_e32 v224, v224, v225
	v_add_f32_e32 v226, v226, v227
	v_add_f32_e32 v228, v228, v229
	v_add_f32_e32 v230, v230, v231
	v_add_f32_e32 v232, v232, v233
	v_add_f32_e32 v234, v234, v235
	v_add_f32_e32 v236, v236, v237
	v_add_f32_e32 v238, v238, v239
	v_add_f32_e32 v208, v208, v210
	v_add_f32_e32 v212, v212, v214
	v_add_f32_e32 v216, v216, v218
	v_add_f32_e32 v220, v220, v222
	v_add_f32_e32 v224, v224, v226
	v_add_f32_e32 v228, v228, v230
	v_add_f32_e32 v232, v232, v234
	v_add_f32_e32 v236, v236, v238
	ds_bpermute_b32 v209, v248, v208
	ds_bpermute_b32 v213, v248, v212
	ds_bpermute_b32 v217, v248, v216
	ds_bpermute_b32 v221, v248, v220
	ds_bpermute_b32 v225, v248, v224
	ds_bpermute_b32 v229, v248, v228
	ds_bpermute_b32 v233, v248, v232
	ds_bpermute_b32 v237, v248, v236
	s_waitcnt lgkmcnt(0)
	v_add_f32_e32 v208, v208, v209
	v_add_f32_e32 v212, v212, v213
	v_add_f32_e32 v216, v216, v217
	v_add_f32_e32 v220, v220, v221
	v_add_f32_e32 v224, v224, v225
	v_add_f32_e32 v228, v228, v229
	v_add_f32_e32 v232, v232, v233
	v_add_f32_e32 v236, v236, v237
	v_mov_b32_e32 v209, v208
	v_mov_b32_e32 v213, v212
	v_mov_b32_e32 v217, v216
	v_mov_b32_e32 v221, v220
	v_mov_b32_e32 v225, v224
	v_mov_b32_e32 v229, v228
	v_mov_b32_e32 v233, v232
	v_mov_b32_e32 v237, v236
	s_nop 1
	v_permlane32_swap_b32_e32 v208, v209
	v_permlane32_swap_b32_e32 v212, v213
	v_permlane32_swap_b32_e32 v216, v217
	v_permlane32_swap_b32_e32 v220, v221
	v_permlane32_swap_b32_e32 v224, v225
	v_permlane32_swap_b32_e32 v228, v229
	v_permlane32_swap_b32_e32 v232, v233
	v_permlane32_swap_b32_e32 v236, v237
	v_add_f32_e32 v208, v208, v209
	v_add_f32_e32 v212, v212, v213
	v_add_f32_e32 v216, v216, v217
	v_add_f32_e32 v220, v220, v221
	v_add_f32_e32 v224, v224, v225
	v_add_f32_e32 v228, v228, v229
	v_add_f32_e32 v232, v232, v233
	v_add_f32_e32 v236, v236, v237
	v_fmamk_f32 v208, v208, 0x3a800000, v177
	v_fmamk_f32 v212, v212, 0x3a800000, v177
	v_fmamk_f32 v216, v216, 0x3a800000, v177
	v_fmamk_f32 v220, v220, 0x3a800000, v177
	v_fmamk_f32 v224, v224, 0x3a800000, v177
	v_fmamk_f32 v228, v228, 0x3a800000, v177
	v_fmamk_f32 v232, v232, 0x3a800000, v177
	v_fmamk_f32 v236, v236, 0x3a800000, v177
	v_rsq_f32_e32 v176, v208
	v_rsq_f32_e32 v174, v212
	v_rsq_f32_e32 v172, v216
	v_rsq_f32_e32 v170, v220
	v_rsq_f32_e32 v168, v224
	v_rsq_f32_e32 v166, v228
	v_rsq_f32_e32 v164, v232
	v_rsq_f32_e32 v158, v236
	s_nop 0
	v_or_b32_e32 v160, 16, v162
	v_or_b32_e32 v156, 32, v162
	v_or_b32_e32 v154, 48, v162
	v_add_u32_e32 v148, 0x80, v162
	s_waitcnt vmcnt(0)
	s_waitcnt lgkmcnt(2)
	s_waitcnt lgkmcnt(2)
	s_waitcnt lgkmcnt(1)
	s_waitcnt lgkmcnt(2)
	s_waitcnt lgkmcnt(1)
	s_waitcnt lgkmcnt(0)
	s_nop 0
	s_nop 0
	v_add_u32_e32 v152, 0x90, v162
	s_waitcnt lgkmcnt(0)
	s_waitcnt lgkmcnt(0)
	s_waitcnt vmcnt(0)
	v_add_u32_e32 v150, 0xa0, v162
	s_waitcnt lgkmcnt(0)
	s_waitcnt lgkmcnt(0)
	s_nop 0
	s_nop 1
	v_add_u32_e32 v146, 0xb0, v162
	s_waitcnt lgkmcnt(0)
	s_waitcnt lgkmcnt(0)
	s_waitcnt vmcnt(1)
	s_waitcnt lgkmcnt(0)
	s_waitcnt lgkmcnt(0)
	s_waitcnt vmcnt(0)
	v_mov_b32_e32 v180, v120
	s_waitcnt lgkmcnt(0)
	s_waitcnt lgkmcnt(0)
	v_mov_b32_e32 v181, v124
	v_pk_mul_f32 v[180:181], v[180:181], v[176:177] op_sel_hi:[1,0]
	v_mov_b32_e32 v124, v121
	v_mul_f32_e32 v120, 0xbfb8aa3b, v181
	v_exp_f32_e32 v147, v120
	v_pk_mul_f32 v[120:121], v[124:125], v[176:177] op_sel_hi:[1,0]
	s_andn2_b64 vcc, exec, s[6:7]
	v_mul_f32_e32 v124, 0xbfb8aa3b, v121
	v_exp_f32_e32 v125, v124
	v_add_f32_e32 v147, 1.0, v147
	v_rcp_f32_e32 v147, v147
	v_lshl_or_b32 v124, s33, 7, v167
	v_add_f32_e32 v125, 1.0, v125
	v_rcp_f32_e32 v149, v125
	v_mul_f32_e32 v147, v181, v147
	v_mul_f32_e32 v147, v180, v147
	v_mov_b32_e32 v180, v122
	v_mov_b32_e32 v181, v126
	v_pk_mul_f32 v[180:181], v[180:181], v[176:177] op_sel_hi:[1,0]
	v_mov_b32_e32 v126, v123
	v_mul_f32_e32 v122, 0xbfb8aa3b, v181
	v_mul_f32_e32 v121, v121, v149
	v_exp_f32_e32 v149, v122
	v_pk_mul_f32 v[122:123], v[126:127], v[176:177] op_sel_hi:[1,0]
	v_mul_f32_e32 v127, v120, v121
	v_mul_f32_e32 v126, 0xbfb8aa3b, v123
	v_exp_f32_e32 v126, v126
	v_add_f32_e32 v120, 1.0, v149
	v_rcp_f32_e32 v149, v120
	v_mov_b32_e32 v121, v116
	v_add_f32_e32 v120, 1.0, v126
	v_rcp_f32_e32 v126, v120
	v_mov_b32_e32 v120, v112
	v_pk_mul_f32 v[120:121], v[120:121], v[176:177] op_sel_hi:[1,0]
	v_mul_f32_e32 v116, v181, v149
	v_mul_f32_e32 v112, 0xbfb8aa3b, v121
	v_exp_f32_e32 v112, v112
	v_mul_f32_e32 v149, v180, v116
	v_mov_b32_e32 v116, v113
	v_mul_f32_e32 v123, v123, v126
	v_add_f32_e32 v112, 1.0, v112
	v_rcp_f32_e32 v126, v112
	v_pk_mul_f32 v[112:113], v[116:117], v[176:177] op_sel_hi:[1,0]
	v_mul_f32_e32 v122, v122, v123
	v_mul_f32_e32 v116, 0xbfb8aa3b, v113
	v_exp_f32_e32 v116, v116
	v_mul_f32_e32 v117, v121, v126
	v_mul_f32_e32 v120, v120, v117
	v_mov_b32_e32 v117, v118
	v_add_f32_e32 v116, 1.0, v116
	v_rcp_f32_e32 v121, v116
	v_mov_b32_e32 v116, v114
	v_pk_mul_f32 v[116:117], v[116:117], v[176:177] op_sel_hi:[1,0]
	v_mov_b32_e32 v118, v115
	v_mul_f32_e32 v114, 0xbfb8aa3b, v117
	v_exp_f32_e32 v123, v114
	v_pk_mul_f32 v[114:115], v[118:119], v[176:177] op_sel_hi:[1,0]
	v_mul_f32_e32 v113, v113, v121
	v_mul_f32_e32 v118, 0xbfb8aa3b, v115
	v_exp_f32_e32 v118, v118
	v_add_f32_e32 v119, 1.0, v123
	v_rcp_f32_e32 v119, v119
	v_mul_f32_e32 v112, v112, v113
	v_add_f32_e32 v118, 1.0, v118
	v_rcp_f32_e32 v118, v118
	v_mul_f32_e32 v113, v117, v119
	v_mul_f32_e32 v113, v116, v113
	v_cvt_pk_bf16_f32 v116, v147, v127
	v_cvt_pk_bf16_f32 v117, v149, v122
	v_mov_b32_e32 v122, v104
	v_mov_b32_e32 v123, v108
	v_mul_f32_e32 v115, v115, v118
	v_pk_mul_f32 v[122:123], v[122:123], v[174:175] op_sel_hi:[1,0]
	v_ashrrev_i32_e32 v125, 31, v124
	v_mul_f32_e32 v114, v114, v115
	v_mul_f32_e32 v104, 0xbfb8aa3b, v123
	v_cvt_pk_bf16_f32 v118, v120, v112
	v_cvt_pk_bf16_f32 v119, v113, v114
	v_lshlrev_b64 v[114:115], 1, v[124:125]
	v_exp_f32_e32 v124, v104
	v_mov_b32_e32 v108, v105
	v_mov_b64_e32 v[112:113], s[26:27]
	v_pk_mul_f32 v[104:105], v[108:109], v[174:175] op_sel_hi:[1,0]
	v_mad_i64_i32 v[120:121], s[4:5], v162, s52, v[112:113]
	v_mul_f32_e32 v108, 0xbfb8aa3b, v105
	v_exp_f32_e32 v125, v108
	v_lshl_add_u64 v[108:109], v[120:121], 0, v[114:115]
	v_add_f32_e32 v120, 1.0, v124
	v_rcp_f32_e32 v120, v120
	global_store_dwordx4 v[108:109], v[116:119], off
	v_mov_b32_e32 v109, v110
	v_add_f32_e32 v121, 1.0, v125
	v_mul_f32_e32 v108, v123, v120
	v_mul_f32_e32 v116, v122, v108
	v_mov_b32_e32 v108, v106
	v_pk_mul_f32 v[108:109], v[108:109], v[174:175] op_sel_hi:[1,0]
	v_mov_b32_e32 v110, v107
	v_mul_f32_e32 v106, 0xbfb8aa3b, v109
	v_rcp_f32_e32 v121, v121
	v_exp_f32_e32 v117, v106
	v_pk_mul_f32 v[106:107], v[110:111], v[174:175] op_sel_hi:[1,0]
	v_mul_f32_e32 v105, v105, v121
	v_mul_f32_e32 v110, 0xbfb8aa3b, v107
	v_exp_f32_e32 v110, v110
	v_mul_f32_e32 v111, v104, v105
	v_add_f32_e32 v104, 1.0, v117
	v_rcp_f32_e32 v117, v104
	v_add_f32_e32 v104, 1.0, v110
	v_rcp_f32_e32 v110, v104
	v_mov_b32_e32 v104, v96
	v_mov_b32_e32 v105, v100
	v_pk_mul_f32 v[104:105], v[104:105], v[174:175] op_sel_hi:[1,0]
	v_mul_f32_e32 v100, v109, v117
	v_mul_f32_e32 v96, 0xbfb8aa3b, v105
	v_exp_f32_e32 v96, v96
	v_mul_f32_e32 v108, v108, v100
	v_mov_b32_e32 v100, v97
	v_mul_f32_e32 v107, v107, v110
	v_add_f32_e32 v96, 1.0, v96
	v_rcp_f32_e32 v109, v96
	v_pk_mul_f32 v[96:97], v[100:101], v[174:175] op_sel_hi:[1,0]
	v_mul_f32_e32 v106, v106, v107
	v_mul_f32_e32 v100, 0xbfb8aa3b, v97
	v_exp_f32_e32 v100, v100
	v_mul_f32_e32 v101, v105, v109
	v_mul_f32_e32 v104, v104, v101
	v_mov_b32_e32 v101, v102
	v_add_f32_e32 v100, 1.0, v100
	v_rcp_f32_e32 v105, v100
	v_mov_b32_e32 v100, v98
	v_pk_mul_f32 v[100:101], v[100:101], v[174:175] op_sel_hi:[1,0]
	v_mov_b32_e32 v102, v99
	v_mul_f32_e32 v98, 0xbfb8aa3b, v101
	v_exp_f32_e32 v107, v98
	v_pk_mul_f32 v[98:99], v[102:103], v[174:175] op_sel_hi:[1,0]
	v_mul_f32_e32 v97, v97, v105
	v_mul_f32_e32 v102, 0xbfb8aa3b, v99
	v_exp_f32_e32 v102, v102
	v_add_f32_e32 v103, 1.0, v107
	v_rcp_f32_e32 v103, v103
	v_mul_f32_e32 v105, v96, v97
	v_add_f32_e32 v102, 1.0, v102
	v_rcp_f32_e32 v102, v102
	v_mul_f32_e32 v96, v101, v103
	v_mul_f32_e32 v100, v100, v96
	v_mov_b32_e32 v103, v92
	v_mul_f32_e32 v96, v99, v102
	v_mov_b32_e32 v102, v88
	v_pk_mul_f32 v[102:103], v[102:103], v[172:173] op_sel_hi:[1,0]
	v_mul_f32_e32 v99, v98, v96
	v_mul_f32_e32 v88, 0xbfb8aa3b, v103
	v_cvt_pk_bf16_f32 v96, v116, v111
	v_cvt_pk_bf16_f32 v97, v108, v106
	v_cvt_pk_bf16_f32 v98, v104, v105
	v_exp_f32_e32 v104, v88
	v_mov_b32_e32 v92, v89
	v_pk_mul_f32 v[88:89], v[92:93], v[172:173] op_sel_hi:[1,0]
	v_cvt_pk_bf16_f32 v99, v100, v99
	v_mad_i64_i32 v[100:101], s[4:5], v160, s52, v[112:113]
	v_mul_f32_e32 v92, 0xbfb8aa3b, v89
	v_exp_f32_e32 v105, v92
	v_lshl_add_u64 v[92:93], v[100:101], 0, v[114:115]
	v_add_f32_e32 v100, 1.0, v104
	v_rcp_f32_e32 v100, v100
	global_store_dwordx4 v[92:93], v[96:99], off
	v_mov_b32_e32 v93, v94
	v_add_f32_e32 v101, 1.0, v105
	v_mul_f32_e32 v92, v103, v100
	v_mul_f32_e32 v96, v102, v92
	v_mov_b32_e32 v92, v90
	v_pk_mul_f32 v[92:93], v[92:93], v[172:173] op_sel_hi:[1,0]
	v_mov_b32_e32 v94, v91
	v_mul_f32_e32 v90, 0xbfb8aa3b, v93
	v_rcp_f32_e32 v101, v101
	v_exp_f32_e32 v97, v90
	v_pk_mul_f32 v[90:91], v[94:95], v[172:173] op_sel_hi:[1,0]
	v_mul_f32_e32 v89, v89, v101
	v_mul_f32_e32 v94, 0xbfb8aa3b, v91
	v_exp_f32_e32 v94, v94
	v_mul_f32_e32 v95, v88, v89
	v_add_f32_e32 v88, 1.0, v97
	v_rcp_f32_e32 v97, v88
	v_add_f32_e32 v88, 1.0, v94
	v_rcp_f32_e32 v94, v88
	v_mov_b32_e32 v88, v80
	v_mov_b32_e32 v89, v84
	v_pk_mul_f32 v[88:89], v[88:89], v[172:173] op_sel_hi:[1,0]
	v_mul_f32_e32 v84, v93, v97
	v_mul_f32_e32 v80, 0xbfb8aa3b, v89
	v_exp_f32_e32 v80, v80
	v_mul_f32_e32 v92, v92, v84
	v_mov_b32_e32 v84, v81
	v_mul_f32_e32 v91, v91, v94
	v_add_f32_e32 v80, 1.0, v80
	v_rcp_f32_e32 v93, v80
	v_pk_mul_f32 v[80:81], v[84:85], v[172:173] op_sel_hi:[1,0]
	v_mul_f32_e32 v90, v90, v91
	v_mul_f32_e32 v84, 0xbfb8aa3b, v81
	v_exp_f32_e32 v84, v84
	v_mul_f32_e32 v85, v89, v93
	v_mul_f32_e32 v88, v88, v85
	v_mov_b32_e32 v85, v86
	v_add_f32_e32 v84, 1.0, v84
	v_rcp_f32_e32 v89, v84
	v_mov_b32_e32 v84, v82
	v_pk_mul_f32 v[84:85], v[84:85], v[172:173] op_sel_hi:[1,0]
	v_mov_b32_e32 v86, v83
	v_mul_f32_e32 v82, 0xbfb8aa3b, v85
	v_exp_f32_e32 v91, v82
	v_pk_mul_f32 v[82:83], v[86:87], v[172:173] op_sel_hi:[1,0]
	v_mul_f32_e32 v81, v81, v89
	v_mul_f32_e32 v86, 0xbfb8aa3b, v83
	v_exp_f32_e32 v86, v86
	v_add_f32_e32 v87, 1.0, v91
	v_rcp_f32_e32 v87, v87
	v_mul_f32_e32 v89, v80, v81
	v_add_f32_e32 v86, 1.0, v86
	v_rcp_f32_e32 v86, v86
	v_mul_f32_e32 v80, v85, v87
	v_mul_f32_e32 v84, v84, v80
	v_mov_b32_e32 v87, v76
	v_mul_f32_e32 v80, v83, v86
	v_mov_b32_e32 v86, v72
	v_pk_mul_f32 v[86:87], v[86:87], v[170:171] op_sel_hi:[1,0]
	v_mul_f32_e32 v83, v82, v80
	v_mul_f32_e32 v72, 0xbfb8aa3b, v87
	v_cvt_pk_bf16_f32 v80, v96, v95
	v_cvt_pk_bf16_f32 v81, v92, v90
	v_cvt_pk_bf16_f32 v82, v88, v89
	v_exp_f32_e32 v88, v72
	v_mov_b32_e32 v76, v73
	v_pk_mul_f32 v[72:73], v[76:77], v[170:171] op_sel_hi:[1,0]
	v_cvt_pk_bf16_f32 v83, v84, v83
	v_mad_i64_i32 v[84:85], s[4:5], v156, s52, v[112:113]
	v_mul_f32_e32 v76, 0xbfb8aa3b, v73
	v_exp_f32_e32 v89, v76
	v_lshl_add_u64 v[76:77], v[84:85], 0, v[114:115]
	v_add_f32_e32 v84, 1.0, v88
	v_rcp_f32_e32 v84, v84
	global_store_dwordx4 v[76:77], v[80:83], off
	v_mov_b32_e32 v77, v78
	v_add_f32_e32 v85, 1.0, v89
	v_mul_f32_e32 v76, v87, v84
	v_mul_f32_e32 v80, v86, v76
	v_mov_b32_e32 v76, v74
	v_pk_mul_f32 v[76:77], v[76:77], v[170:171] op_sel_hi:[1,0]
	v_mov_b32_e32 v78, v75
	v_mul_f32_e32 v74, 0xbfb8aa3b, v77
	v_rcp_f32_e32 v85, v85
	v_exp_f32_e32 v81, v74
	v_pk_mul_f32 v[74:75], v[78:79], v[170:171] op_sel_hi:[1,0]
	v_mul_f32_e32 v73, v73, v85
	v_mul_f32_e32 v78, 0xbfb8aa3b, v75
	v_exp_f32_e32 v78, v78
	v_mul_f32_e32 v79, v72, v73
	v_add_f32_e32 v72, 1.0, v81
	v_rcp_f32_e32 v81, v72
	v_add_f32_e32 v72, 1.0, v78
	v_rcp_f32_e32 v78, v72
	v_mov_b32_e32 v72, v64
	v_mov_b32_e32 v73, v68
	v_pk_mul_f32 v[72:73], v[72:73], v[170:171] op_sel_hi:[1,0]
	v_mul_f32_e32 v68, v77, v81
	v_mul_f32_e32 v64, 0xbfb8aa3b, v73
	v_exp_f32_e32 v64, v64
	v_mul_f32_e32 v76, v76, v68
	v_mov_b32_e32 v68, v65
	v_mul_f32_e32 v75, v75, v78
	v_add_f32_e32 v64, 1.0, v64
	v_rcp_f32_e32 v77, v64
	v_pk_mul_f32 v[64:65], v[68:69], v[170:171] op_sel_hi:[1,0]
	v_mul_f32_e32 v74, v74, v75
	v_mul_f32_e32 v68, 0xbfb8aa3b, v65
	v_exp_f32_e32 v68, v68
	v_mul_f32_e32 v69, v73, v77
	v_mul_f32_e32 v72, v72, v69
	v_mov_b32_e32 v69, v70
	v_add_f32_e32 v68, 1.0, v68
	v_rcp_f32_e32 v73, v68
	v_mov_b32_e32 v68, v66
	v_pk_mul_f32 v[68:69], v[68:69], v[170:171] op_sel_hi:[1,0]
	v_mov_b32_e32 v70, v67
	v_mul_f32_e32 v66, 0xbfb8aa3b, v69
	v_exp_f32_e32 v75, v66
	v_pk_mul_f32 v[66:67], v[70:71], v[170:171] op_sel_hi:[1,0]
	v_mul_f32_e32 v65, v65, v73
	v_mul_f32_e32 v70, 0xbfb8aa3b, v67
	v_exp_f32_e32 v70, v70
	v_add_f32_e32 v71, 1.0, v75
	v_rcp_f32_e32 v71, v71
	v_mul_f32_e32 v73, v64, v65
	v_add_f32_e32 v70, 1.0, v70
	v_rcp_f32_e32 v70, v70
	v_mul_f32_e32 v64, v69, v71
	v_mul_f32_e32 v68, v68, v64
	v_mov_b32_e32 v71, v60
	v_mul_f32_e32 v64, v67, v70
	v_mov_b32_e32 v70, v56
	v_pk_mul_f32 v[70:71], v[70:71], v[168:169] op_sel_hi:[1,0]
	v_mul_f32_e32 v67, v66, v64
	v_mul_f32_e32 v56, 0xbfb8aa3b, v71
	v_cvt_pk_bf16_f32 v64, v80, v79
	v_cvt_pk_bf16_f32 v65, v76, v74
	v_cvt_pk_bf16_f32 v66, v72, v73
	v_exp_f32_e32 v72, v56
	v_mov_b32_e32 v60, v57
	v_pk_mul_f32 v[56:57], v[60:61], v[168:169] op_sel_hi:[1,0]
	v_cvt_pk_bf16_f32 v67, v68, v67
	v_mad_i64_i32 v[68:69], s[4:5], v154, s52, v[112:113]
	v_mul_f32_e32 v60, 0xbfb8aa3b, v57
	v_exp_f32_e32 v73, v60
	v_lshl_add_u64 v[60:61], v[68:69], 0, v[114:115]
	v_add_f32_e32 v68, 1.0, v72
	v_rcp_f32_e32 v68, v68
	global_store_dwordx4 v[60:61], v[64:67], off
	v_mov_b32_e32 v61, v62
	v_add_f32_e32 v69, 1.0, v73
	v_mul_f32_e32 v60, v71, v68
	v_mul_f32_e32 v64, v70, v60
	v_mov_b32_e32 v60, v58
	v_pk_mul_f32 v[60:61], v[60:61], v[168:169] op_sel_hi:[1,0]
	v_mov_b32_e32 v62, v59
	v_mul_f32_e32 v58, 0xbfb8aa3b, v61
	v_rcp_f32_e32 v69, v69
	v_exp_f32_e32 v65, v58
	v_pk_mul_f32 v[58:59], v[62:63], v[168:169] op_sel_hi:[1,0]
	v_mul_f32_e32 v57, v57, v69
	v_mul_f32_e32 v62, 0xbfb8aa3b, v59
	v_exp_f32_e32 v62, v62
	v_mul_f32_e32 v63, v56, v57
	v_add_f32_e32 v56, 1.0, v65
	v_rcp_f32_e32 v65, v56
	v_add_f32_e32 v56, 1.0, v62
	v_rcp_f32_e32 v62, v56
	v_mov_b32_e32 v56, v48
	v_mov_b32_e32 v57, v52
	v_pk_mul_f32 v[56:57], v[56:57], v[168:169] op_sel_hi:[1,0]
	v_mul_f32_e32 v52, v61, v65
	v_mul_f32_e32 v48, 0xbfb8aa3b, v57
	v_exp_f32_e32 v48, v48
	v_mul_f32_e32 v60, v60, v52
	v_mov_b32_e32 v52, v49
	v_mul_f32_e32 v59, v59, v62
	v_add_f32_e32 v48, 1.0, v48
	v_rcp_f32_e32 v61, v48
	v_pk_mul_f32 v[48:49], v[52:53], v[168:169] op_sel_hi:[1,0]
	v_mul_f32_e32 v58, v58, v59
	v_mul_f32_e32 v52, 0xbfb8aa3b, v49
	v_exp_f32_e32 v52, v52
	v_mul_f32_e32 v53, v57, v61
	v_mul_f32_e32 v56, v56, v53
	v_mov_b32_e32 v53, v54
	v_add_f32_e32 v52, 1.0, v52
	v_rcp_f32_e32 v57, v52
	v_mov_b32_e32 v52, v50
	v_pk_mul_f32 v[52:53], v[52:53], v[168:169] op_sel_hi:[1,0]
	v_mov_b32_e32 v54, v51
	v_mul_f32_e32 v50, 0xbfb8aa3b, v53
	v_exp_f32_e32 v59, v50
	v_pk_mul_f32 v[50:51], v[54:55], v[168:169] op_sel_hi:[1,0]
	v_mul_f32_e32 v49, v49, v57
	v_mul_f32_e32 v54, 0xbfb8aa3b, v51
	v_exp_f32_e32 v54, v54
	v_add_f32_e32 v55, 1.0, v59
	v_rcp_f32_e32 v55, v55
	v_mul_f32_e32 v57, v48, v49
	v_add_f32_e32 v54, 1.0, v54
	v_rcp_f32_e32 v54, v54
	v_mul_f32_e32 v48, v53, v55
	v_mul_f32_e32 v52, v52, v48
	v_mov_b32_e32 v55, v44
	v_mul_f32_e32 v48, v51, v54
	v_mov_b32_e32 v54, v40
	v_pk_mul_f32 v[54:55], v[54:55], v[166:167] op_sel_hi:[1,0]
	v_mul_f32_e32 v51, v50, v48
	v_mul_f32_e32 v40, 0xbfb8aa3b, v55
	v_cvt_pk_bf16_f32 v48, v64, v63
	v_cvt_pk_bf16_f32 v49, v60, v58
	v_cvt_pk_bf16_f32 v50, v56, v57
	v_exp_f32_e32 v56, v40
	v_mov_b32_e32 v44, v41
	v_pk_mul_f32 v[40:41], v[44:45], v[166:167] op_sel_hi:[1,0]
	v_cvt_pk_bf16_f32 v51, v52, v51
	v_mad_i64_i32 v[52:53], s[4:5], v148, s52, v[112:113]
	v_mul_f32_e32 v44, 0xbfb8aa3b, v41
	v_exp_f32_e32 v57, v44
	v_lshl_add_u64 v[44:45], v[52:53], 0, v[114:115]
	v_add_f32_e32 v52, 1.0, v56
	v_rcp_f32_e32 v52, v52
	global_store_dwordx4 v[44:45], v[48:51], off
	v_mov_b32_e32 v45, v46
	v_add_f32_e32 v53, 1.0, v57
	v_mul_f32_e32 v44, v55, v52
	v_mul_f32_e32 v48, v54, v44
	v_mov_b32_e32 v44, v42
	v_pk_mul_f32 v[44:45], v[44:45], v[166:167] op_sel_hi:[1,0]
	v_mov_b32_e32 v46, v43
	v_mul_f32_e32 v42, 0xbfb8aa3b, v45
	v_rcp_f32_e32 v53, v53
	v_exp_f32_e32 v49, v42
	v_pk_mul_f32 v[42:43], v[46:47], v[166:167] op_sel_hi:[1,0]
	v_mul_f32_e32 v41, v41, v53
	v_mul_f32_e32 v46, 0xbfb8aa3b, v43
	v_exp_f32_e32 v46, v46
	v_mul_f32_e32 v47, v40, v41
	v_add_f32_e32 v40, 1.0, v49
	v_rcp_f32_e32 v49, v40
	v_add_f32_e32 v40, 1.0, v46
	v_rcp_f32_e32 v46, v40
	v_mov_b32_e32 v40, v32
	v_mov_b32_e32 v41, v36
	v_pk_mul_f32 v[40:41], v[40:41], v[166:167] op_sel_hi:[1,0]
	v_mul_f32_e32 v36, v45, v49
	v_mul_f32_e32 v32, 0xbfb8aa3b, v41
	v_exp_f32_e32 v32, v32
	v_mul_f32_e32 v44, v44, v36
	v_mov_b32_e32 v36, v33
	v_mul_f32_e32 v43, v43, v46
	v_add_f32_e32 v32, 1.0, v32
	v_rcp_f32_e32 v45, v32
	v_pk_mul_f32 v[32:33], v[36:37], v[166:167] op_sel_hi:[1,0]
	v_mul_f32_e32 v42, v42, v43
	v_mul_f32_e32 v36, 0xbfb8aa3b, v33
	v_exp_f32_e32 v36, v36
	v_mul_f32_e32 v37, v41, v45
	v_mul_f32_e32 v40, v40, v37
	v_mov_b32_e32 v37, v38
	v_add_f32_e32 v36, 1.0, v36
	v_rcp_f32_e32 v41, v36
	v_mov_b32_e32 v36, v34
	v_pk_mul_f32 v[36:37], v[36:37], v[166:167] op_sel_hi:[1,0]
	v_mov_b32_e32 v38, v35
	v_mul_f32_e32 v34, 0xbfb8aa3b, v37
	v_exp_f32_e32 v43, v34
	v_pk_mul_f32 v[34:35], v[38:39], v[166:167] op_sel_hi:[1,0]
	v_mul_f32_e32 v33, v33, v41
	v_mul_f32_e32 v38, 0xbfb8aa3b, v35
	v_exp_f32_e32 v38, v38
	v_add_f32_e32 v39, 1.0, v43
	v_rcp_f32_e32 v39, v39
	v_mul_f32_e32 v41, v32, v33
	v_add_f32_e32 v38, 1.0, v38
	v_rcp_f32_e32 v38, v38
	v_mul_f32_e32 v32, v37, v39
	v_mul_f32_e32 v36, v36, v32
	v_mov_b32_e32 v39, v28
	v_mul_f32_e32 v32, v35, v38
	v_mov_b32_e32 v38, v24
	v_pk_mul_f32 v[38:39], v[38:39], v[164:165] op_sel_hi:[1,0]
	v_mul_f32_e32 v35, v34, v32
	v_mul_f32_e32 v24, 0xbfb8aa3b, v39
	v_cvt_pk_bf16_f32 v32, v48, v47
	v_cvt_pk_bf16_f32 v33, v44, v42
	v_cvt_pk_bf16_f32 v34, v40, v41
	v_exp_f32_e32 v40, v24
	v_mov_b32_e32 v28, v25
	v_pk_mul_f32 v[24:25], v[28:29], v[164:165] op_sel_hi:[1,0]
	v_cvt_pk_bf16_f32 v35, v36, v35
	v_mad_i64_i32 v[36:37], s[4:5], v152, s52, v[112:113]
	v_mul_f32_e32 v28, 0xbfb8aa3b, v25
	v_exp_f32_e32 v41, v28
	v_lshl_add_u64 v[28:29], v[36:37], 0, v[114:115]
	v_add_f32_e32 v36, 1.0, v40
	v_rcp_f32_e32 v36, v36
	global_store_dwordx4 v[28:29], v[32:35], off
	v_mov_b32_e32 v29, v30
	v_add_f32_e32 v37, 1.0, v41
	v_mul_f32_e32 v28, v39, v36
	v_mul_f32_e32 v32, v38, v28
	v_mov_b32_e32 v28, v26
	v_pk_mul_f32 v[28:29], v[28:29], v[164:165] op_sel_hi:[1,0]
	v_mov_b32_e32 v30, v27
	v_mul_f32_e32 v26, 0xbfb8aa3b, v29
	v_rcp_f32_e32 v37, v37
	v_exp_f32_e32 v33, v26
	v_pk_mul_f32 v[26:27], v[30:31], v[164:165] op_sel_hi:[1,0]
	v_mul_f32_e32 v25, v25, v37
	v_mul_f32_e32 v30, 0xbfb8aa3b, v27
	v_exp_f32_e32 v30, v30
	v_mul_f32_e32 v31, v24, v25
	v_add_f32_e32 v24, 1.0, v33
	v_rcp_f32_e32 v33, v24
	v_add_f32_e32 v24, 1.0, v30
	v_rcp_f32_e32 v30, v24
	v_mov_b32_e32 v24, v16
	v_mov_b32_e32 v25, v20
	v_pk_mul_f32 v[24:25], v[24:25], v[164:165] op_sel_hi:[1,0]
	v_mul_f32_e32 v20, v29, v33
	v_mul_f32_e32 v16, 0xbfb8aa3b, v25
	v_exp_f32_e32 v16, v16
	v_mul_f32_e32 v28, v28, v20
	v_mov_b32_e32 v20, v17
	v_mul_f32_e32 v27, v27, v30
	v_add_f32_e32 v16, 1.0, v16
	v_rcp_f32_e32 v29, v16
	v_pk_mul_f32 v[16:17], v[20:21], v[164:165] op_sel_hi:[1,0]
	v_mul_f32_e32 v26, v26, v27
	v_mul_f32_e32 v20, 0xbfb8aa3b, v17
	v_exp_f32_e32 v20, v20
	v_mul_f32_e32 v21, v25, v29
	v_mul_f32_e32 v24, v24, v21
	v_mov_b32_e32 v21, v22
	v_add_f32_e32 v20, 1.0, v20
	v_rcp_f32_e32 v25, v20
	v_mov_b32_e32 v20, v18
	v_pk_mul_f32 v[20:21], v[20:21], v[164:165] op_sel_hi:[1,0]
	v_mov_b32_e32 v22, v19
	v_mul_f32_e32 v18, 0xbfb8aa3b, v21
	v_exp_f32_e32 v27, v18
	v_pk_mul_f32 v[18:19], v[22:23], v[164:165] op_sel_hi:[1,0]
	v_mul_f32_e32 v17, v17, v25
	v_mul_f32_e32 v22, 0xbfb8aa3b, v19
	v_exp_f32_e32 v22, v22
	v_add_f32_e32 v23, 1.0, v27
	v_rcp_f32_e32 v23, v23
	v_mul_f32_e32 v25, v16, v17
	v_add_f32_e32 v22, 1.0, v22
	v_rcp_f32_e32 v22, v22
	v_mul_f32_e32 v16, v21, v23
	v_mul_f32_e32 v20, v20, v16
	v_mov_b32_e32 v23, v12
	v_mul_f32_e32 v16, v19, v22
	v_mov_b32_e32 v22, v8
	v_pk_mul_f32 v[22:23], v[22:23], v[158:159] op_sel_hi:[1,0]
	v_mul_f32_e32 v19, v18, v16
	v_mul_f32_e32 v8, 0xbfb8aa3b, v23
	v_cvt_pk_bf16_f32 v16, v32, v31
	v_cvt_pk_bf16_f32 v17, v28, v26
	v_cvt_pk_bf16_f32 v18, v24, v25
	v_exp_f32_e32 v24, v8
	v_mov_b32_e32 v12, v9
	v_pk_mul_f32 v[8:9], v[12:13], v[158:159] op_sel_hi:[1,0]
	v_cvt_pk_bf16_f32 v19, v20, v19
	v_mad_i64_i32 v[20:21], s[4:5], v150, s52, v[112:113]
	v_mul_f32_e32 v12, 0xbfb8aa3b, v9
	v_exp_f32_e32 v25, v12
	v_lshl_add_u64 v[12:13], v[20:21], 0, v[114:115]
	v_add_f32_e32 v20, 1.0, v24
	v_rcp_f32_e32 v20, v20
	global_store_dwordx4 v[12:13], v[16:19], off
	v_mov_b32_e32 v13, v14
	v_add_f32_e32 v21, 1.0, v25
	v_mul_f32_e32 v12, v23, v20
	v_mul_f32_e32 v16, v22, v12
	v_mov_b32_e32 v12, v10
	v_pk_mul_f32 v[12:13], v[12:13], v[158:159] op_sel_hi:[1,0]
	v_mov_b32_e32 v14, v11
	v_mul_f32_e32 v10, 0xbfb8aa3b, v13
	v_rcp_f32_e32 v21, v21
	v_exp_f32_e32 v17, v10
	v_pk_mul_f32 v[10:11], v[14:15], v[158:159] op_sel_hi:[1,0]
	v_mul_f32_e32 v9, v9, v21
	v_mul_f32_e32 v14, 0xbfb8aa3b, v11
	v_exp_f32_e32 v14, v14
	v_mul_f32_e32 v15, v8, v9
	v_add_f32_e32 v8, 1.0, v17
	v_rcp_f32_e32 v17, v8
	v_add_f32_e32 v8, 1.0, v14
	v_rcp_f32_e32 v14, v8
	v_mov_b32_e32 v8, v0
	v_mov_b32_e32 v9, v4
	v_pk_mul_f32 v[8:9], v[8:9], v[158:159] op_sel_hi:[1,0]
	v_mul_f32_e32 v4, v13, v17
	v_mul_f32_e32 v0, 0xbfb8aa3b, v9
	v_exp_f32_e32 v0, v0
	v_mul_f32_e32 v12, v12, v4
	v_mov_b32_e32 v4, v1
	v_mul_f32_e32 v11, v11, v14
	v_add_f32_e32 v0, 1.0, v0
	v_rcp_f32_e32 v13, v0
	v_pk_mul_f32 v[0:1], v[4:5], v[158:159] op_sel_hi:[1,0]
	v_mul_f32_e32 v10, v10, v11
	v_mul_f32_e32 v4, 0xbfb8aa3b, v1
	v_exp_f32_e32 v4, v4
	v_mul_f32_e32 v5, v9, v13
	v_mul_f32_e32 v8, v8, v5
	v_mov_b32_e32 v5, v6
	v_add_f32_e32 v4, 1.0, v4
	v_rcp_f32_e32 v9, v4
	v_mov_b32_e32 v4, v2
	v_pk_mul_f32 v[4:5], v[4:5], v[158:159] op_sel_hi:[1,0]
	v_mov_b32_e32 v6, v3
	v_mul_f32_e32 v2, 0xbfb8aa3b, v5
	v_exp_f32_e32 v11, v2
	v_pk_mul_f32 v[2:3], v[6:7], v[158:159] op_sel_hi:[1,0]
	v_mul_f32_e32 v1, v1, v9
	v_mul_f32_e32 v6, 0xbfb8aa3b, v3
	v_exp_f32_e32 v6, v6
	v_add_f32_e32 v7, 1.0, v11
	v_rcp_f32_e32 v7, v7
	v_mul_f32_e32 v9, v0, v1
	v_add_f32_e32 v6, 1.0, v6
	v_rcp_f32_e32 v6, v6
	v_mul_f32_e32 v0, v5, v7
	v_mul_f32_e32 v4, v4, v0
	v_mul_f32_e32 v0, v3, v6
	v_mul_f32_e32 v3, v2, v0
	v_cvt_pk_bf16_f32 v0, v16, v15
	v_cvt_pk_bf16_f32 v1, v12, v10
	v_cvt_pk_bf16_f32 v2, v8, v9
	v_cvt_pk_bf16_f32 v3, v4, v3
	v_mad_i64_i32 v[4:5], s[4:5], v146, s52, v[112:113]
	v_lshl_add_u64 v[4:5], v[4:5], 0, v[114:115]
	s_mov_b64 s[4:5], -1
	global_store_dwordx4 v[4:5], v[0:3], off
	s_cbranch_vccnz .LBB0_479
	s_andn2_b64 vcc, exec, s[16:17]
	s_cbranch_vccnz .LBB0_478
	s_barrier
	s_branch .LBB0_478

.LBB0_559:
	ds_read_b128 v[128:131], v189
	ds_read_b128 v[132:135], v189 offset:1024
	ds_read_b128 v[136:139], v189 offset:2048
	ds_read_b128 v[140:143], v189 offset:3072
	ds_read_b128 v[144:147], v190
	ds_read_b128 v[148:151], v190 offset:1024
	ds_read_b128 v[168:171], v190 offset:2048
	ds_read_b128 v[172:175], v190 offset:3072
	s_add_u32 s4, s22, 0x100
	s_addc_u32 s5, s23, 0
	s_cmp_eq_u32 s57, 40
	s_cselect_b32 s41, s11, s5
	s_cselect_b32 s40, s10, s4
	s_cselect_b32 s39, s37, s56
	s_cselect_b32 s38, s36, s55
	v_lshl_add_u64 v[184:185], s[22:23], 0, v[160:161]
	s_add_i32 m0, s43, 0xc000
	ds_read_b128 v[176:179], v191
	ds_read_b128 v[180:183], v191 offset:1024
	ds_read_b128 v[194:197], v191 offset:2048
	ds_read_b128 v[198:201], v191 offset:3072
	ds_read_b128 v[204:207], v191 offset:4096
	ds_read_b128 v[208:211], v191 offset:5120
	ds_read_b128 v[212:215], v191 offset:6144
	ds_read_b128 v[216:219], v191 offset:7168
	global_load_lds_dwordx4 v[184:185], off
	v_lshl_add_u64 v[184:185], s[22:23], 0, v[162:163]
	s_add_i32 m0, s43, 0xe000
	s_nop 0
	global_load_lds_dwordx4 v[184:185], off
	s_waitcnt vmcnt(8)
	s_waitcnt lgkmcnt(0)
	s_barrier
	s_setprio 0
	s_waitcnt lgkmcnt(0)
	v_mfma_f32_16x16x32_bf16 v[124:127], v[128:131], v[176:179], v[124:127]
	v_mfma_f32_16x16x32_bf16 v[120:123], v[136:139], v[176:179], v[120:123]
	v_mfma_f32_16x16x32_bf16 v[108:111], v[128:131], v[194:197], v[108:111]
	v_mfma_f32_16x16x32_bf16 v[104:107], v[136:139], v[194:197], v[104:107]
	v_mfma_f32_16x16x32_bf16 v[92:95], v[128:131], v[204:207], v[92:95]
	v_mfma_f32_16x16x32_bf16 v[88:91], v[136:139], v[204:207], v[88:91]
	v_mfma_f32_16x16x32_bf16 v[76:79], v[128:131], v[212:215], v[76:79]
	v_mfma_f32_16x16x32_bf16 v[72:75], v[136:139], v[212:215], v[72:75]
	v_mfma_f32_16x16x32_bf16 v[124:127], v[132:135], v[180:183], v[124:127]
	v_mfma_f32_16x16x32_bf16 v[120:123], v[140:143], v[180:183], v[120:123]
	v_mfma_f32_16x16x32_bf16 v[108:111], v[132:135], v[198:201], v[108:111]
	v_mfma_f32_16x16x32_bf16 v[104:107], v[140:143], v[198:201], v[104:107]
	v_mfma_f32_16x16x32_bf16 v[92:95], v[132:135], v[208:211], v[92:95]
	v_mfma_f32_16x16x32_bf16 v[88:91], v[140:143], v[208:211], v[88:91]
	v_mfma_f32_16x16x32_bf16 v[76:79], v[132:135], v[216:219], v[76:79]
	v_mfma_f32_16x16x32_bf16 v[72:75], v[140:143], v[216:219], v[72:75]
	v_mfma_f32_16x16x32_bf16 v[116:119], v[144:147], v[176:179], v[116:119]
	v_mfma_f32_16x16x32_bf16 v[112:115], v[168:171], v[176:179], v[112:115]
	v_mfma_f32_16x16x32_bf16 v[100:103], v[144:147], v[194:197], v[100:103]
	v_mfma_f32_16x16x32_bf16 v[96:99], v[168:171], v[194:197], v[96:99]
	v_mfma_f32_16x16x32_bf16 v[84:87], v[144:147], v[204:207], v[84:87]
	v_mfma_f32_16x16x32_bf16 v[80:83], v[168:171], v[204:207], v[80:83]
	v_mfma_f32_16x16x32_bf16 v[68:71], v[144:147], v[212:215], v[68:71]
	v_mfma_f32_16x16x32_bf16 v[64:67], v[168:171], v[212:215], v[64:67]
	v_mfma_f32_16x16x32_bf16 v[116:119], v[148:151], v[180:183], v[116:119]
	v_mfma_f32_16x16x32_bf16 v[112:115], v[172:175], v[180:183], v[112:115]
	v_mfma_f32_16x16x32_bf16 v[100:103], v[148:151], v[198:201], v[100:103]
	v_mfma_f32_16x16x32_bf16 v[96:99], v[172:175], v[198:201], v[96:99]
	v_mfma_f32_16x16x32_bf16 v[84:87], v[148:151], v[208:211], v[84:87]
	v_mfma_f32_16x16x32_bf16 v[80:83], v[172:175], v[208:211], v[80:83]
	v_mfma_f32_16x16x32_bf16 v[68:71], v[148:151], v[216:219], v[68:71]
	v_mfma_f32_16x16x32_bf16 v[64:67], v[172:175], v[216:219], v[64:67]
	s_setprio 1
	s_barrier
	s_add_i32 s22, s49, s42
	v_lshl_add_u64 v[184:185], s[38:39], 0, v[154:155]
	s_mov_b32 m0, s22
	ds_read_b128 v[176:179], v191 offset:16384
	ds_read_b128 v[180:183], v191 offset:17408
	ds_read_b128 v[194:197], v191 offset:18432
	ds_read_b128 v[198:201], v191 offset:19456
	ds_read_b128 v[204:207], v191 offset:20480
	ds_read_b128 v[208:211], v191 offset:21504
	ds_read_b128 v[212:215], v191 offset:22528
	ds_read_b128 v[216:219], v191 offset:23552
	global_load_lds_dwordx4 v[184:185], off
	s_add_i32 m0, s22, 0x2000
	s_add_u32 s22, s38, 0xb0000
	v_lshl_add_u64 v[220:221], s[38:39], 0, v[158:159]
	s_addc_u32 s23, s39, 0
	s_add_i32 s58, s50, s42
	global_load_lds_dwordx4 v[220:221], off
	v_lshl_add_u64 v[222:223], s[22:23], 0, v[154:155]
	s_mov_b32 m0, s58
	v_lshl_add_u64 v[224:225], s[40:41], 0, v[156:157]
	global_load_lds_dwordx4 v[222:223], off
	v_lshl_add_u64 v[222:223], s[22:23], 0, v[158:159]
	s_add_i32 m0, s58, 0x2000
	s_nop 0
	global_load_lds_dwordx4 v[222:223], off
	v_lshl_add_u64 v[222:223], s[40:41], 0, v[152:153]
	s_mov_b32 m0, s43
	s_nop 0
	global_load_lds_dwordx4 v[222:223], off
	s_mov_b32 m0, s44
	s_nop 0
	global_load_lds_dwordx4 v[224:225], off
	s_waitcnt vmcnt(8)
	s_waitcnt lgkmcnt(0)
	s_barrier
	s_setprio 0
	s_waitcnt lgkmcnt(0)
	v_mfma_f32_16x16x32_bf16 v[60:63], v[128:131], v[176:179], v[60:63]
	v_mfma_f32_16x16x32_bf16 v[56:59], v[136:139], v[176:179], v[56:59]
	v_mfma_f32_16x16x32_bf16 v[44:47], v[128:131], v[194:197], v[44:47]
	v_mfma_f32_16x16x32_bf16 v[40:43], v[136:139], v[194:197], v[40:43]
	v_mfma_f32_16x16x32_bf16 v[28:31], v[128:131], v[204:207], v[28:31]
	v_mfma_f32_16x16x32_bf16 v[24:27], v[136:139], v[204:207], v[24:27]
	v_mfma_f32_16x16x32_bf16 v[12:15], v[128:131], v[212:215], v[12:15]
	v_mfma_f32_16x16x32_bf16 v[8:11], v[136:139], v[212:215], v[8:11]
	v_mfma_f32_16x16x32_bf16 v[60:63], v[132:135], v[180:183], v[60:63]
	v_mfma_f32_16x16x32_bf16 v[56:59], v[140:143], v[180:183], v[56:59]
	v_mfma_f32_16x16x32_bf16 v[44:47], v[132:135], v[198:201], v[44:47]
	v_mfma_f32_16x16x32_bf16 v[40:43], v[140:143], v[198:201], v[40:43]
	v_mfma_f32_16x16x32_bf16 v[28:31], v[132:135], v[208:211], v[28:31]
	v_mfma_f32_16x16x32_bf16 v[24:27], v[140:143], v[208:211], v[24:27]
	v_mfma_f32_16x16x32_bf16 v[12:15], v[132:135], v[216:219], v[12:15]
	v_mfma_f32_16x16x32_bf16 v[8:11], v[140:143], v[216:219], v[8:11]
	v_mfma_f32_16x16x32_bf16 v[52:55], v[144:147], v[176:179], v[52:55]
	v_mfma_f32_16x16x32_bf16 v[48:51], v[168:171], v[176:179], v[48:51]
	v_mfma_f32_16x16x32_bf16 v[36:39], v[144:147], v[194:197], v[36:39]
	v_mfma_f32_16x16x32_bf16 v[32:35], v[168:171], v[194:197], v[32:35]
	v_mfma_f32_16x16x32_bf16 v[20:23], v[144:147], v[204:207], v[20:23]
	v_mfma_f32_16x16x32_bf16 v[16:19], v[168:171], v[204:207], v[16:19]
	v_mfma_f32_16x16x32_bf16 v[4:7], v[144:147], v[212:215], v[4:7]
	v_mfma_f32_16x16x32_bf16 v[0:3], v[168:171], v[212:215], v[0:3]
	v_mfma_f32_16x16x32_bf16 v[52:55], v[148:151], v[180:183], v[52:55]
	v_mfma_f32_16x16x32_bf16 v[48:51], v[172:175], v[180:183], v[48:51]
	v_mfma_f32_16x16x32_bf16 v[36:39], v[148:151], v[198:201], v[36:39]
	v_mfma_f32_16x16x32_bf16 v[32:35], v[172:175], v[198:201], v[32:35]
	v_mfma_f32_16x16x32_bf16 v[20:23], v[148:151], v[208:211], v[20:23]
	v_mfma_f32_16x16x32_bf16 v[16:19], v[172:175], v[208:211], v[16:19]
	v_mfma_f32_16x16x32_bf16 v[4:7], v[148:151], v[216:219], v[4:7]
	v_mfma_f32_16x16x32_bf16 v[0:3], v[172:175], v[216:219], v[0:3]
	s_setprio 1
	s_barrier
	s_add_i32 s58, 0, 0x18000
	s_add_i32 s59, 0, 0x1c000
	v_add_u32_e32 v140, s58, v187
	v_add_u32_e32 v172, s59, v187
	ds_read_b128 v[128:131], v140
	ds_read_b128 v[132:135], v140 offset:1024
	ds_read_b128 v[136:139], v140 offset:2048
	ds_read_b128 v[140:143], v140 offset:3072
	ds_read_b128 v[144:147], v172
	ds_read_b128 v[148:151], v172 offset:1024
	ds_read_b128 v[168:171], v172 offset:2048
	ds_read_b128 v[172:175], v172 offset:3072
	s_add_u32 s22, s40, 0xb0000
	s_addc_u32 s23, s41, 0
	s_mov_b32 m0, s45
	v_lshl_add_u64 v[226:227], s[22:23], 0, v[152:153]
	ds_read_b128 v[176:179], v191 offset:32768
	ds_read_b128 v[180:183], v191 offset:33792
	ds_read_b128 v[194:197], v191 offset:34816
	ds_read_b128 v[198:201], v191 offset:35840
	ds_read_b128 v[204:207], v191 offset:36864
	ds_read_b128 v[208:211], v191 offset:37888
	ds_read_b128 v[212:215], v191 offset:38912
	ds_read_b128 v[216:219], v191 offset:39936
	global_load_lds_dwordx4 v[226:227], off
	v_lshl_add_u64 v[226:227], s[22:23], 0, v[156:157]
	s_mov_b32 m0, s46
	s_nop 0
	global_load_lds_dwordx4 v[226:227], off
	s_waitcnt vmcnt(8)
	s_waitcnt lgkmcnt(0)
	s_barrier
	s_setprio 0
	s_waitcnt lgkmcnt(0)
	v_mfma_f32_16x16x32_bf16 v[124:127], v[128:131], v[176:179], v[124:127]
	v_mfma_f32_16x16x32_bf16 v[120:123], v[136:139], v[176:179], v[120:123]
	v_mfma_f32_16x16x32_bf16 v[108:111], v[128:131], v[194:197], v[108:111]
	v_mfma_f32_16x16x32_bf16 v[104:107], v[136:139], v[194:197], v[104:107]
	v_mfma_f32_16x16x32_bf16 v[92:95], v[128:131], v[204:207], v[92:95]
	v_mfma_f32_16x16x32_bf16 v[88:91], v[136:139], v[204:207], v[88:91]
	v_mfma_f32_16x16x32_bf16 v[76:79], v[128:131], v[212:215], v[76:79]
	v_mfma_f32_16x16x32_bf16 v[72:75], v[136:139], v[212:215], v[72:75]
	v_mfma_f32_16x16x32_bf16 v[124:127], v[132:135], v[180:183], v[124:127]
	v_mfma_f32_16x16x32_bf16 v[120:123], v[140:143], v[180:183], v[120:123]
	v_mfma_f32_16x16x32_bf16 v[108:111], v[132:135], v[198:201], v[108:111]
	v_mfma_f32_16x16x32_bf16 v[104:107], v[140:143], v[198:201], v[104:107]
	v_mfma_f32_16x16x32_bf16 v[92:95], v[132:135], v[208:211], v[92:95]
	v_mfma_f32_16x16x32_bf16 v[88:91], v[140:143], v[208:211], v[88:91]
	v_mfma_f32_16x16x32_bf16 v[76:79], v[132:135], v[216:219], v[76:79]
	v_mfma_f32_16x16x32_bf16 v[72:75], v[140:143], v[216:219], v[72:75]
	v_mfma_f32_16x16x32_bf16 v[116:119], v[144:147], v[176:179], v[116:119]
	v_mfma_f32_16x16x32_bf16 v[112:115], v[168:171], v[176:179], v[112:115]
	v_mfma_f32_16x16x32_bf16 v[100:103], v[144:147], v[194:197], v[100:103]
	v_mfma_f32_16x16x32_bf16 v[96:99], v[168:171], v[194:197], v[96:99]
	v_mfma_f32_16x16x32_bf16 v[84:87], v[144:147], v[204:207], v[84:87]
	v_mfma_f32_16x16x32_bf16 v[80:83], v[168:171], v[204:207], v[80:83]
	v_mfma_f32_16x16x32_bf16 v[68:71], v[144:147], v[212:215], v[68:71]
	v_mfma_f32_16x16x32_bf16 v[64:67], v[168:171], v[212:215], v[64:67]
	v_mfma_f32_16x16x32_bf16 v[116:119], v[148:151], v[180:183], v[116:119]
	v_mfma_f32_16x16x32_bf16 v[112:115], v[172:175], v[180:183], v[112:115]
	v_mfma_f32_16x16x32_bf16 v[100:103], v[148:151], v[198:201], v[100:103]
	v_mfma_f32_16x16x32_bf16 v[96:99], v[172:175], v[198:201], v[96:99]
	v_mfma_f32_16x16x32_bf16 v[84:87], v[148:151], v[208:211], v[84:87]
	v_mfma_f32_16x16x32_bf16 v[80:83], v[172:175], v[208:211], v[80:83]
	v_mfma_f32_16x16x32_bf16 v[68:71], v[148:151], v[216:219], v[68:71]
	v_mfma_f32_16x16x32_bf16 v[64:67], v[172:175], v[216:219], v[64:67]
	s_setprio 1
	s_barrier
	s_add_i32 s22, s58, s42
	v_lshl_add_u64 v[184:185], v[184:185], 0, s[30:31]
	s_mov_b32 m0, s22
	ds_read_b128 v[176:179], v191 offset:49152
	ds_read_b128 v[180:183], v191 offset:50176
	ds_read_b128 v[194:197], v191 offset:51200
	ds_read_b128 v[198:201], v191 offset:52224
	ds_read_b128 v[204:207], v191 offset:53248
	ds_read_b128 v[208:211], v191 offset:54272
	ds_read_b128 v[212:215], v191 offset:55296
	ds_read_b128 v[216:219], v191 offset:56320
	global_load_lds_dwordx4 v[184:185], off
	s_add_i32 m0, s22, 0x2000
	s_add_u32 s22, s38, 0xb0080
	v_lshl_add_u64 v[184:185], v[220:221], 0, s[30:31]
	s_addc_u32 s23, s39, 0
	s_add_i32 s38, s59, s42
	global_load_lds_dwordx4 v[184:185], off
	v_lshl_add_u64 v[184:185], s[22:23], 0, v[154:155]
	s_mov_b32 m0, s38
	s_nop 0
	global_load_lds_dwordx4 v[184:185], off
	v_lshl_add_u64 v[184:185], s[22:23], 0, v[158:159]
	s_add_i32 m0, s38, 0x2000
	s_nop 0
	global_load_lds_dwordx4 v[184:185], off
	v_lshl_add_u64 v[184:185], v[222:223], 0, s[30:31]
	s_mov_b32 m0, s33
	s_nop 0
	global_load_lds_dwordx4 v[184:185], off
	v_lshl_add_u64 v[184:185], v[224:225], 0, s[30:31]
	s_mov_b32 m0, s48
	s_nop 0
	global_load_lds_dwordx4 v[184:185], off
	s_waitcnt vmcnt(8)
	s_waitcnt lgkmcnt(0)
	s_barrier
	s_setprio 0
	s_waitcnt lgkmcnt(0)
	v_mfma_f32_16x16x32_bf16 v[60:63], v[128:131], v[176:179], v[60:63]
	v_mfma_f32_16x16x32_bf16 v[56:59], v[136:139], v[176:179], v[56:59]
	v_mfma_f32_16x16x32_bf16 v[44:47], v[128:131], v[194:197], v[44:47]
	v_mfma_f32_16x16x32_bf16 v[40:43], v[136:139], v[194:197], v[40:43]
	v_mfma_f32_16x16x32_bf16 v[28:31], v[128:131], v[204:207], v[28:31]
	v_mfma_f32_16x16x32_bf16 v[24:27], v[136:139], v[204:207], v[24:27]
	v_mfma_f32_16x16x32_bf16 v[12:15], v[128:131], v[212:215], v[12:15]
	v_mfma_f32_16x16x32_bf16 v[8:11], v[136:139], v[212:215], v[8:11]
	v_mfma_f32_16x16x32_bf16 v[60:63], v[132:135], v[180:183], v[60:63]
	v_mfma_f32_16x16x32_bf16 v[56:59], v[140:143], v[180:183], v[56:59]
	v_mfma_f32_16x16x32_bf16 v[44:47], v[132:135], v[198:201], v[44:47]
	v_mfma_f32_16x16x32_bf16 v[40:43], v[140:143], v[198:201], v[40:43]
	v_mfma_f32_16x16x32_bf16 v[28:31], v[132:135], v[208:211], v[28:31]
	v_mfma_f32_16x16x32_bf16 v[24:27], v[140:143], v[208:211], v[24:27]
	v_mfma_f32_16x16x32_bf16 v[12:15], v[132:135], v[216:219], v[12:15]
	v_mfma_f32_16x16x32_bf16 v[8:11], v[140:143], v[216:219], v[8:11]
	v_mfma_f32_16x16x32_bf16 v[52:55], v[144:147], v[176:179], v[52:55]
	v_mfma_f32_16x16x32_bf16 v[48:51], v[168:171], v[176:179], v[48:51]
	v_mfma_f32_16x16x32_bf16 v[36:39], v[144:147], v[194:197], v[36:39]
	v_mfma_f32_16x16x32_bf16 v[32:35], v[168:171], v[194:197], v[32:35]
	v_mfma_f32_16x16x32_bf16 v[20:23], v[144:147], v[204:207], v[20:23]
	v_mfma_f32_16x16x32_bf16 v[16:19], v[168:171], v[204:207], v[16:19]
	v_mfma_f32_16x16x32_bf16 v[4:7], v[144:147], v[212:215], v[4:7]
	v_mfma_f32_16x16x32_bf16 v[0:3], v[168:171], v[212:215], v[0:3]
	v_mfma_f32_16x16x32_bf16 v[52:55], v[148:151], v[180:183], v[52:55]
	v_mfma_f32_16x16x32_bf16 v[48:51], v[172:175], v[180:183], v[48:51]
	v_mfma_f32_16x16x32_bf16 v[36:39], v[148:151], v[198:201], v[36:39]
	v_mfma_f32_16x16x32_bf16 v[32:35], v[172:175], v[198:201], v[32:35]
	v_mfma_f32_16x16x32_bf16 v[20:23], v[148:151], v[208:211], v[20:23]
	v_mfma_f32_16x16x32_bf16 v[16:19], v[172:175], v[208:211], v[16:19]
	v_mfma_f32_16x16x32_bf16 v[4:7], v[148:151], v[216:219], v[4:7]
	v_mfma_f32_16x16x32_bf16 v[0:3], v[172:175], v[216:219], v[0:3]
	s_setprio 1
	s_barrier
	s_add_i32 s57, s57, 2
	s_add_u32 s55, s55, 0x100
	s_addc_u32 s56, s56, 0
	s_cmp_gt_u32 s57, 41
	s_mov_b64 s[22:23], s[4:5]
	s_cbranch_scc0 .LBB0_559
	s_and_b64 vcc, exec, s[34:35]
	s_cbranch_vccz .LBB0_562
	s_barrier
.LBB0_562:
	s_setprio 0
	v_lshl_or_b32 v168, s12, 8, v188
	v_lshl_add_u32 v172, s54, 8, v186
	v_ashrrev_i32_e32 v169, 31, v168
	v_lshlrev_b64 v[204:205], 1, v[168:169]
	v_ashrrev_i32_e32 v173, 31, v172
	v_lshl_add_u64 v[170:171], s[26:27], 0, v[204:205]
	v_lshlrev_b64 v[206:207], 11, v[172:173]
	v_lshl_add_u64 v[128:129], v[170:171], 0, v[206:207]
	global_load_dwordx4 v[194:197], v[128:129], off
	global_load_dwordx4 v[198:201], v[128:129], off offset:256
	v_or_b32_e32 v182, 16, v172
	v_or_b32_e32 v178, 32, v172
	v_or_b32_e32 v174, 48, v172
	v_ashrrev_i32_e32 v183, 31, v182
	v_ashrrev_i32_e32 v179, 31, v178
	v_ashrrev_i32_e32 v175, 31, v174
	v_lshlrev_b64 v[184:185], 11, v[182:183]
	v_lshlrev_b64 v[180:181], 11, v[178:179]
	v_lshlrev_b64 v[176:177], 11, v[174:175]
	v_lshl_add_u64 v[128:129], v[170:171], 0, v[184:185]
	v_lshl_add_u64 v[130:131], v[170:171], 0, v[180:181]
	v_lshl_add_u64 v[208:209], v[170:171], 0, v[176:177]
	global_load_dwordx4 v[148:151], v[128:129], off
	global_load_dwordx4 v[144:147], v[128:129], off offset:256
	global_load_dwordx4 v[140:143], v[130:131], off
	global_load_dwordx4 v[136:139], v[130:131], off offset:256
	global_load_dwordx4 v[132:135], v[208:209], off
	s_nop 0
	global_load_dwordx4 v[128:131], v[208:209], off offset:256
	v_and_b32_e32 v208, 64, v192
	v_xor_b32_e32 v193, 16, v192
	v_add_u32_e32 v208, 64, v208
	v_xor_b32_e32 v209, 32, v192
	v_cmp_lt_i32_e32 vcc, v193, v208
	v_lshl_add_u64 v[206:207], s[26:27], 0, v[206:207]
	v_lshl_add_u64 v[204:205], v[206:207], 0, v[204:205]
	v_cndmask_b32_e32 v193, v192, v193, vcc
	v_cmp_lt_i32_e32 vcc, v209, v208
	v_lshlrev_b32_e32 v193, 2, v193
	s_lshl_b32 s38, s12, 2
	v_cndmask_b32_e32 v214, v192, v209, vcc
	s_ashr_i32 s39, s38, 31
	s_waitcnt vmcnt(0)
	v_lshlrev_b32_e32 v206, 16, v194
	v_and_b32_e32 v207, 0xffff0000, v194
	v_lshlrev_b32_e32 v194, 16, v195
	v_and_b32_e32 v195, 0xffff0000, v195
	v_lshlrev_b32_e32 v208, 16, v196
	v_and_b32_e32 v209, 0xffff0000, v196
	v_lshlrev_b32_e32 v196, 16, v197
	v_and_b32_e32 v197, 0xffff0000, v197
	v_lshlrev_b32_e32 v210, 16, v198
	v_and_b32_e32 v211, 0xffff0000, v198
	v_lshlrev_b32_e32 v198, 16, v199
	v_and_b32_e32 v199, 0xffff0000, v199
	v_lshlrev_b32_e32 v212, 16, v200
	v_and_b32_e32 v213, 0xffff0000, v200
	v_lshlrev_b32_e32 v200, 16, v201
	v_and_b32_e32 v201, 0xffff0000, v201
	v_pk_add_f32 v[126:127], v[126:127], v[194:195]
	v_pk_add_f32 v[124:125], v[124:125], v[206:207]
	v_pk_add_f32 v[122:123], v[122:123], v[196:197]
	v_pk_add_f32 v[120:121], v[120:121], v[208:209]
	v_pk_add_f32 v[118:119], v[118:119], v[198:199]
	v_pk_add_f32 v[116:117], v[116:117], v[210:211]
	v_pk_add_f32 v[194:195], v[114:115], v[200:201]
	v_pk_add_f32 v[196:197], v[112:113], v[212:213]
	v_mul_f32_e32 v114, v125, v125
	v_mul_f32_e32 v115, v127, v127
	v_mul_f32_e32 v198, v121, v121
	v_mul_f32_e32 v199, v123, v123
	v_cvt_pk_bf16_f32 v112, v124, v125
	v_cvt_pk_bf16_f32 v113, v126, v127
	v_mul_f32_e32 v125, v117, v117
	v_mul_f32_e32 v127, v119, v119
	v_mul_f32_e32 v200, v197, v197
	v_mul_f32_e32 v201, v195, v195
	v_fmac_f32_e32 v114, v124, v124
	v_fmac_f32_e32 v115, v126, v126
	v_fmac_f32_e32 v198, v120, v120
	v_fmac_f32_e32 v199, v122, v122
	v_fmac_f32_e32 v125, v116, v116
	v_fmac_f32_e32 v127, v118, v118
	v_fmac_f32_e32 v200, v196, v196
	v_fmac_f32_e32 v201, v194, v194
	v_add_f32_e32 v114, v114, v115
	v_add_f32_e32 v115, v198, v199
	v_add_f32_e32 v124, v125, v127
	v_add_f32_e32 v125, v200, v201
	v_add_f32_e32 v114, v114, v115
	v_add_f32_e32 v115, v124, v125
	v_add_f32_e32 v124, v114, v115
	ds_bpermute_b32 v125, v193, v124
	v_cvt_pk_bf16_f32 v114, v120, v121
	v_cvt_pk_bf16_f32 v115, v122, v123
	global_store_dwordx4 v[204:205], v[112:115], off
	v_cvt_pk_bf16_f32 v116, v116, v117
	v_cvt_pk_bf16_f32 v117, v118, v119
	v_cvt_pk_bf16_f32 v118, v196, v197
	v_cvt_pk_bf16_f32 v119, v194, v195
	global_store_dwordx4 v[204:205], v[116:119], off offset:256
	s_waitcnt lgkmcnt(0)
	v_add_f32_e32 v113, v124, v125
	v_lshlrev_b32_e32 v112, 2, v214
	ds_bpermute_b32 v114, v112, v113
	s_and_saveexec_b64 s[4:5], s[6:7]
	s_cbranch_execz .LBB0_564
	v_lshlrev_b64 v[116:117], 6, v[172:173]
	v_lshl_add_u64 v[116:117], s[28:29], 0, v[116:117]
	v_lshl_add_u64 v[116:117], s[38:39], 2, v[116:117]
	s_lshl_b32 s12, s47, 2
	v_lshl_add_u64 v[116:117], v[116:117], 0, s[12:13]
	s_waitcnt lgkmcnt(0)
	v_add_f32_e32 v113, v113, v114
	global_store_dword v[116:117], v113, off

.LBB0_643:
	ds_read_b128 v[128:131], v191
	ds_read_b128 v[132:135], v191 offset:1024
	ds_read_b128 v[156:159], v191 offset:2048
	ds_read_b128 v[160:163], v191 offset:3072
	ds_read_b128 v[164:167], v192
	ds_read_b128 v[168:171], v192 offset:1024
	ds_read_b128 v[172:175], v192 offset:2048
	ds_read_b128 v[176:179], v192 offset:3072
	s_add_u32 s4, s22, 0xfffc0080
	s_addc_u32 s5, s23, -1
	s_cmp_eq_u32 s63, 12
	s_cselect_b32 s47, s13, s5
	s_cselect_b32 s46, s17, s4
	s_cselect_b32 s5, s33, s62
	s_cselect_b32 s4, s39, s41
	v_lshl_add_u64 v[224:225], s[22:23], 0, v[148:149]
	s_add_i32 m0, s49, 0xc000
	ds_read_b128 v[180:183], v193
	ds_read_b128 v[184:187], v193 offset:1024
	ds_read_b128 v[198:201], v193 offset:2048
	ds_read_b128 v[204:207], v193 offset:3072
	ds_read_b128 v[208:211], v193 offset:4096
	ds_read_b128 v[212:215], v193 offset:5120
	ds_read_b128 v[216:219], v193 offset:6144
	ds_read_b128 v[220:223], v193 offset:7168
	global_load_lds_dwordx4 v[224:225], off
	v_lshl_add_u64 v[224:225], s[22:23], 0, v[150:151]
	s_add_i32 m0, s49, 0xe000
	s_nop 0
	global_load_lds_dwordx4 v[224:225], off
	s_waitcnt vmcnt(8)
	s_waitcnt lgkmcnt(0)
	s_barrier
	s_setprio 0
	s_waitcnt lgkmcnt(0)
	v_mfma_f32_16x16x32_bf16 v[124:127], v[128:131], v[180:183], v[124:127]
	v_mfma_f32_16x16x32_bf16 v[120:123], v[156:159], v[180:183], v[120:123]
	v_mfma_f32_16x16x32_bf16 v[108:111], v[128:131], v[198:201], v[108:111]
	v_mfma_f32_16x16x32_bf16 v[104:107], v[156:159], v[198:201], v[104:107]
	v_mfma_f32_16x16x32_bf16 v[92:95], v[128:131], v[208:211], v[92:95]
	v_mfma_f32_16x16x32_bf16 v[88:91], v[156:159], v[208:211], v[88:91]
	v_mfma_f32_16x16x32_bf16 v[76:79], v[128:131], v[216:219], v[76:79]
	v_mfma_f32_16x16x32_bf16 v[72:75], v[156:159], v[216:219], v[72:75]
	v_mfma_f32_16x16x32_bf16 v[124:127], v[132:135], v[184:187], v[124:127]
	v_mfma_f32_16x16x32_bf16 v[120:123], v[160:163], v[184:187], v[120:123]
	v_mfma_f32_16x16x32_bf16 v[108:111], v[132:135], v[204:207], v[108:111]
	v_mfma_f32_16x16x32_bf16 v[104:107], v[160:163], v[204:207], v[104:107]
	v_mfma_f32_16x16x32_bf16 v[92:95], v[132:135], v[212:215], v[92:95]
	v_mfma_f32_16x16x32_bf16 v[88:91], v[160:163], v[212:215], v[88:91]
	v_mfma_f32_16x16x32_bf16 v[76:79], v[132:135], v[220:223], v[76:79]
	v_mfma_f32_16x16x32_bf16 v[72:75], v[160:163], v[220:223], v[72:75]
	v_mfma_f32_16x16x32_bf16 v[116:119], v[164:167], v[180:183], v[116:119]
	v_mfma_f32_16x16x32_bf16 v[112:115], v[172:175], v[180:183], v[112:115]
	v_mfma_f32_16x16x32_bf16 v[100:103], v[164:167], v[198:201], v[100:103]
	v_mfma_f32_16x16x32_bf16 v[96:99], v[172:175], v[198:201], v[96:99]
	v_mfma_f32_16x16x32_bf16 v[84:87], v[164:167], v[208:211], v[84:87]
	v_mfma_f32_16x16x32_bf16 v[80:83], v[172:175], v[208:211], v[80:83]
	v_mfma_f32_16x16x32_bf16 v[68:71], v[164:167], v[216:219], v[68:71]
	v_mfma_f32_16x16x32_bf16 v[64:67], v[172:175], v[216:219], v[64:67]
	v_mfma_f32_16x16x32_bf16 v[116:119], v[168:171], v[184:187], v[116:119]
	v_mfma_f32_16x16x32_bf16 v[112:115], v[176:179], v[184:187], v[112:115]
	v_mfma_f32_16x16x32_bf16 v[100:103], v[168:171], v[204:207], v[100:103]
	v_mfma_f32_16x16x32_bf16 v[96:99], v[176:179], v[204:207], v[96:99]
	v_mfma_f32_16x16x32_bf16 v[84:87], v[168:171], v[212:215], v[84:87]
	v_mfma_f32_16x16x32_bf16 v[80:83], v[176:179], v[212:215], v[80:83]
	v_mfma_f32_16x16x32_bf16 v[68:71], v[168:171], v[220:223], v[68:71]
	v_mfma_f32_16x16x32_bf16 v[64:67], v[176:179], v[220:223], v[64:67]
	s_setprio 1
	s_barrier
	s_add_i32 s64, s59, s48
	v_lshl_add_u64 v[224:225], s[4:5], 0, v[138:139]
	s_mov_b32 m0, s64
	ds_read_b128 v[180:183], v193 offset:16384
	ds_read_b128 v[184:187], v193 offset:17408
	ds_read_b128 v[198:201], v193 offset:18432
	ds_read_b128 v[204:207], v193 offset:19456
	ds_read_b128 v[208:211], v193 offset:20480
	ds_read_b128 v[212:215], v193 offset:21504
	ds_read_b128 v[216:219], v193 offset:22528
	ds_read_b128 v[220:223], v193 offset:23552
	global_load_lds_dwordx4 v[224:225], off
	s_add_i32 m0, s64, 0x2000
	s_add_u32 s64, s4, 0x40000
	v_lshl_add_u64 v[226:227], s[4:5], 0, v[142:143]
	s_addc_u32 s65, s5, 0
	s_add_i32 s66, s60, s48
	global_load_lds_dwordx4 v[226:227], off
	v_lshl_add_u64 v[228:229], s[64:65], 0, v[138:139]
	s_mov_b32 m0, s66
	v_lshl_add_u64 v[230:231], s[46:47], 0, v[140:141]
	global_load_lds_dwordx4 v[228:229], off
	v_lshl_add_u64 v[228:229], s[64:65], 0, v[142:143]
	s_add_i32 m0, s66, 0x2000
	s_nop 0
	global_load_lds_dwordx4 v[228:229], off
	v_lshl_add_u64 v[228:229], s[46:47], 0, v[136:137]
	s_mov_b32 m0, s49
	s_nop 0
	global_load_lds_dwordx4 v[228:229], off
	s_mov_b32 m0, s50
	s_nop 0
	global_load_lds_dwordx4 v[230:231], off
	s_waitcnt vmcnt(8)
	s_waitcnt lgkmcnt(0)
	s_barrier
	s_setprio 0
	s_waitcnt lgkmcnt(0)
	v_mfma_f32_16x16x32_bf16 v[60:63], v[128:131], v[180:183], v[60:63]
	v_mfma_f32_16x16x32_bf16 v[56:59], v[156:159], v[180:183], v[56:59]
	v_mfma_f32_16x16x32_bf16 v[44:47], v[128:131], v[198:201], v[44:47]
	v_mfma_f32_16x16x32_bf16 v[40:43], v[156:159], v[198:201], v[40:43]
	v_mfma_f32_16x16x32_bf16 v[28:31], v[128:131], v[208:211], v[28:31]
	v_mfma_f32_16x16x32_bf16 v[24:27], v[156:159], v[208:211], v[24:27]
	v_mfma_f32_16x16x32_bf16 v[12:15], v[128:131], v[216:219], v[12:15]
	v_mfma_f32_16x16x32_bf16 v[8:11], v[156:159], v[216:219], v[8:11]
	v_mfma_f32_16x16x32_bf16 v[60:63], v[132:135], v[184:187], v[60:63]
	v_mfma_f32_16x16x32_bf16 v[56:59], v[160:163], v[184:187], v[56:59]
	v_mfma_f32_16x16x32_bf16 v[44:47], v[132:135], v[204:207], v[44:47]
	v_mfma_f32_16x16x32_bf16 v[40:43], v[160:163], v[204:207], v[40:43]
	v_mfma_f32_16x16x32_bf16 v[28:31], v[132:135], v[212:215], v[28:31]
	v_mfma_f32_16x16x32_bf16 v[24:27], v[160:163], v[212:215], v[24:27]
	v_mfma_f32_16x16x32_bf16 v[12:15], v[132:135], v[220:223], v[12:15]
	v_mfma_f32_16x16x32_bf16 v[8:11], v[160:163], v[220:223], v[8:11]
	v_mfma_f32_16x16x32_bf16 v[52:55], v[164:167], v[180:183], v[52:55]
	v_mfma_f32_16x16x32_bf16 v[48:51], v[172:175], v[180:183], v[48:51]
	v_mfma_f32_16x16x32_bf16 v[36:39], v[164:167], v[198:201], v[36:39]
	v_mfma_f32_16x16x32_bf16 v[32:35], v[172:175], v[198:201], v[32:35]
	v_mfma_f32_16x16x32_bf16 v[20:23], v[164:167], v[208:211], v[20:23]
	v_mfma_f32_16x16x32_bf16 v[16:19], v[172:175], v[208:211], v[16:19]
	v_mfma_f32_16x16x32_bf16 v[4:7], v[164:167], v[216:219], v[4:7]
	v_mfma_f32_16x16x32_bf16 v[0:3], v[172:175], v[216:219], v[0:3]
	v_mfma_f32_16x16x32_bf16 v[52:55], v[168:171], v[184:187], v[52:55]
	v_mfma_f32_16x16x32_bf16 v[48:51], v[176:179], v[184:187], v[48:51]
	v_mfma_f32_16x16x32_bf16 v[36:39], v[168:171], v[204:207], v[36:39]
	v_mfma_f32_16x16x32_bf16 v[32:35], v[176:179], v[204:207], v[32:35]
	v_mfma_f32_16x16x32_bf16 v[20:23], v[168:171], v[212:215], v[20:23]
	v_mfma_f32_16x16x32_bf16 v[16:19], v[176:179], v[212:215], v[16:19]
	v_mfma_f32_16x16x32_bf16 v[4:7], v[168:171], v[220:223], v[4:7]
	v_mfma_f32_16x16x32_bf16 v[0:3], v[176:179], v[220:223], v[0:3]
	s_setprio 1
	s_barrier
	s_add_i32 s64, 0, 0x18000
	v_add_u32_e32 v144, s64, v189
	s_add_i32 s65, 0, 0x1c000
	ds_read_b128 v[128:131], v144
	ds_read_b128 v[132:135], v144 offset:1024
	ds_read_b128 v[156:159], v144 offset:2048
	ds_read_b128 v[160:163], v144 offset:3072
	v_add_u32_e32 v144, s65, v189
	ds_read_b128 v[164:167], v144
	ds_read_b128 v[168:171], v144 offset:1024
	ds_read_b128 v[172:175], v144 offset:2048
	ds_read_b128 v[176:179], v144 offset:3072
	s_add_u32 s46, s46, 0x40000
	s_addc_u32 s47, s47, 0
	s_mov_b32 m0, s51
	v_lshl_add_u64 v[232:233], s[46:47], 0, v[136:137]
	ds_read_b128 v[180:183], v193 offset:32768
	ds_read_b128 v[184:187], v193 offset:33792
	ds_read_b128 v[198:201], v193 offset:34816
	ds_read_b128 v[204:207], v193 offset:35840
	ds_read_b128 v[208:211], v193 offset:36864
	ds_read_b128 v[212:215], v193 offset:37888
	ds_read_b128 v[216:219], v193 offset:38912
	ds_read_b128 v[220:223], v193 offset:39936
	global_load_lds_dwordx4 v[232:233], off
	v_lshl_add_u64 v[232:233], s[46:47], 0, v[140:141]
	s_mov_b32 m0, s52
	s_nop 0
	global_load_lds_dwordx4 v[232:233], off
	s_waitcnt vmcnt(8)
	s_waitcnt lgkmcnt(0)
	s_barrier
	s_setprio 0
	s_waitcnt lgkmcnt(0)
	v_mfma_f32_16x16x32_bf16 v[124:127], v[128:131], v[180:183], v[124:127]
	v_mfma_f32_16x16x32_bf16 v[120:123], v[156:159], v[180:183], v[120:123]
	v_mfma_f32_16x16x32_bf16 v[108:111], v[128:131], v[198:201], v[108:111]
	v_mfma_f32_16x16x32_bf16 v[104:107], v[156:159], v[198:201], v[104:107]
	v_mfma_f32_16x16x32_bf16 v[92:95], v[128:131], v[208:211], v[92:95]
	v_mfma_f32_16x16x32_bf16 v[88:91], v[156:159], v[208:211], v[88:91]
	v_mfma_f32_16x16x32_bf16 v[76:79], v[128:131], v[216:219], v[76:79]
	v_mfma_f32_16x16x32_bf16 v[72:75], v[156:159], v[216:219], v[72:75]
	v_mfma_f32_16x16x32_bf16 v[124:127], v[132:135], v[184:187], v[124:127]
	v_mfma_f32_16x16x32_bf16 v[120:123], v[160:163], v[184:187], v[120:123]
	v_mfma_f32_16x16x32_bf16 v[108:111], v[132:135], v[204:207], v[108:111]
	v_mfma_f32_16x16x32_bf16 v[104:107], v[160:163], v[204:207], v[104:107]
	v_mfma_f32_16x16x32_bf16 v[92:95], v[132:135], v[212:215], v[92:95]
	v_mfma_f32_16x16x32_bf16 v[88:91], v[160:163], v[212:215], v[88:91]
	v_mfma_f32_16x16x32_bf16 v[76:79], v[132:135], v[220:223], v[76:79]
	v_mfma_f32_16x16x32_bf16 v[72:75], v[160:163], v[220:223], v[72:75]
	v_mfma_f32_16x16x32_bf16 v[116:119], v[164:167], v[180:183], v[116:119]
	v_mfma_f32_16x16x32_bf16 v[112:115], v[172:175], v[180:183], v[112:115]
	v_mfma_f32_16x16x32_bf16 v[100:103], v[164:167], v[198:201], v[100:103]
	v_mfma_f32_16x16x32_bf16 v[96:99], v[172:175], v[198:201], v[96:99]
	v_mfma_f32_16x16x32_bf16 v[84:87], v[164:167], v[208:211], v[84:87]
	v_mfma_f32_16x16x32_bf16 v[80:83], v[172:175], v[208:211], v[80:83]
	v_mfma_f32_16x16x32_bf16 v[68:71], v[164:167], v[216:219], v[68:71]
	v_mfma_f32_16x16x32_bf16 v[64:67], v[172:175], v[216:219], v[64:67]
	v_mfma_f32_16x16x32_bf16 v[116:119], v[168:171], v[184:187], v[116:119]
	v_mfma_f32_16x16x32_bf16 v[112:115], v[176:179], v[184:187], v[112:115]
	v_mfma_f32_16x16x32_bf16 v[100:103], v[168:171], v[204:207], v[100:103]
	v_mfma_f32_16x16x32_bf16 v[96:99], v[176:179], v[204:207], v[96:99]
	v_mfma_f32_16x16x32_bf16 v[84:87], v[168:171], v[212:215], v[84:87]
	v_mfma_f32_16x16x32_bf16 v[80:83], v[176:179], v[212:215], v[80:83]
	v_mfma_f32_16x16x32_bf16 v[68:71], v[168:171], v[220:223], v[68:71]
	v_mfma_f32_16x16x32_bf16 v[64:67], v[176:179], v[220:223], v[64:67]
	s_setprio 1
	s_barrier
	s_add_i32 s46, s64, s48
	v_lshl_add_u64 v[224:225], v[224:225], 0, s[30:31]
	s_mov_b32 m0, s46
	ds_read_b128 v[180:183], v193 offset:49152
	ds_read_b128 v[184:187], v193 offset:50176
	ds_read_b128 v[198:201], v193 offset:51200
	ds_read_b128 v[204:207], v193 offset:52224
	ds_read_b128 v[208:211], v193 offset:53248
	ds_read_b128 v[212:215], v193 offset:54272
	ds_read_b128 v[216:219], v193 offset:55296
	ds_read_b128 v[220:223], v193 offset:56320
	global_load_lds_dwordx4 v[224:225], off
	s_add_i32 m0, s46, 0x2000
	s_add_u32 s4, s4, 0x40080
	v_lshl_add_u64 v[224:225], v[226:227], 0, s[30:31]
	s_addc_u32 s5, s5, 0
	s_add_i32 s46, s65, s48
	global_load_lds_dwordx4 v[224:225], off
	v_lshl_add_u64 v[224:225], s[4:5], 0, v[138:139]
	s_mov_b32 m0, s46
	s_nop 0
	global_load_lds_dwordx4 v[224:225], off
	v_lshl_add_u64 v[224:225], s[4:5], 0, v[142:143]
	s_add_i32 m0, s46, 0x2000
	s_nop 0
	global_load_lds_dwordx4 v[224:225], off
	v_lshl_add_u64 v[224:225], v[228:229], 0, s[30:31]
	s_mov_b32 m0, s56
	s_nop 0
	global_load_lds_dwordx4 v[224:225], off
	v_lshl_add_u64 v[224:225], v[230:231], 0, s[30:31]
	s_mov_b32 m0, s57
	s_nop 0
	global_load_lds_dwordx4 v[224:225], off
	s_waitcnt vmcnt(8)
	s_waitcnt lgkmcnt(0)
	s_barrier
	s_setprio 0
	s_waitcnt lgkmcnt(0)
	v_mfma_f32_16x16x32_bf16 v[60:63], v[128:131], v[180:183], v[60:63]
	v_mfma_f32_16x16x32_bf16 v[56:59], v[156:159], v[180:183], v[56:59]
	v_mfma_f32_16x16x32_bf16 v[44:47], v[128:131], v[198:201], v[44:47]
	v_mfma_f32_16x16x32_bf16 v[40:43], v[156:159], v[198:201], v[40:43]
	v_mfma_f32_16x16x32_bf16 v[28:31], v[128:131], v[208:211], v[28:31]
	v_mfma_f32_16x16x32_bf16 v[24:27], v[156:159], v[208:211], v[24:27]
	v_mfma_f32_16x16x32_bf16 v[12:15], v[128:131], v[216:219], v[12:15]
	v_mfma_f32_16x16x32_bf16 v[8:11], v[156:159], v[216:219], v[8:11]
	v_mfma_f32_16x16x32_bf16 v[60:63], v[132:135], v[184:187], v[60:63]
	v_mfma_f32_16x16x32_bf16 v[56:59], v[160:163], v[184:187], v[56:59]
	v_mfma_f32_16x16x32_bf16 v[44:47], v[132:135], v[204:207], v[44:47]
	v_mfma_f32_16x16x32_bf16 v[40:43], v[160:163], v[204:207], v[40:43]
	v_mfma_f32_16x16x32_bf16 v[28:31], v[132:135], v[212:215], v[28:31]
	v_mfma_f32_16x16x32_bf16 v[24:27], v[160:163], v[212:215], v[24:27]
	v_mfma_f32_16x16x32_bf16 v[12:15], v[132:135], v[220:223], v[12:15]
	v_mfma_f32_16x16x32_bf16 v[8:11], v[160:163], v[220:223], v[8:11]
	v_mfma_f32_16x16x32_bf16 v[52:55], v[164:167], v[180:183], v[52:55]
	v_mfma_f32_16x16x32_bf16 v[48:51], v[172:175], v[180:183], v[48:51]
	v_mfma_f32_16x16x32_bf16 v[36:39], v[164:167], v[198:201], v[36:39]
	v_mfma_f32_16x16x32_bf16 v[32:35], v[172:175], v[198:201], v[32:35]
	v_mfma_f32_16x16x32_bf16 v[20:23], v[164:167], v[208:211], v[20:23]
	v_mfma_f32_16x16x32_bf16 v[16:19], v[172:175], v[208:211], v[16:19]
	v_mfma_f32_16x16x32_bf16 v[4:7], v[164:167], v[216:219], v[4:7]
	v_mfma_f32_16x16x32_bf16 v[0:3], v[172:175], v[216:219], v[0:3]
	v_mfma_f32_16x16x32_bf16 v[52:55], v[168:171], v[184:187], v[52:55]
	v_mfma_f32_16x16x32_bf16 v[48:51], v[176:179], v[184:187], v[48:51]
	v_mfma_f32_16x16x32_bf16 v[36:39], v[168:171], v[204:207], v[36:39]
	v_mfma_f32_16x16x32_bf16 v[32:35], v[176:179], v[204:207], v[32:35]
	v_mfma_f32_16x16x32_bf16 v[20:23], v[168:171], v[212:215], v[20:23]
	v_mfma_f32_16x16x32_bf16 v[16:19], v[176:179], v[212:215], v[16:19]
	v_mfma_f32_16x16x32_bf16 v[4:7], v[168:171], v[220:223], v[4:7]
	v_mfma_f32_16x16x32_bf16 v[0:3], v[176:179], v[220:223], v[0:3]
	s_setprio 1
	s_barrier
	s_add_i32 s63, s63, 2
	s_add_u32 s22, s22, 0x100
	s_addc_u32 s23, s23, 0
	s_add_u32 s41, s41, 0x100
	s_addc_u32 s62, s62, 0
	s_cmp_gt_u32 s63, 13
	s_cbranch_scc0 .LBB0_643
	s_and_b64 vcc, exec, s[34:35]
	s_cbranch_vccz .LBB0_646
	s_barrier
.LBB0_646:
	s_setprio 0
	v_lshl_add_u32 v170, s12, 8, v188
	v_or_b32_e32 v168, 16, v170
	v_or_b32_e32 v166, 32, v170
	v_or_b32_e32 v164, 48, v170
	v_ashrrev_i32_e32 v171, 31, v170
	v_ashrrev_i32_e32 v169, 31, v168
	v_ashrrev_i32_e32 v167, 31, v166
	v_ashrrev_i32_e32 v165, 31, v164
	v_lshlrev_b64 v[128:129], 6, v[170:171]
	v_lshlrev_b64 v[130:131], 6, v[168:169]
	v_lshlrev_b64 v[156:157], 6, v[166:167]
	v_lshlrev_b64 v[158:159], 6, v[164:165]
	v_add_u32_e32 v162, 0x80, v170
	v_add_u32_e32 v160, 0x90, v170
	v_lshl_add_u64 v[128:129], v[146:147], 0, v[128:129]
	v_lshl_add_u64 v[132:133], v[146:147], 0, v[130:131]
	v_lshl_add_u64 v[156:157], v[146:147], 0, v[156:157]
	v_lshl_add_u64 v[158:159], v[146:147], 0, v[158:159]
	v_ashrrev_i32_e32 v163, 31, v162
	v_ashrrev_i32_e32 v161, 31, v160
	global_load_dwordx4 v[128:131], v[128:129], off
	s_nop 0
	global_load_dwordx4 v[132:135], v[132:133], off
	s_nop 0
	global_load_dwordx4 v[172:175], v[156:157], off
	global_load_dwordx4 v[176:179], v[158:159], off
	v_lshlrev_b64 v[156:157], 6, v[162:163]
	v_lshlrev_b64 v[158:159], 6, v[160:161]
	v_lshl_add_u64 v[156:157], v[146:147], 0, v[156:157]
	v_lshl_add_u64 v[158:159], v[146:147], 0, v[158:159]
	global_load_dwordx4 v[180:183], v[156:157], off
	global_load_dwordx4 v[184:187], v[158:159], off
	v_add_u32_e32 v158, 0xa0, v170
	v_ashrrev_i32_e32 v159, 31, v158
	v_lshlrev_b64 v[156:157], 6, v[158:159]
	v_lshl_add_u64 v[156:157], v[146:147], 0, v[156:157]
	global_load_dwordx4 v[204:207], v[156:157], off
	v_add_u32_e32 v156, 0xb0, v170
	v_ashrrev_i32_e32 v157, 31, v156
	v_lshlrev_b64 v[198:199], 6, v[156:157]
	v_lshl_add_u64 v[198:199], v[146:147], 0, v[198:199]
	global_load_dwordx4 v[208:211], v[198:199], off
	v_and_b32_e32 v198, 64, v194
	v_xor_b32_e32 v144, 16, v194
	v_add_u32_e32 v198, 64, v198
	v_cmp_lt_i32_e32 vcc, v144, v198
	v_xor_b32_e32 v199, 32, v194
	s_ashr_i32 s4, s16, 2
	v_cndmask_b32_e32 v144, v194, v144, vcc
	v_cmp_lt_i32_e32 vcc, v199, v198
	v_lshlrev_b32_e32 v198, 2, v144
	s_cmp_lg_u32 s4, 1
	v_cndmask_b32_e32 v199, v194, v199, vcc
	v_lshlrev_b32_e32 v200, 2, v199
	s_cselect_b64 s[12:13], -1, 0
	s_and_b64 s[22:23], s[36:37], s[12:13]
	s_and_b64 s[46:47], s[22:23], s[6:7]
	s_waitcnt vmcnt(0)
	v_add_f32_e32 v128, v128, v129
	v_add_f32_e32 v129, v130, v131
	v_add_f32_e32 v128, v128, v129
	v_add_f32_e32 v129, v132, v133
	v_add_f32_e32 v130, v134, v135
	v_add_f32_e32 v131, v172, v173
	v_add_f32_e32 v132, v174, v175
	v_add_f32_e32 v133, v176, v177
	v_add_f32_e32 v134, v178, v179
	v_add_f32_e32 v135, v180, v181
	v_add_f32_e32 v144, v182, v183
	v_add_f32_e32 v172, v184, v185
	v_add_f32_e32 v173, v186, v187
	v_add_f32_e32 v174, v204, v205
	v_add_f32_e32 v175, v206, v207
	v_add_f32_e32 v129, v129, v130
	v_add_f32_e32 v130, v131, v132
	v_add_f32_e32 v176, v208, v209
	v_add_f32_e32 v177, v210, v211
	v_add_f32_e32 v131, v133, v134
	v_add_f32_e32 v132, v135, v144
	v_add_f32_e32 v133, v172, v173
	v_add_f32_e32 v134, v174, v175
	v_add_f32_e32 v135, v176, v177
	ds_bpermute_b32 v178, v198, v128
	ds_bpermute_b32 v172, v198, v129
	ds_bpermute_b32 v173, v198, v130
	ds_bpermute_b32 v174, v198, v131
	ds_bpermute_b32 v175, v198, v132
	ds_bpermute_b32 v176, v198, v133
	ds_bpermute_b32 v177, v198, v134
	ds_bpermute_b32 v179, v198, v135
	s_waitcnt lgkmcnt(7)
	v_add_f32_e32 v144, v128, v178
	s_waitcnt lgkmcnt(6)
	v_add_f32_e32 v213, v129, v172
	s_waitcnt lgkmcnt(5)
	v_add_f32_e32 v211, v130, v173
	s_waitcnt lgkmcnt(4)
	v_add_f32_e32 v209, v131, v174
	s_waitcnt lgkmcnt(3)
	v_add_f32_e32 v207, v132, v175
	s_waitcnt lgkmcnt(2)
	v_add_f32_e32 v205, v133, v176
	s_waitcnt lgkmcnt(1)
	v_add_f32_e32 v201, v134, v177
	s_waitcnt lgkmcnt(0)
	v_add_f32_e32 v199, v135, v179
	ds_bpermute_b32 v180, v200, v144
	ds_bpermute_b32 v214, v200, v213
	ds_bpermute_b32 v212, v200, v211
	ds_bpermute_b32 v210, v200, v209
	ds_bpermute_b32 v208, v200, v207
	ds_bpermute_b32 v206, v200, v205
	ds_bpermute_b32 v204, v200, v201
	ds_bpermute_b32 v200, v200, v199
	v_mov_b32_e32 v176, 0
	v_mov_b32_e32 v132, 1.0
	v_mov_b32_e32 v133, 1.0
	v_mov_b32_e32 v134, 1.0
	v_mov_b32_e32 v135, 1.0
	v_mov_b32_e32 v128, 1.0
	v_mov_b32_e32 v129, 1.0
	v_mov_b32_e32 v130, 1.0
	v_mov_b32_e32 v131, 1.0
	v_mov_b32_e32 v177, 0
	v_mov_b32_e32 v178, 0
	v_mov_b32_e32 v179, 0
	v_mov_b32_e32 v174, 0
	v_mov_b32_e32 v175, 0
	v_mov_b32_e32 v172, 0
	v_mov_b32_e32 v173, 0
	s_and_saveexec_b64 s[12:13], s[46:47]
	s_cbranch_execz .LBB0_648
	v_lshlrev_b32_e32 v128, 6, v170
	v_and_b32_e32 v128, 0x7f3c0, v128
	global_load_dwordx4 v[172:175], v128, s[28:29] offset:32
	global_load_dwordx4 v[182:185], v128, s[28:29] offset:48
	global_load_dwordx4 v[132:135], v128, s[28:29]
	s_nop 0
	global_load_dwordx4 v[128:131], v128, s[28:29] offset:16
	s_waitcnt vmcnt(3)
	v_xor_b32_e32 v179, 0x80000000, v175
	v_xor_b32_e32 v178, 0x80000000, v174
	v_xor_b32_e32 v177, 0x80000000, v173
	v_xor_b32_e32 v176, 0x80000000, v172
	s_waitcnt vmcnt(2)
	v_xor_b32_e32 v181, 0x80000000, v185
	v_xor_b32_e32 v186, 0x80000000, v184
	v_xor_b32_e32 v187, 0x80000000, v183
	v_xor_b32_e32 v215, 0x80000000, v182
	v_cndmask_b32_e64 v176, v172, v176, s[8:9]
	v_cndmask_b32_e64 v177, v173, v177, s[8:9]
	v_cndmask_b32_e64 v178, v174, v178, s[8:9]
	v_cndmask_b32_e64 v179, v175, v179, s[8:9]
	v_cndmask_b32_e64 v174, v182, v215, s[8:9]
	v_cndmask_b32_e64 v175, v183, v187, s[8:9]
	v_cndmask_b32_e64 v172, v184, v186, s[8:9]
	v_cndmask_b32_e64 v173, v185, v181, s[8:9]

.LBB0_966:
	ds_read_b128 v[128:131], v189
	ds_read_b128 v[132:135], v189 offset:1024
	ds_read_b128 v[136:139], v189 offset:2048
	ds_read_b128 v[140:143], v189 offset:3072
	ds_read_b128 v[144:147], v190
	ds_read_b128 v[148:151], v190 offset:1024
	ds_read_b128 v[168:171], v190 offset:2048
	ds_read_b128 v[172:175], v190 offset:3072
	s_add_u32 s4, s22, 0xfffc0080
	s_addc_u32 s5, s23, -1
	s_cmp_eq_u32 s58, 12
	s_cselect_b32 s43, s35, s5
	s_cselect_b32 s42, s41, s4
	s_cselect_b32 s5, s31, s57
	s_cselect_b32 s4, s55, s56
	v_lshl_add_u64 v[184:185], s[22:23], 0, v[160:161]
	s_add_i32 m0, s46, 0xc000
	ds_read_b128 v[176:179], v191
	ds_read_b128 v[180:183], v191 offset:1024
	ds_read_b128 v[192:195], v191 offset:2048
	ds_read_b128 v[198:201], v191 offset:3072
	ds_read_b128 v[204:207], v191 offset:4096
	ds_read_b128 v[208:211], v191 offset:5120
	ds_read_b128 v[212:215], v191 offset:6144
	ds_read_b128 v[216:219], v191 offset:7168
	global_load_lds_dwordx4 v[184:185], off
	v_lshl_add_u64 v[184:185], s[22:23], 0, v[162:163]
	s_add_i32 m0, s46, 0xe000
	s_nop 0
	global_load_lds_dwordx4 v[184:185], off
	s_waitcnt vmcnt(8)
	s_waitcnt lgkmcnt(0)
	s_barrier
	s_setprio 0
	s_waitcnt lgkmcnt(0)
	v_mfma_f32_16x16x32_bf16 v[124:127], v[128:131], v[176:179], v[124:127]
	v_mfma_f32_16x16x32_bf16 v[120:123], v[136:139], v[176:179], v[120:123]
	v_mfma_f32_16x16x32_bf16 v[108:111], v[128:131], v[192:195], v[108:111]
	v_mfma_f32_16x16x32_bf16 v[104:107], v[136:139], v[192:195], v[104:107]
	v_mfma_f32_16x16x32_bf16 v[92:95], v[128:131], v[204:207], v[92:95]
	v_mfma_f32_16x16x32_bf16 v[88:91], v[136:139], v[204:207], v[88:91]
	v_mfma_f32_16x16x32_bf16 v[76:79], v[128:131], v[212:215], v[76:79]
	v_mfma_f32_16x16x32_bf16 v[72:75], v[136:139], v[212:215], v[72:75]
	v_mfma_f32_16x16x32_bf16 v[124:127], v[132:135], v[180:183], v[124:127]
	v_mfma_f32_16x16x32_bf16 v[120:123], v[140:143], v[180:183], v[120:123]
	v_mfma_f32_16x16x32_bf16 v[108:111], v[132:135], v[198:201], v[108:111]
	v_mfma_f32_16x16x32_bf16 v[104:107], v[140:143], v[198:201], v[104:107]
	v_mfma_f32_16x16x32_bf16 v[92:95], v[132:135], v[208:211], v[92:95]
	v_mfma_f32_16x16x32_bf16 v[88:91], v[140:143], v[208:211], v[88:91]
	v_mfma_f32_16x16x32_bf16 v[76:79], v[132:135], v[216:219], v[76:79]
	v_mfma_f32_16x16x32_bf16 v[72:75], v[140:143], v[216:219], v[72:75]
	v_mfma_f32_16x16x32_bf16 v[116:119], v[144:147], v[176:179], v[116:119]
	v_mfma_f32_16x16x32_bf16 v[112:115], v[168:171], v[176:179], v[112:115]
	v_mfma_f32_16x16x32_bf16 v[100:103], v[144:147], v[192:195], v[100:103]
	v_mfma_f32_16x16x32_bf16 v[96:99], v[168:171], v[192:195], v[96:99]
	v_mfma_f32_16x16x32_bf16 v[84:87], v[144:147], v[204:207], v[84:87]
	v_mfma_f32_16x16x32_bf16 v[80:83], v[168:171], v[204:207], v[80:83]
	v_mfma_f32_16x16x32_bf16 v[68:71], v[144:147], v[212:215], v[68:71]
	v_mfma_f32_16x16x32_bf16 v[64:67], v[168:171], v[212:215], v[64:67]
	v_mfma_f32_16x16x32_bf16 v[116:119], v[148:151], v[180:183], v[116:119]
	v_mfma_f32_16x16x32_bf16 v[112:115], v[172:175], v[180:183], v[112:115]
	v_mfma_f32_16x16x32_bf16 v[100:103], v[148:151], v[198:201], v[100:103]
	v_mfma_f32_16x16x32_bf16 v[96:99], v[172:175], v[198:201], v[96:99]
	v_mfma_f32_16x16x32_bf16 v[84:87], v[148:151], v[208:211], v[84:87]
	v_mfma_f32_16x16x32_bf16 v[80:83], v[172:175], v[208:211], v[80:83]
	v_mfma_f32_16x16x32_bf16 v[68:71], v[148:151], v[216:219], v[68:71]
	v_mfma_f32_16x16x32_bf16 v[64:67], v[172:175], v[216:219], v[64:67]
	s_setprio 1
	s_barrier
	s_add_i32 s59, s52, s45
	v_lshl_add_u64 v[184:185], s[4:5], 0, v[154:155]
	s_mov_b32 m0, s59
	ds_read_b128 v[176:179], v191 offset:16384
	ds_read_b128 v[180:183], v191 offset:17408
	ds_read_b128 v[192:195], v191 offset:18432
	ds_read_b128 v[198:201], v191 offset:19456
	ds_read_b128 v[204:207], v191 offset:20480
	ds_read_b128 v[208:211], v191 offset:21504
	ds_read_b128 v[212:215], v191 offset:22528
	ds_read_b128 v[216:219], v191 offset:23552
	global_load_lds_dwordx4 v[184:185], off
	s_add_i32 m0, s59, 0x2000
	s_add_u32 s60, s4, 0x40000
	v_lshl_add_u64 v[220:221], s[4:5], 0, v[158:159]
	s_addc_u32 s61, s5, 0
	s_add_i32 s59, s53, s45
	global_load_lds_dwordx4 v[220:221], off
	v_lshl_add_u64 v[222:223], s[60:61], 0, v[154:155]
	s_mov_b32 m0, s59
	v_lshl_add_u64 v[224:225], s[42:43], 0, v[156:157]
	global_load_lds_dwordx4 v[222:223], off
	v_lshl_add_u64 v[222:223], s[60:61], 0, v[158:159]
	s_add_i32 m0, s59, 0x2000
	s_nop 0
	global_load_lds_dwordx4 v[222:223], off
	v_lshl_add_u64 v[222:223], s[42:43], 0, v[152:153]
	s_mov_b32 m0, s46
	s_nop 0
	global_load_lds_dwordx4 v[222:223], off
	s_mov_b32 m0, s33
	s_nop 0
	global_load_lds_dwordx4 v[224:225], off
	s_waitcnt vmcnt(8)
	s_waitcnt lgkmcnt(0)
	s_barrier
	s_setprio 0
	s_waitcnt lgkmcnt(0)
	v_mfma_f32_16x16x32_bf16 v[60:63], v[128:131], v[176:179], v[60:63]
	v_mfma_f32_16x16x32_bf16 v[56:59], v[136:139], v[176:179], v[56:59]
	v_mfma_f32_16x16x32_bf16 v[44:47], v[128:131], v[192:195], v[44:47]
	v_mfma_f32_16x16x32_bf16 v[40:43], v[136:139], v[192:195], v[40:43]
	v_mfma_f32_16x16x32_bf16 v[28:31], v[128:131], v[204:207], v[28:31]
	v_mfma_f32_16x16x32_bf16 v[24:27], v[136:139], v[204:207], v[24:27]
	v_mfma_f32_16x16x32_bf16 v[12:15], v[128:131], v[212:215], v[12:15]
	v_mfma_f32_16x16x32_bf16 v[8:11], v[136:139], v[212:215], v[8:11]
	v_mfma_f32_16x16x32_bf16 v[60:63], v[132:135], v[180:183], v[60:63]
	v_mfma_f32_16x16x32_bf16 v[56:59], v[140:143], v[180:183], v[56:59]
	v_mfma_f32_16x16x32_bf16 v[44:47], v[132:135], v[198:201], v[44:47]
	v_mfma_f32_16x16x32_bf16 v[40:43], v[140:143], v[198:201], v[40:43]
	v_mfma_f32_16x16x32_bf16 v[28:31], v[132:135], v[208:211], v[28:31]
	v_mfma_f32_16x16x32_bf16 v[24:27], v[140:143], v[208:211], v[24:27]
	v_mfma_f32_16x16x32_bf16 v[12:15], v[132:135], v[216:219], v[12:15]
	v_mfma_f32_16x16x32_bf16 v[8:11], v[140:143], v[216:219], v[8:11]
	v_mfma_f32_16x16x32_bf16 v[52:55], v[144:147], v[176:179], v[52:55]
	v_mfma_f32_16x16x32_bf16 v[48:51], v[168:171], v[176:179], v[48:51]
	v_mfma_f32_16x16x32_bf16 v[36:39], v[144:147], v[192:195], v[36:39]
	v_mfma_f32_16x16x32_bf16 v[32:35], v[168:171], v[192:195], v[32:35]
	v_mfma_f32_16x16x32_bf16 v[20:23], v[144:147], v[204:207], v[20:23]
	v_mfma_f32_16x16x32_bf16 v[16:19], v[168:171], v[204:207], v[16:19]
	v_mfma_f32_16x16x32_bf16 v[4:7], v[144:147], v[212:215], v[4:7]
	v_mfma_f32_16x16x32_bf16 v[0:3], v[168:171], v[212:215], v[0:3]
	v_mfma_f32_16x16x32_bf16 v[52:55], v[148:151], v[180:183], v[52:55]
	v_mfma_f32_16x16x32_bf16 v[48:51], v[172:175], v[180:183], v[48:51]
	v_mfma_f32_16x16x32_bf16 v[36:39], v[148:151], v[198:201], v[36:39]
	v_mfma_f32_16x16x32_bf16 v[32:35], v[172:175], v[198:201], v[32:35]
	v_mfma_f32_16x16x32_bf16 v[20:23], v[148:151], v[208:211], v[20:23]
	v_mfma_f32_16x16x32_bf16 v[16:19], v[172:175], v[208:211], v[16:19]
	v_mfma_f32_16x16x32_bf16 v[4:7], v[148:151], v[216:219], v[4:7]
	v_mfma_f32_16x16x32_bf16 v[0:3], v[172:175], v[216:219], v[0:3]
	s_setprio 1
	s_barrier
	s_add_i32 s59, 0, 0x18000
	s_add_i32 s60, 0, 0x1c000
	v_add_u32_e32 v140, s59, v187
	v_add_u32_e32 v172, s60, v187
	ds_read_b128 v[128:131], v140
	ds_read_b128 v[132:135], v140 offset:1024
	ds_read_b128 v[136:139], v140 offset:2048
	ds_read_b128 v[140:143], v140 offset:3072
	ds_read_b128 v[144:147], v172
	ds_read_b128 v[148:151], v172 offset:1024
	ds_read_b128 v[168:171], v172 offset:2048
	ds_read_b128 v[172:175], v172 offset:3072
	s_add_u32 s42, s42, 0x40000
	s_addc_u32 s43, s43, 0
	s_mov_b32 m0, s47
	v_lshl_add_u64 v[226:227], s[42:43], 0, v[152:153]
	ds_read_b128 v[176:179], v191 offset:32768
	ds_read_b128 v[180:183], v191 offset:33792
	ds_read_b128 v[192:195], v191 offset:34816
	ds_read_b128 v[198:201], v191 offset:35840
	ds_read_b128 v[204:207], v191 offset:36864
	ds_read_b128 v[208:211], v191 offset:37888
	ds_read_b128 v[212:215], v191 offset:38912
	ds_read_b128 v[216:219], v191 offset:39936
	global_load_lds_dwordx4 v[226:227], off
	v_lshl_add_u64 v[226:227], s[42:43], 0, v[156:157]
	s_mov_b32 m0, s48
	s_nop 0
	global_load_lds_dwordx4 v[226:227], off
	s_waitcnt vmcnt(8)
	s_waitcnt lgkmcnt(0)
	s_barrier
	s_setprio 0
	s_waitcnt lgkmcnt(0)
	v_mfma_f32_16x16x32_bf16 v[124:127], v[128:131], v[176:179], v[124:127]
	v_mfma_f32_16x16x32_bf16 v[120:123], v[136:139], v[176:179], v[120:123]
	v_mfma_f32_16x16x32_bf16 v[108:111], v[128:131], v[192:195], v[108:111]
	v_mfma_f32_16x16x32_bf16 v[104:107], v[136:139], v[192:195], v[104:107]
	v_mfma_f32_16x16x32_bf16 v[92:95], v[128:131], v[204:207], v[92:95]
	v_mfma_f32_16x16x32_bf16 v[88:91], v[136:139], v[204:207], v[88:91]
	v_mfma_f32_16x16x32_bf16 v[76:79], v[128:131], v[212:215], v[76:79]
	v_mfma_f32_16x16x32_bf16 v[72:75], v[136:139], v[212:215], v[72:75]
	v_mfma_f32_16x16x32_bf16 v[124:127], v[132:135], v[180:183], v[124:127]
	v_mfma_f32_16x16x32_bf16 v[120:123], v[140:143], v[180:183], v[120:123]
	v_mfma_f32_16x16x32_bf16 v[108:111], v[132:135], v[198:201], v[108:111]
	v_mfma_f32_16x16x32_bf16 v[104:107], v[140:143], v[198:201], v[104:107]
	v_mfma_f32_16x16x32_bf16 v[92:95], v[132:135], v[208:211], v[92:95]
	v_mfma_f32_16x16x32_bf16 v[88:91], v[140:143], v[208:211], v[88:91]
	v_mfma_f32_16x16x32_bf16 v[76:79], v[132:135], v[216:219], v[76:79]
	v_mfma_f32_16x16x32_bf16 v[72:75], v[140:143], v[216:219], v[72:75]
	v_mfma_f32_16x16x32_bf16 v[116:119], v[144:147], v[176:179], v[116:119]
	v_mfma_f32_16x16x32_bf16 v[112:115], v[168:171], v[176:179], v[112:115]
	v_mfma_f32_16x16x32_bf16 v[100:103], v[144:147], v[192:195], v[100:103]
	v_mfma_f32_16x16x32_bf16 v[96:99], v[168:171], v[192:195], v[96:99]
	v_mfma_f32_16x16x32_bf16 v[84:87], v[144:147], v[204:207], v[84:87]
	v_mfma_f32_16x16x32_bf16 v[80:83], v[168:171], v[204:207], v[80:83]
	v_mfma_f32_16x16x32_bf16 v[68:71], v[144:147], v[212:215], v[68:71]
	v_mfma_f32_16x16x32_bf16 v[64:67], v[168:171], v[212:215], v[64:67]
	v_mfma_f32_16x16x32_bf16 v[116:119], v[148:151], v[180:183], v[116:119]
	v_mfma_f32_16x16x32_bf16 v[112:115], v[172:175], v[180:183], v[112:115]
	v_mfma_f32_16x16x32_bf16 v[100:103], v[148:151], v[198:201], v[100:103]
	v_mfma_f32_16x16x32_bf16 v[96:99], v[172:175], v[198:201], v[96:99]
	v_mfma_f32_16x16x32_bf16 v[84:87], v[148:151], v[208:211], v[84:87]
	v_mfma_f32_16x16x32_bf16 v[80:83], v[172:175], v[208:211], v[80:83]
	v_mfma_f32_16x16x32_bf16 v[68:71], v[148:151], v[216:219], v[68:71]
	v_mfma_f32_16x16x32_bf16 v[64:67], v[172:175], v[216:219], v[64:67]
	s_setprio 1
	s_barrier
	s_add_i32 s42, s59, s45
	v_lshl_add_u64 v[184:185], v[184:185], 0, s[26:27]
	s_mov_b32 m0, s42
	ds_read_b128 v[176:179], v191 offset:49152
	ds_read_b128 v[180:183], v191 offset:50176
	ds_read_b128 v[192:195], v191 offset:51200
	ds_read_b128 v[198:201], v191 offset:52224
	ds_read_b128 v[204:207], v191 offset:53248
	ds_read_b128 v[208:211], v191 offset:54272
	ds_read_b128 v[212:215], v191 offset:55296
	ds_read_b128 v[216:219], v191 offset:56320
	global_load_lds_dwordx4 v[184:185], off
	s_add_i32 m0, s42, 0x2000
	s_add_u32 s4, s4, 0x40080
	v_lshl_add_u64 v[184:185], v[220:221], 0, s[26:27]
	s_addc_u32 s5, s5, 0
	s_add_i32 s42, s60, s45
	global_load_lds_dwordx4 v[184:185], off
	v_lshl_add_u64 v[184:185], s[4:5], 0, v[154:155]
	s_mov_b32 m0, s42
	s_nop 0
	global_load_lds_dwordx4 v[184:185], off
	v_lshl_add_u64 v[184:185], s[4:5], 0, v[158:159]
	s_add_i32 m0, s42, 0x2000
	s_nop 0
	global_load_lds_dwordx4 v[184:185], off
	v_lshl_add_u64 v[184:185], v[222:223], 0, s[26:27]
	s_mov_b32 m0, s50
	s_nop 0
	global_load_lds_dwordx4 v[184:185], off
	v_lshl_add_u64 v[184:185], v[224:225], 0, s[26:27]
	s_mov_b32 m0, s51
	s_nop 0
	global_load_lds_dwordx4 v[184:185], off
	s_waitcnt vmcnt(8)
	s_waitcnt lgkmcnt(0)
	s_barrier
	s_setprio 0
	s_waitcnt lgkmcnt(0)
	v_mfma_f32_16x16x32_bf16 v[60:63], v[128:131], v[176:179], v[60:63]
	v_mfma_f32_16x16x32_bf16 v[56:59], v[136:139], v[176:179], v[56:59]
	v_mfma_f32_16x16x32_bf16 v[44:47], v[128:131], v[192:195], v[44:47]
	v_mfma_f32_16x16x32_bf16 v[40:43], v[136:139], v[192:195], v[40:43]
	v_mfma_f32_16x16x32_bf16 v[28:31], v[128:131], v[204:207], v[28:31]
	v_mfma_f32_16x16x32_bf16 v[24:27], v[136:139], v[204:207], v[24:27]
	v_mfma_f32_16x16x32_bf16 v[12:15], v[128:131], v[212:215], v[12:15]
	v_mfma_f32_16x16x32_bf16 v[8:11], v[136:139], v[212:215], v[8:11]
	v_mfma_f32_16x16x32_bf16 v[60:63], v[132:135], v[180:183], v[60:63]
	v_mfma_f32_16x16x32_bf16 v[56:59], v[140:143], v[180:183], v[56:59]
	v_mfma_f32_16x16x32_bf16 v[44:47], v[132:135], v[198:201], v[44:47]
	v_mfma_f32_16x16x32_bf16 v[40:43], v[140:143], v[198:201], v[40:43]
	v_mfma_f32_16x16x32_bf16 v[28:31], v[132:135], v[208:211], v[28:31]
	v_mfma_f32_16x16x32_bf16 v[24:27], v[140:143], v[208:211], v[24:27]
	v_mfma_f32_16x16x32_bf16 v[12:15], v[132:135], v[216:219], v[12:15]
	v_mfma_f32_16x16x32_bf16 v[8:11], v[140:143], v[216:219], v[8:11]
	v_mfma_f32_16x16x32_bf16 v[52:55], v[144:147], v[176:179], v[52:55]
	v_mfma_f32_16x16x32_bf16 v[48:51], v[168:171], v[176:179], v[48:51]
	v_mfma_f32_16x16x32_bf16 v[36:39], v[144:147], v[192:195], v[36:39]
	v_mfma_f32_16x16x32_bf16 v[32:35], v[168:171], v[192:195], v[32:35]
	v_mfma_f32_16x16x32_bf16 v[20:23], v[144:147], v[204:207], v[20:23]
	v_mfma_f32_16x16x32_bf16 v[16:19], v[168:171], v[204:207], v[16:19]
	v_mfma_f32_16x16x32_bf16 v[4:7], v[144:147], v[212:215], v[4:7]
	v_mfma_f32_16x16x32_bf16 v[0:3], v[168:171], v[212:215], v[0:3]
	v_mfma_f32_16x16x32_bf16 v[52:55], v[148:151], v[180:183], v[52:55]
	v_mfma_f32_16x16x32_bf16 v[48:51], v[172:175], v[180:183], v[48:51]
	v_mfma_f32_16x16x32_bf16 v[36:39], v[148:151], v[198:201], v[36:39]
	v_mfma_f32_16x16x32_bf16 v[32:35], v[172:175], v[198:201], v[32:35]
	v_mfma_f32_16x16x32_bf16 v[20:23], v[148:151], v[208:211], v[20:23]
	v_mfma_f32_16x16x32_bf16 v[16:19], v[172:175], v[208:211], v[16:19]
	v_mfma_f32_16x16x32_bf16 v[4:7], v[148:151], v[216:219], v[4:7]
	v_mfma_f32_16x16x32_bf16 v[0:3], v[172:175], v[216:219], v[0:3]
	s_setprio 1
	s_barrier
	s_add_i32 s58, s58, 2
	s_add_u32 s22, s22, 0x100
	s_addc_u32 s23, s23, 0
	s_add_u32 s56, s56, 0x100
	s_addc_u32 s57, s57, 0
	s_cmp_gt_u32 s58, 13
	s_cbranch_scc0 .LBB0_966
	s_and_b64 vcc, exec, s[28:29]
	s_cbranch_vccz .LBB0_969
	s_barrier
.LBB0_969:
	s_setprio 0
	v_lshl_or_b32 v168, s10, 8, v188
	v_lshl_add_u32 v172, s40, 8, v186
	v_ashrrev_i32_e32 v169, 31, v168
	v_lshlrev_b64 v[204:205], 1, v[168:169]
	v_ashrrev_i32_e32 v173, 31, v172
	v_lshl_add_u64 v[170:171], s[16:17], 0, v[204:205]
	v_lshlrev_b64 v[206:207], 11, v[172:173]
	v_lshl_add_u64 v[128:129], v[170:171], 0, v[206:207]
	global_load_dwordx4 v[192:195], v[128:129], off
	global_load_dwordx4 v[198:201], v[128:129], off offset:256
	v_or_b32_e32 v182, 16, v172
	v_or_b32_e32 v178, 32, v172
	v_or_b32_e32 v174, 48, v172
	v_ashrrev_i32_e32 v183, 31, v182
	v_ashrrev_i32_e32 v179, 31, v178
	v_ashrrev_i32_e32 v175, 31, v174
	v_lshlrev_b64 v[184:185], 11, v[182:183]
	v_lshlrev_b64 v[180:181], 11, v[178:179]
	v_lshlrev_b64 v[176:177], 11, v[174:175]
	v_lshl_add_u64 v[128:129], v[170:171], 0, v[184:185]
	v_lshl_add_u64 v[130:131], v[170:171], 0, v[180:181]
	v_lshl_add_u64 v[208:209], v[170:171], 0, v[176:177]
	global_load_dwordx4 v[148:151], v[128:129], off
	global_load_dwordx4 v[144:147], v[128:129], off offset:256
	global_load_dwordx4 v[140:143], v[130:131], off
	global_load_dwordx4 v[136:139], v[130:131], off offset:256
	global_load_dwordx4 v[132:135], v[208:209], off
	s_nop 0
	global_load_dwordx4 v[128:131], v[208:209], off offset:256
	s_lshl_b32 s40, s10, 2
	s_ashr_i32 s41, s40, 31
	s_waitcnt vmcnt(0)
	v_lshlrev_b32_e32 v208, 16, v192
	v_and_b32_e32 v209, 0xffff0000, v192
	v_lshlrev_b32_e32 v192, 16, v193
	v_and_b32_e32 v193, 0xffff0000, v193
	v_lshlrev_b32_e32 v210, 16, v194
	v_and_b32_e32 v211, 0xffff0000, v194
	v_lshlrev_b32_e32 v194, 16, v195
	v_and_b32_e32 v195, 0xffff0000, v195
	v_lshlrev_b32_e32 v212, 16, v198
	v_and_b32_e32 v213, 0xffff0000, v198
	v_lshlrev_b32_e32 v198, 16, v199
	v_and_b32_e32 v199, 0xffff0000, v199
	v_lshlrev_b32_e32 v214, 16, v200
	v_and_b32_e32 v215, 0xffff0000, v200
	v_lshlrev_b32_e32 v200, 16, v201
	v_and_b32_e32 v201, 0xffff0000, v201
	v_pk_add_f32 v[126:127], v[126:127], v[192:193]
	v_pk_add_f32 v[124:125], v[124:125], v[208:209]
	v_pk_add_f32 v[122:123], v[122:123], v[194:195]
	v_pk_add_f32 v[120:121], v[120:121], v[210:211]
	v_pk_add_f32 v[118:119], v[118:119], v[198:199]
	v_pk_add_f32 v[116:117], v[116:117], v[212:213]
	v_pk_add_f32 v[192:193], v[114:115], v[200:201]
	v_pk_add_f32 v[194:195], v[112:113], v[214:215]
	v_mul_f32_e32 v198, v125, v125
	v_mul_f32_e32 v199, v127, v127
	v_mul_f32_e32 v200, v121, v121
	v_mul_f32_e32 v201, v123, v123
	v_cvt_pk_bf16_f32 v112, v124, v125
	v_cvt_pk_bf16_f32 v113, v126, v127
	v_cvt_pk_bf16_f32 v114, v120, v121
	v_cvt_pk_bf16_f32 v115, v122, v123
	v_mul_f32_e32 v121, v117, v117
	v_mul_f32_e32 v123, v119, v119
	v_mul_f32_e32 v125, v195, v195
	v_mul_f32_e32 v127, v193, v193
	v_fmac_f32_e32 v198, v124, v124
	v_fmac_f32_e32 v199, v126, v126
	v_fmac_f32_e32 v200, v120, v120
	v_fmac_f32_e32 v201, v122, v122
	v_fmac_f32_e32 v121, v116, v116
	v_fmac_f32_e32 v123, v118, v118
	v_fmac_f32_e32 v125, v194, v194
	v_fmac_f32_e32 v127, v192, v192
	v_add_f32_e32 v120, v198, v199
	v_add_f32_e32 v122, v200, v201
	v_add_f32_e32 v121, v121, v123
	v_add_f32_e32 v123, v125, v127
	v_add_f32_e32 v120, v120, v122
	v_add_f32_e32 v121, v121, v123
	v_add_f32_e32 v122, v120, v121
	ds_bpermute_b32 v123, v196, v122
	v_lshl_add_u64 v[120:121], s[16:17], 0, v[206:207]
	v_lshl_add_u64 v[120:121], v[120:121], 0, v[204:205]
	global_store_dwordx4 v[120:121], v[112:115], off
	s_waitcnt lgkmcnt(0)
	s_nop 0
	v_add_f32_e32 v112, v122, v123
	ds_bpermute_b32 v113, v197, v112
	v_cvt_pk_bf16_f32 v114, v116, v117
	v_cvt_pk_bf16_f32 v115, v118, v119
	v_cvt_pk_bf16_f32 v116, v194, v195
	v_cvt_pk_bf16_f32 v117, v192, v193
	global_store_dwordx4 v[120:121], v[114:117], off offset:256
	s_and_saveexec_b64 s[4:5], s[6:7]
	s_cbranch_execz .LBB0_971
	v_lshlrev_b64 v[114:115], 6, v[172:173]
	v_lshl_add_u64 v[114:115], s[24:25], 0, v[114:115]
	v_lshl_add_u64 v[114:115], s[40:41], 2, v[114:115]
	s_lshl_b32 s10, s49, 2
	v_lshl_add_u64 v[114:115], v[114:115], 0, s[10:11]
	s_waitcnt lgkmcnt(0)
	v_add_f32_e32 v112, v112, v113
	global_store_dword v[114:115], v112, off

.LBB0_1048:
	ds_read_b128 v[146:149], v169
	ds_read_b128 v[150:153], v169 offset:1024
	ds_read_b128 v[154:157], v169 offset:2048
	ds_read_b128 v[160:163], v169 offset:3072
	ds_read_b128 v[178:181], v171
	ds_read_b128 v[182:185], v171 offset:1024
	ds_read_b128 v[186:189], v171 offset:2048
	ds_read_b128 v[190:193], v171 offset:3072
	s_add_u32 s4, s10, 0xfffc0080
	s_addc_u32 s5, s11, -1
	s_cmp_eq_u32 s55, 12
	s_cselect_b32 s13, s9, s5
	s_cselect_b32 s12, s31, s4
	s_cselect_b32 s5, s29, s54
	s_cselect_b32 s4, s52, s53
	v_lshl_add_u64 v[194:195], s[10:11], 0, v[138:139]
	s_add_i32 m0, s41, 0xc000
	ds_read_b128 v[198:201], v173
	ds_read_b128 v[204:207], v173 offset:1024
	ds_read_b128 v[208:211], v173 offset:2048
	ds_read_b128 v[212:215], v173 offset:3072
	ds_read_b128 v[216:219], v173 offset:4096
	ds_read_b128 v[220:223], v173 offset:5120
	ds_read_b128 v[224:227], v173 offset:6144
	ds_read_b128 v[228:231], v173 offset:7168
	global_load_lds_dwordx4 v[194:195], off
	v_lshl_add_u64 v[194:195], s[10:11], 0, v[140:141]
	s_add_i32 m0, s41, 0xe000
	s_nop 0
	global_load_lds_dwordx4 v[194:195], off
	s_waitcnt vmcnt(8)
	s_waitcnt lgkmcnt(0)
	s_barrier
	s_setprio 0
	s_waitcnt lgkmcnt(0)
	v_mfma_f32_16x16x32_bf16 v[124:127], v[146:149], v[198:201], v[124:127]
	v_mfma_f32_16x16x32_bf16 v[116:119], v[154:157], v[198:201], v[116:119]
	v_mfma_f32_16x16x32_bf16 v[108:111], v[146:149], v[208:211], v[108:111]
	v_mfma_f32_16x16x32_bf16 v[100:103], v[154:157], v[208:211], v[100:103]
	v_mfma_f32_16x16x32_bf16 v[92:95], v[146:149], v[216:219], v[92:95]
	v_mfma_f32_16x16x32_bf16 v[84:87], v[154:157], v[216:219], v[84:87]
	v_mfma_f32_16x16x32_bf16 v[76:79], v[146:149], v[224:227], v[76:79]
	v_mfma_f32_16x16x32_bf16 v[68:71], v[154:157], v[224:227], v[68:71]
	v_mfma_f32_16x16x32_bf16 v[124:127], v[150:153], v[204:207], v[124:127]
	v_mfma_f32_16x16x32_bf16 v[116:119], v[160:163], v[204:207], v[116:119]
	v_mfma_f32_16x16x32_bf16 v[108:111], v[150:153], v[212:215], v[108:111]
	v_mfma_f32_16x16x32_bf16 v[100:103], v[160:163], v[212:215], v[100:103]
	v_mfma_f32_16x16x32_bf16 v[92:95], v[150:153], v[220:223], v[92:95]
	v_mfma_f32_16x16x32_bf16 v[84:87], v[160:163], v[220:223], v[84:87]
	v_mfma_f32_16x16x32_bf16 v[76:79], v[150:153], v[228:231], v[76:79]
	v_mfma_f32_16x16x32_bf16 v[68:71], v[160:163], v[228:231], v[68:71]
	v_mfma_f32_16x16x32_bf16 v[120:123], v[178:181], v[198:201], v[120:123]
	v_mfma_f32_16x16x32_bf16 v[112:115], v[186:189], v[198:201], v[112:115]
	v_mfma_f32_16x16x32_bf16 v[104:107], v[178:181], v[208:211], v[104:107]
	v_mfma_f32_16x16x32_bf16 v[96:99], v[186:189], v[208:211], v[96:99]
	v_mfma_f32_16x16x32_bf16 v[88:91], v[178:181], v[216:219], v[88:91]
	v_mfma_f32_16x16x32_bf16 v[80:83], v[186:189], v[216:219], v[80:83]
	v_mfma_f32_16x16x32_bf16 v[72:75], v[178:181], v[224:227], v[72:75]
	v_mfma_f32_16x16x32_bf16 v[64:67], v[186:189], v[224:227], v[64:67]
	v_mfma_f32_16x16x32_bf16 v[120:123], v[182:185], v[204:207], v[120:123]
	v_mfma_f32_16x16x32_bf16 v[112:115], v[190:193], v[204:207], v[112:115]
	v_mfma_f32_16x16x32_bf16 v[104:107], v[182:185], v[212:215], v[104:107]
	v_mfma_f32_16x16x32_bf16 v[96:99], v[190:193], v[212:215], v[96:99]
	v_mfma_f32_16x16x32_bf16 v[88:91], v[182:185], v[220:223], v[88:91]
	v_mfma_f32_16x16x32_bf16 v[80:83], v[190:193], v[220:223], v[80:83]
	v_mfma_f32_16x16x32_bf16 v[72:75], v[182:185], v[228:231], v[72:75]
	v_mfma_f32_16x16x32_bf16 v[64:67], v[190:193], v[228:231], v[64:67]
	s_setprio 1
	s_barrier
	s_add_i32 s56, s48, s39
	v_lshl_add_u64 v[194:195], s[4:5], 0, v[132:133]
	s_mov_b32 m0, s56
	ds_read_b128 v[198:201], v173 offset:16384
	ds_read_b128 v[204:207], v173 offset:17408
	ds_read_b128 v[208:211], v173 offset:18432
	ds_read_b128 v[212:215], v173 offset:19456
	ds_read_b128 v[216:219], v173 offset:20480
	ds_read_b128 v[220:223], v173 offset:21504
	ds_read_b128 v[224:227], v173 offset:22528
	ds_read_b128 v[228:231], v173 offset:23552
	global_load_lds_dwordx4 v[194:195], off
	s_add_i32 m0, s56, 0x2000
	s_add_u32 s56, s4, 0x40000
	v_lshl_add_u64 v[232:233], s[4:5], 0, v[128:129]
	s_addc_u32 s57, s5, 0
	s_add_i32 s58, s49, s39
	global_load_lds_dwordx4 v[232:233], off
	v_lshl_add_u64 v[234:235], s[56:57], 0, v[132:133]
	s_mov_b32 m0, s58
	v_lshl_add_u64 v[236:237], s[12:13], 0, v[130:131]
	global_load_lds_dwordx4 v[234:235], off
	v_lshl_add_u64 v[234:235], s[56:57], 0, v[128:129]
	s_add_i32 m0, s58, 0x2000
	s_nop 0
	global_load_lds_dwordx4 v[234:235], off
	v_lshl_add_u64 v[234:235], s[12:13], 0, v[134:135]
	s_mov_b32 m0, s41
	s_nop 0
	global_load_lds_dwordx4 v[234:235], off
	s_mov_b32 m0, s42
	s_nop 0
	global_load_lds_dwordx4 v[236:237], off
	s_waitcnt vmcnt(8)
	s_waitcnt lgkmcnt(0)
	s_barrier
	s_setprio 0
	s_waitcnt lgkmcnt(0)
	v_mfma_f32_16x16x32_bf16 v[60:63], v[146:149], v[198:201], v[60:63]
	v_mfma_f32_16x16x32_bf16 v[52:55], v[154:157], v[198:201], v[52:55]
	v_mfma_f32_16x16x32_bf16 v[44:47], v[146:149], v[208:211], v[44:47]
	v_mfma_f32_16x16x32_bf16 v[36:39], v[154:157], v[208:211], v[36:39]
	v_mfma_f32_16x16x32_bf16 v[28:31], v[146:149], v[216:219], v[28:31]
	v_mfma_f32_16x16x32_bf16 v[20:23], v[154:157], v[216:219], v[20:23]
	v_mfma_f32_16x16x32_bf16 v[12:15], v[146:149], v[224:227], v[12:15]
	v_mfma_f32_16x16x32_bf16 v[4:7], v[154:157], v[224:227], v[4:7]
	v_mfma_f32_16x16x32_bf16 v[60:63], v[150:153], v[204:207], v[60:63]
	v_mfma_f32_16x16x32_bf16 v[52:55], v[160:163], v[204:207], v[52:55]
	v_mfma_f32_16x16x32_bf16 v[44:47], v[150:153], v[212:215], v[44:47]
	v_mfma_f32_16x16x32_bf16 v[36:39], v[160:163], v[212:215], v[36:39]
	v_mfma_f32_16x16x32_bf16 v[28:31], v[150:153], v[220:223], v[28:31]
	v_mfma_f32_16x16x32_bf16 v[20:23], v[160:163], v[220:223], v[20:23]
	v_mfma_f32_16x16x32_bf16 v[12:15], v[150:153], v[228:231], v[12:15]
	v_mfma_f32_16x16x32_bf16 v[4:7], v[160:163], v[228:231], v[4:7]
	v_mfma_f32_16x16x32_bf16 v[56:59], v[178:181], v[198:201], v[56:59]
	v_mfma_f32_16x16x32_bf16 v[48:51], v[186:189], v[198:201], v[48:51]
	v_mfma_f32_16x16x32_bf16 v[40:43], v[178:181], v[208:211], v[40:43]
	v_mfma_f32_16x16x32_bf16 v[32:35], v[186:189], v[208:211], v[32:35]
	v_mfma_f32_16x16x32_bf16 v[24:27], v[178:181], v[216:219], v[24:27]
	v_mfma_f32_16x16x32_bf16 v[16:19], v[186:189], v[216:219], v[16:19]
	v_mfma_f32_16x16x32_bf16 v[8:11], v[178:181], v[224:227], v[8:11]
	v_mfma_f32_16x16x32_bf16 v[0:3], v[186:189], v[224:227], v[0:3]
	v_mfma_f32_16x16x32_bf16 v[56:59], v[182:185], v[204:207], v[56:59]
	v_mfma_f32_16x16x32_bf16 v[48:51], v[190:193], v[204:207], v[48:51]
	v_mfma_f32_16x16x32_bf16 v[40:43], v[182:185], v[212:215], v[40:43]
	v_mfma_f32_16x16x32_bf16 v[32:35], v[190:193], v[212:215], v[32:35]
	v_mfma_f32_16x16x32_bf16 v[24:27], v[182:185], v[220:223], v[24:27]
	v_mfma_f32_16x16x32_bf16 v[16:19], v[190:193], v[220:223], v[16:19]
	v_mfma_f32_16x16x32_bf16 v[8:11], v[182:185], v[228:231], v[8:11]
	v_mfma_f32_16x16x32_bf16 v[0:3], v[190:193], v[228:231], v[0:3]
	s_setprio 1
	s_barrier
	s_add_i32 s56, 0, 0x18000
	v_add_u32_e32 v158, s56, v165
	s_add_i32 s57, 0, 0x1c000
	ds_read_b128 v[146:149], v158
	ds_read_b128 v[150:153], v158 offset:1024
	ds_read_b128 v[154:157], v158 offset:2048
	ds_read_b128 v[160:163], v158 offset:3072
	v_add_u32_e32 v158, s57, v165
	ds_read_b128 v[178:181], v158
	ds_read_b128 v[182:185], v158 offset:1024
	ds_read_b128 v[186:189], v158 offset:2048
	ds_read_b128 v[190:193], v158 offset:3072
	s_add_u32 s12, s12, 0x40000
	s_addc_u32 s13, s13, 0
	s_mov_b32 m0, s43
	v_lshl_add_u64 v[238:239], s[12:13], 0, v[134:135]
	ds_read_b128 v[198:201], v173 offset:32768
	ds_read_b128 v[204:207], v173 offset:33792
	ds_read_b128 v[208:211], v173 offset:34816
	ds_read_b128 v[212:215], v173 offset:35840
	ds_read_b128 v[216:219], v173 offset:36864
	ds_read_b128 v[220:223], v173 offset:37888
	ds_read_b128 v[224:227], v173 offset:38912
	ds_read_b128 v[228:231], v173 offset:39936
	global_load_lds_dwordx4 v[238:239], off
	v_lshl_add_u64 v[238:239], s[12:13], 0, v[130:131]
	s_mov_b32 m0, s44
	s_nop 0
	global_load_lds_dwordx4 v[238:239], off
	s_waitcnt vmcnt(8)
	s_waitcnt lgkmcnt(0)
	s_barrier
	s_setprio 0
	s_waitcnt lgkmcnt(0)
	v_mfma_f32_16x16x32_bf16 v[124:127], v[146:149], v[198:201], v[124:127]
	v_mfma_f32_16x16x32_bf16 v[116:119], v[154:157], v[198:201], v[116:119]
	v_mfma_f32_16x16x32_bf16 v[108:111], v[146:149], v[208:211], v[108:111]
	v_mfma_f32_16x16x32_bf16 v[100:103], v[154:157], v[208:211], v[100:103]
	v_mfma_f32_16x16x32_bf16 v[92:95], v[146:149], v[216:219], v[92:95]
	v_mfma_f32_16x16x32_bf16 v[84:87], v[154:157], v[216:219], v[84:87]
	v_mfma_f32_16x16x32_bf16 v[76:79], v[146:149], v[224:227], v[76:79]
	v_mfma_f32_16x16x32_bf16 v[68:71], v[154:157], v[224:227], v[68:71]
	v_mfma_f32_16x16x32_bf16 v[124:127], v[150:153], v[204:207], v[124:127]
	v_mfma_f32_16x16x32_bf16 v[116:119], v[160:163], v[204:207], v[116:119]
	v_mfma_f32_16x16x32_bf16 v[108:111], v[150:153], v[212:215], v[108:111]
	v_mfma_f32_16x16x32_bf16 v[100:103], v[160:163], v[212:215], v[100:103]
	v_mfma_f32_16x16x32_bf16 v[92:95], v[150:153], v[220:223], v[92:95]
	v_mfma_f32_16x16x32_bf16 v[84:87], v[160:163], v[220:223], v[84:87]
	v_mfma_f32_16x16x32_bf16 v[76:79], v[150:153], v[228:231], v[76:79]
	v_mfma_f32_16x16x32_bf16 v[68:71], v[160:163], v[228:231], v[68:71]
	v_mfma_f32_16x16x32_bf16 v[120:123], v[178:181], v[198:201], v[120:123]
	v_mfma_f32_16x16x32_bf16 v[112:115], v[186:189], v[198:201], v[112:115]
	v_mfma_f32_16x16x32_bf16 v[104:107], v[178:181], v[208:211], v[104:107]
	v_mfma_f32_16x16x32_bf16 v[96:99], v[186:189], v[208:211], v[96:99]
	v_mfma_f32_16x16x32_bf16 v[88:91], v[178:181], v[216:219], v[88:91]
	v_mfma_f32_16x16x32_bf16 v[80:83], v[186:189], v[216:219], v[80:83]
	v_mfma_f32_16x16x32_bf16 v[72:75], v[178:181], v[224:227], v[72:75]
	v_mfma_f32_16x16x32_bf16 v[64:67], v[186:189], v[224:227], v[64:67]
	v_mfma_f32_16x16x32_bf16 v[120:123], v[182:185], v[204:207], v[120:123]
	v_mfma_f32_16x16x32_bf16 v[112:115], v[190:193], v[204:207], v[112:115]
	v_mfma_f32_16x16x32_bf16 v[104:107], v[182:185], v[212:215], v[104:107]
	v_mfma_f32_16x16x32_bf16 v[96:99], v[190:193], v[212:215], v[96:99]
	v_mfma_f32_16x16x32_bf16 v[88:91], v[182:185], v[220:223], v[88:91]
	v_mfma_f32_16x16x32_bf16 v[80:83], v[190:193], v[220:223], v[80:83]
	v_mfma_f32_16x16x32_bf16 v[72:75], v[182:185], v[228:231], v[72:75]
	v_mfma_f32_16x16x32_bf16 v[64:67], v[190:193], v[228:231], v[64:67]
	s_setprio 1
	s_barrier
	s_add_i32 s12, s56, s39
	v_lshl_add_u64 v[194:195], v[194:195], 0, s[24:25]
	s_mov_b32 m0, s12
	ds_read_b128 v[198:201], v173 offset:49152
	ds_read_b128 v[204:207], v173 offset:50176
	ds_read_b128 v[208:211], v173 offset:51200
	ds_read_b128 v[212:215], v173 offset:52224
	ds_read_b128 v[216:219], v173 offset:53248
	ds_read_b128 v[220:223], v173 offset:54272
	ds_read_b128 v[224:227], v173 offset:55296
	ds_read_b128 v[228:231], v173 offset:56320
	global_load_lds_dwordx4 v[194:195], off
	s_add_i32 m0, s12, 0x2000
	s_add_u32 s4, s4, 0x40080
	v_lshl_add_u64 v[194:195], v[232:233], 0, s[24:25]
	s_addc_u32 s5, s5, 0
	s_add_i32 s12, s57, s39
	global_load_lds_dwordx4 v[194:195], off
	v_lshl_add_u64 v[194:195], s[4:5], 0, v[132:133]
	s_mov_b32 m0, s12
	s_nop 0
	global_load_lds_dwordx4 v[194:195], off
	v_lshl_add_u64 v[194:195], s[4:5], 0, v[128:129]
	s_add_i32 m0, s12, 0x2000
	s_nop 0
	global_load_lds_dwordx4 v[194:195], off
	v_lshl_add_u64 v[194:195], v[234:235], 0, s[24:25]
	s_mov_b32 m0, s46
	s_nop 0
	global_load_lds_dwordx4 v[194:195], off
	v_lshl_add_u64 v[194:195], v[236:237], 0, s[24:25]
	s_mov_b32 m0, s47
	s_nop 0
	global_load_lds_dwordx4 v[194:195], off
	s_waitcnt vmcnt(8)
	s_waitcnt lgkmcnt(0)
	s_barrier
	s_setprio 0
	s_waitcnt lgkmcnt(0)
	v_mfma_f32_16x16x32_bf16 v[60:63], v[146:149], v[198:201], v[60:63]
	v_mfma_f32_16x16x32_bf16 v[52:55], v[154:157], v[198:201], v[52:55]
	v_mfma_f32_16x16x32_bf16 v[44:47], v[146:149], v[208:211], v[44:47]
	v_mfma_f32_16x16x32_bf16 v[36:39], v[154:157], v[208:211], v[36:39]
	v_mfma_f32_16x16x32_bf16 v[28:31], v[146:149], v[216:219], v[28:31]
	v_mfma_f32_16x16x32_bf16 v[20:23], v[154:157], v[216:219], v[20:23]
	v_mfma_f32_16x16x32_bf16 v[12:15], v[146:149], v[224:227], v[12:15]
	v_mfma_f32_16x16x32_bf16 v[4:7], v[154:157], v[224:227], v[4:7]
	v_mfma_f32_16x16x32_bf16 v[60:63], v[150:153], v[204:207], v[60:63]
	v_mfma_f32_16x16x32_bf16 v[52:55], v[160:163], v[204:207], v[52:55]
	v_mfma_f32_16x16x32_bf16 v[44:47], v[150:153], v[212:215], v[44:47]
	v_mfma_f32_16x16x32_bf16 v[36:39], v[160:163], v[212:215], v[36:39]
	v_mfma_f32_16x16x32_bf16 v[28:31], v[150:153], v[220:223], v[28:31]
	v_mfma_f32_16x16x32_bf16 v[20:23], v[160:163], v[220:223], v[20:23]
	v_mfma_f32_16x16x32_bf16 v[12:15], v[150:153], v[228:231], v[12:15]
	v_mfma_f32_16x16x32_bf16 v[4:7], v[160:163], v[228:231], v[4:7]
	v_mfma_f32_16x16x32_bf16 v[56:59], v[178:181], v[198:201], v[56:59]
	v_mfma_f32_16x16x32_bf16 v[48:51], v[186:189], v[198:201], v[48:51]
	v_mfma_f32_16x16x32_bf16 v[40:43], v[178:181], v[208:211], v[40:43]
	v_mfma_f32_16x16x32_bf16 v[32:35], v[186:189], v[208:211], v[32:35]
	v_mfma_f32_16x16x32_bf16 v[24:27], v[178:181], v[216:219], v[24:27]
	v_mfma_f32_16x16x32_bf16 v[16:19], v[186:189], v[216:219], v[16:19]
	v_mfma_f32_16x16x32_bf16 v[8:11], v[178:181], v[224:227], v[8:11]
	v_mfma_f32_16x16x32_bf16 v[0:3], v[186:189], v[224:227], v[0:3]
	v_mfma_f32_16x16x32_bf16 v[56:59], v[182:185], v[204:207], v[56:59]
	v_mfma_f32_16x16x32_bf16 v[48:51], v[190:193], v[204:207], v[48:51]
	v_mfma_f32_16x16x32_bf16 v[40:43], v[182:185], v[212:215], v[40:43]
	v_mfma_f32_16x16x32_bf16 v[32:35], v[190:193], v[212:215], v[32:35]
	v_mfma_f32_16x16x32_bf16 v[24:27], v[182:185], v[220:223], v[24:27]
	v_mfma_f32_16x16x32_bf16 v[16:19], v[190:193], v[220:223], v[16:19]
	v_mfma_f32_16x16x32_bf16 v[8:11], v[182:185], v[228:231], v[8:11]
	v_mfma_f32_16x16x32_bf16 v[0:3], v[190:193], v[228:231], v[0:3]
	s_setprio 1
	s_barrier
	s_add_i32 s55, s55, 2
	s_add_u32 s10, s10, 0x100
	s_addc_u32 s11, s11, 0
	s_add_u32 s53, s53, 0x100
	s_addc_u32 s54, s54, 0
	s_cmp_gt_u32 s55, 13
	s_cbranch_scc0 .LBB0_1048
	s_and_b64 vcc, exec, s[26:27]
	s_cbranch_vccz .LBB0_1051
	s_barrier
.LBB0_1051:
	s_setprio 0
	v_lshl_add_u32 v162, s8, 8, v159
	s_mov_b64 s[60:61], 0x2000
	v_lshlrev_b32_e32 v204, 6, v162
	v_mov_b32_e32 v205, 0
	v_mbcnt_lo_u32_b32 v248, -1, 0
	v_mbcnt_hi_u32_b32 v248, -1, v248
	v_xor_b32_e32 v248, 16, v248
	v_lshl_add_u64 v[204:205], v[136:137], 0, v[204:205]
	v_lshlrev_b32_e32 v248, 2, v248
	v_lshl_add_u64 v[206:207], v[204:205], 0, s[60:61]
	global_load_dwordx4 v[208:211], v[204:205], off
	global_load_dwordx4 v[212:215], v[204:205], off offset:1024
	global_load_dwordx4 v[216:219], v[204:205], off offset:2048
	global_load_dwordx4 v[220:223], v[204:205], off offset:3072
	global_load_dwordx4 v[224:227], v[206:207], off
	global_load_dwordx4 v[228:231], v[206:207], off offset:1024
	global_load_dwordx4 v[232:235], v[206:207], off offset:2048
	global_load_dwordx4 v[236:239], v[206:207], off offset:3072
	s_waitcnt vmcnt(0)
	v_add_f32_e32 v208, v208, v209
	v_add_f32_e32 v210, v210, v211
	v_add_f32_e32 v212, v212, v213
	v_add_f32_e32 v214, v214, v215
	v_add_f32_e32 v216, v216, v217
	v_add_f32_e32 v218, v218, v219
	v_add_f32_e32 v220, v220, v221
	v_add_f32_e32 v222, v222, v223
	v_add_f32_e32 v224, v224, v225
	v_add_f32_e32 v226, v226, v227
	v_add_f32_e32 v228, v228, v229
	v_add_f32_e32 v230, v230, v231
	v_add_f32_e32 v232, v232, v233
	v_add_f32_e32 v234, v234, v235
	v_add_f32_e32 v236, v236, v237
	v_add_f32_e32 v238, v238, v239
	v_add_f32_e32 v208, v208, v210
	v_add_f32_e32 v212, v212, v214
	v_add_f32_e32 v216, v216, v218
	v_add_f32_e32 v220, v220, v222
	v_add_f32_e32 v224, v224, v226
	v_add_f32_e32 v228, v228, v230
	v_add_f32_e32 v232, v232, v234
	v_add_f32_e32 v236, v236, v238
	ds_bpermute_b32 v209, v248, v208
	ds_bpermute_b32 v213, v248, v212
	ds_bpermute_b32 v217, v248, v216
	ds_bpermute_b32 v221, v248, v220
	ds_bpermute_b32 v225, v248, v224
	ds_bpermute_b32 v229, v248, v228
	ds_bpermute_b32 v233, v248, v232
	ds_bpermute_b32 v237, v248, v236
	s_waitcnt lgkmcnt(0)
	v_add_f32_e32 v208, v208, v209
	v_add_f32_e32 v212, v212, v213
	v_add_f32_e32 v216, v216, v217
	v_add_f32_e32 v220, v220, v221
	v_add_f32_e32 v224, v224, v225
	v_add_f32_e32 v228, v228, v229
	v_add_f32_e32 v232, v232, v233
	v_add_f32_e32 v236, v236, v237
	v_mov_b32_e32 v209, v208
	v_mov_b32_e32 v213, v212
	v_mov_b32_e32 v217, v216
	v_mov_b32_e32 v221, v220
	v_mov_b32_e32 v225, v224
	v_mov_b32_e32 v229, v228
	v_mov_b32_e32 v233, v232
	v_mov_b32_e32 v237, v236
	s_nop 1
	v_permlane32_swap_b32_e32 v208, v209
	v_permlane32_swap_b32_e32 v212, v213
	v_permlane32_swap_b32_e32 v216, v217
	v_permlane32_swap_b32_e32 v220, v221
	v_permlane32_swap_b32_e32 v224, v225
	v_permlane32_swap_b32_e32 v228, v229
	v_permlane32_swap_b32_e32 v232, v233
	v_permlane32_swap_b32_e32 v236, v237
	v_add_f32_e32 v208, v208, v209
	v_add_f32_e32 v212, v212, v213
	v_add_f32_e32 v216, v216, v217
	v_add_f32_e32 v220, v220, v221
	v_add_f32_e32 v224, v224, v225
	v_add_f32_e32 v228, v228, v229
	v_add_f32_e32 v232, v232, v233
	v_add_f32_e32 v236, v236, v237
	v_fmamk_f32 v208, v208, 0x3a800000, v175
	v_fmamk_f32 v212, v212, 0x3a800000, v175
	v_fmamk_f32 v216, v216, 0x3a800000, v175
	v_fmamk_f32 v220, v220, 0x3a800000, v175
	v_fmamk_f32 v224, v224, 0x3a800000, v175
	v_fmamk_f32 v228, v228, 0x3a800000, v175
	v_fmamk_f32 v232, v232, 0x3a800000, v175
	v_fmamk_f32 v236, v236, 0x3a800000, v175
	v_rsq_f32_e32 v176, v208
	v_rsq_f32_e32 v174, v212
	v_rsq_f32_e32 v172, v216
	v_rsq_f32_e32 v170, v220
	v_rsq_f32_e32 v168, v224
	v_rsq_f32_e32 v166, v228
	v_rsq_f32_e32 v164, v232
	v_rsq_f32_e32 v158, v236
	s_nop 0
	v_or_b32_e32 v160, 16, v162
	v_or_b32_e32 v156, 32, v162
	v_or_b32_e32 v154, 48, v162
	v_add_u32_e32 v148, 0x80, v162
	s_waitcnt vmcnt(0)
	s_waitcnt lgkmcnt(2)
	s_waitcnt lgkmcnt(2)
	s_waitcnt lgkmcnt(1)
	s_waitcnt lgkmcnt(2)
	s_waitcnt lgkmcnt(1)
	s_waitcnt lgkmcnt(0)
	s_nop 0
	v_add_u32_e32 v152, 0x90, v162
	s_waitcnt lgkmcnt(0)
	s_waitcnt lgkmcnt(0)
	s_waitcnt vmcnt(0)
	v_add_u32_e32 v150, 0xa0, v162
	s_waitcnt lgkmcnt(0)
	s_waitcnt lgkmcnt(0)
	s_nop 0
	s_nop 1
	v_add_u32_e32 v146, 0xb0, v162
	s_waitcnt lgkmcnt(0)
	s_waitcnt lgkmcnt(0)
	s_waitcnt vmcnt(1)
	s_waitcnt lgkmcnt(0)
	s_waitcnt lgkmcnt(0)
	s_waitcnt vmcnt(0)
	v_mov_b32_e32 v178, v120
	s_waitcnt lgkmcnt(0)
	s_waitcnt lgkmcnt(0)
	v_mov_b32_e32 v179, v124
	v_pk_mul_f32 v[178:179], v[178:179], v[176:177] op_sel_hi:[1,0]
	v_mov_b32_e32 v124, v121
	v_mul_f32_e32 v120, 0xbfb8aa3b, v179
	v_exp_f32_e32 v147, v120
	v_pk_mul_f32 v[120:121], v[124:125], v[176:177] op_sel_hi:[1,0]
	s_andn2_b64 vcc, exec, s[6:7]
	v_mul_f32_e32 v124, 0xbfb8aa3b, v121
	v_exp_f32_e32 v125, v124
	v_add_f32_e32 v147, 1.0, v147
	v_rcp_f32_e32 v147, v147
	v_lshl_or_b32 v124, s33, 7, v167
	v_add_f32_e32 v125, 1.0, v125
	v_rcp_f32_e32 v149, v125
	v_mul_f32_e32 v147, v179, v147
	v_mul_f32_e32 v147, v178, v147
	v_mov_b32_e32 v178, v122
	v_mov_b32_e32 v179, v126
	v_pk_mul_f32 v[178:179], v[178:179], v[176:177] op_sel_hi:[1,0]
	v_mov_b32_e32 v126, v123
	v_mul_f32_e32 v122, 0xbfb8aa3b, v179
	v_mul_f32_e32 v121, v121, v149
	v_exp_f32_e32 v149, v122
	v_pk_mul_f32 v[122:123], v[126:127], v[176:177] op_sel_hi:[1,0]
	v_mul_f32_e32 v127, v120, v121
	v_mul_f32_e32 v126, 0xbfb8aa3b, v123
	v_exp_f32_e32 v126, v126
	v_add_f32_e32 v120, 1.0, v149
	v_rcp_f32_e32 v149, v120
	v_mov_b32_e32 v121, v116
	v_add_f32_e32 v120, 1.0, v126
	v_rcp_f32_e32 v126, v120
	v_mov_b32_e32 v120, v112
	v_pk_mul_f32 v[120:121], v[120:121], v[176:177] op_sel_hi:[1,0]
	v_mul_f32_e32 v116, v179, v149
	v_mul_f32_e32 v112, 0xbfb8aa3b, v121
	v_exp_f32_e32 v112, v112
	v_mul_f32_e32 v149, v178, v116
	v_mov_b32_e32 v116, v113
	v_mul_f32_e32 v123, v123, v126
	v_add_f32_e32 v112, 1.0, v112
	v_rcp_f32_e32 v126, v112
	v_pk_mul_f32 v[112:113], v[116:117], v[176:177] op_sel_hi:[1,0]
	v_mul_f32_e32 v122, v122, v123
	v_mul_f32_e32 v116, 0xbfb8aa3b, v113
	v_exp_f32_e32 v116, v116
	v_mul_f32_e32 v117, v121, v126
	v_mul_f32_e32 v120, v120, v117
	v_mov_b32_e32 v117, v118
	v_add_f32_e32 v116, 1.0, v116
	v_rcp_f32_e32 v121, v116
	v_mov_b32_e32 v116, v114
	v_pk_mul_f32 v[116:117], v[116:117], v[176:177] op_sel_hi:[1,0]
	v_mov_b32_e32 v118, v115
	v_mul_f32_e32 v114, 0xbfb8aa3b, v117
	v_exp_f32_e32 v123, v114
	v_pk_mul_f32 v[114:115], v[118:119], v[176:177] op_sel_hi:[1,0]
	v_mul_f32_e32 v113, v113, v121
	v_mul_f32_e32 v118, 0xbfb8aa3b, v115
	v_exp_f32_e32 v118, v118
	v_add_f32_e32 v119, 1.0, v123
	v_rcp_f32_e32 v119, v119
	v_mul_f32_e32 v112, v112, v113
	v_add_f32_e32 v118, 1.0, v118
	v_rcp_f32_e32 v118, v118
	v_mul_f32_e32 v113, v117, v119
	v_mul_f32_e32 v113, v116, v113
	v_cvt_pk_bf16_f32 v116, v147, v127
	v_cvt_pk_bf16_f32 v117, v149, v122
	v_mov_b32_e32 v122, v104
	v_mov_b32_e32 v123, v108
	v_mul_f32_e32 v115, v115, v118
	v_pk_mul_f32 v[122:123], v[122:123], v[174:175] op_sel_hi:[1,0]
	v_ashrrev_i32_e32 v125, 31, v124
	v_mul_f32_e32 v114, v114, v115
	v_mul_f32_e32 v104, 0xbfb8aa3b, v123
	v_cvt_pk_bf16_f32 v118, v120, v112
	v_cvt_pk_bf16_f32 v119, v113, v114
	v_lshlrev_b64 v[114:115], 1, v[124:125]
	v_exp_f32_e32 v124, v104
	v_mov_b32_e32 v108, v105
	v_mov_b64_e32 v[112:113], s[22:23]
	v_pk_mul_f32 v[104:105], v[108:109], v[174:175] op_sel_hi:[1,0]
	v_mad_i64_i32 v[120:121], s[4:5], v162, s51, v[112:113]
	v_mul_f32_e32 v108, 0xbfb8aa3b, v105
	v_exp_f32_e32 v125, v108
	v_lshl_add_u64 v[108:109], v[120:121], 0, v[114:115]
	v_add_f32_e32 v120, 1.0, v124
	v_rcp_f32_e32 v120, v120
	global_store_dwordx4 v[108:109], v[116:119], off
	v_mov_b32_e32 v109, v110
	v_add_f32_e32 v121, 1.0, v125
	v_mul_f32_e32 v108, v123, v120
	v_mul_f32_e32 v116, v122, v108
	v_mov_b32_e32 v108, v106
	v_pk_mul_f32 v[108:109], v[108:109], v[174:175] op_sel_hi:[1,0]
	v_mov_b32_e32 v110, v107
	v_mul_f32_e32 v106, 0xbfb8aa3b, v109
	v_rcp_f32_e32 v121, v121
	v_exp_f32_e32 v117, v106
	v_pk_mul_f32 v[106:107], v[110:111], v[174:175] op_sel_hi:[1,0]
	v_mul_f32_e32 v105, v105, v121
	v_mul_f32_e32 v110, 0xbfb8aa3b, v107
	v_exp_f32_e32 v110, v110
	v_mul_f32_e32 v111, v104, v105
	v_add_f32_e32 v104, 1.0, v117
	v_rcp_f32_e32 v117, v104
	v_add_f32_e32 v104, 1.0, v110
	v_rcp_f32_e32 v110, v104
	v_mov_b32_e32 v104, v96
	v_mov_b32_e32 v105, v100
	v_pk_mul_f32 v[104:105], v[104:105], v[174:175] op_sel_hi:[1,0]
	v_mul_f32_e32 v100, v109, v117
	v_mul_f32_e32 v96, 0xbfb8aa3b, v105
	v_exp_f32_e32 v96, v96
	v_mul_f32_e32 v108, v108, v100
	v_mov_b32_e32 v100, v97
	v_mul_f32_e32 v107, v107, v110
	v_add_f32_e32 v96, 1.0, v96
	v_rcp_f32_e32 v109, v96
	v_pk_mul_f32 v[96:97], v[100:101], v[174:175] op_sel_hi:[1,0]
	v_mul_f32_e32 v106, v106, v107
	v_mul_f32_e32 v100, 0xbfb8aa3b, v97
	v_exp_f32_e32 v100, v100
	v_mul_f32_e32 v101, v105, v109
	v_mul_f32_e32 v104, v104, v101
	v_mov_b32_e32 v101, v102
	v_add_f32_e32 v100, 1.0, v100
	v_rcp_f32_e32 v105, v100
	v_mov_b32_e32 v100, v98
	v_pk_mul_f32 v[100:101], v[100:101], v[174:175] op_sel_hi:[1,0]
	v_mov_b32_e32 v102, v99
	v_mul_f32_e32 v98, 0xbfb8aa3b, v101
	v_exp_f32_e32 v107, v98
	v_pk_mul_f32 v[98:99], v[102:103], v[174:175] op_sel_hi:[1,0]
	v_mul_f32_e32 v97, v97, v105
	v_mul_f32_e32 v102, 0xbfb8aa3b, v99
	v_exp_f32_e32 v102, v102
	v_add_f32_e32 v103, 1.0, v107
	v_rcp_f32_e32 v103, v103
	v_mul_f32_e32 v105, v96, v97
	v_add_f32_e32 v102, 1.0, v102
	v_rcp_f32_e32 v102, v102
	v_mul_f32_e32 v96, v101, v103
	v_mul_f32_e32 v100, v100, v96
	v_mov_b32_e32 v103, v92
	v_mul_f32_e32 v96, v99, v102
	v_mov_b32_e32 v102, v88
	v_pk_mul_f32 v[102:103], v[102:103], v[172:173] op_sel_hi:[1,0]
	v_mul_f32_e32 v99, v98, v96
	v_mul_f32_e32 v88, 0xbfb8aa3b, v103
	v_cvt_pk_bf16_f32 v96, v116, v111
	v_cvt_pk_bf16_f32 v97, v108, v106
	v_cvt_pk_bf16_f32 v98, v104, v105
	v_exp_f32_e32 v104, v88
	v_mov_b32_e32 v92, v89
	v_pk_mul_f32 v[88:89], v[92:93], v[172:173] op_sel_hi:[1,0]
	v_cvt_pk_bf16_f32 v99, v100, v99
	v_mad_i64_i32 v[100:101], s[4:5], v160, s51, v[112:113]
	v_mul_f32_e32 v92, 0xbfb8aa3b, v89
	v_exp_f32_e32 v105, v92
	v_lshl_add_u64 v[92:93], v[100:101], 0, v[114:115]
	v_add_f32_e32 v100, 1.0, v104
	v_rcp_f32_e32 v100, v100
	global_store_dwordx4 v[92:93], v[96:99], off
	v_mov_b32_e32 v93, v94
	v_add_f32_e32 v101, 1.0, v105
	v_mul_f32_e32 v92, v103, v100
	v_mul_f32_e32 v96, v102, v92
	v_mov_b32_e32 v92, v90
	v_pk_mul_f32 v[92:93], v[92:93], v[172:173] op_sel_hi:[1,0]
	v_mov_b32_e32 v94, v91
	v_mul_f32_e32 v90, 0xbfb8aa3b, v93
	v_rcp_f32_e32 v101, v101
	v_exp_f32_e32 v97, v90
	v_pk_mul_f32 v[90:91], v[94:95], v[172:173] op_sel_hi:[1,0]
	v_mul_f32_e32 v89, v89, v101
	v_mul_f32_e32 v94, 0xbfb8aa3b, v91
	v_exp_f32_e32 v94, v94
	v_mul_f32_e32 v95, v88, v89
	v_add_f32_e32 v88, 1.0, v97
	v_rcp_f32_e32 v97, v88
	v_add_f32_e32 v88, 1.0, v94
	v_rcp_f32_e32 v94, v88
	v_mov_b32_e32 v88, v80
	v_mov_b32_e32 v89, v84
	v_pk_mul_f32 v[88:89], v[88:89], v[172:173] op_sel_hi:[1,0]
	v_mul_f32_e32 v84, v93, v97
	v_mul_f32_e32 v80, 0xbfb8aa3b, v89
	v_exp_f32_e32 v80, v80
	v_mul_f32_e32 v92, v92, v84
	v_mov_b32_e32 v84, v81
	v_mul_f32_e32 v91, v91, v94
	v_add_f32_e32 v80, 1.0, v80
	v_rcp_f32_e32 v93, v80
	v_pk_mul_f32 v[80:81], v[84:85], v[172:173] op_sel_hi:[1,0]
	v_mul_f32_e32 v90, v90, v91
	v_mul_f32_e32 v84, 0xbfb8aa3b, v81
	v_exp_f32_e32 v84, v84
	v_mul_f32_e32 v85, v89, v93
	v_mul_f32_e32 v88, v88, v85
	v_mov_b32_e32 v85, v86
	v_add_f32_e32 v84, 1.0, v84
	v_rcp_f32_e32 v89, v84
	v_mov_b32_e32 v84, v82
	v_pk_mul_f32 v[84:85], v[84:85], v[172:173] op_sel_hi:[1,0]
	v_mov_b32_e32 v86, v83
	v_mul_f32_e32 v82, 0xbfb8aa3b, v85
	v_exp_f32_e32 v91, v82
	v_pk_mul_f32 v[82:83], v[86:87], v[172:173] op_sel_hi:[1,0]
	v_mul_f32_e32 v81, v81, v89
	v_mul_f32_e32 v86, 0xbfb8aa3b, v83
	v_exp_f32_e32 v86, v86
	v_add_f32_e32 v87, 1.0, v91
	v_rcp_f32_e32 v87, v87
	v_mul_f32_e32 v89, v80, v81
	v_add_f32_e32 v86, 1.0, v86
	v_rcp_f32_e32 v86, v86
	v_mul_f32_e32 v80, v85, v87
	v_mul_f32_e32 v84, v84, v80
	v_mov_b32_e32 v87, v76
	v_mul_f32_e32 v80, v83, v86
	v_mov_b32_e32 v86, v72
	v_pk_mul_f32 v[86:87], v[86:87], v[170:171] op_sel_hi:[1,0]
	v_mul_f32_e32 v83, v82, v80
	v_mul_f32_e32 v72, 0xbfb8aa3b, v87
	v_cvt_pk_bf16_f32 v80, v96, v95
	v_cvt_pk_bf16_f32 v81, v92, v90
	v_cvt_pk_bf16_f32 v82, v88, v89
	v_exp_f32_e32 v88, v72
	v_mov_b32_e32 v76, v73
	v_pk_mul_f32 v[72:73], v[76:77], v[170:171] op_sel_hi:[1,0]
	v_cvt_pk_bf16_f32 v83, v84, v83
	v_mad_i64_i32 v[84:85], s[4:5], v156, s51, v[112:113]
	v_mul_f32_e32 v76, 0xbfb8aa3b, v73
	v_exp_f32_e32 v89, v76
	v_lshl_add_u64 v[76:77], v[84:85], 0, v[114:115]
	v_add_f32_e32 v84, 1.0, v88
	v_rcp_f32_e32 v84, v84
	global_store_dwordx4 v[76:77], v[80:83], off
	v_mov_b32_e32 v77, v78
	v_add_f32_e32 v85, 1.0, v89
	v_mul_f32_e32 v76, v87, v84
	v_mul_f32_e32 v80, v86, v76
	v_mov_b32_e32 v76, v74
	v_pk_mul_f32 v[76:77], v[76:77], v[170:171] op_sel_hi:[1,0]
	v_mov_b32_e32 v78, v75
	v_mul_f32_e32 v74, 0xbfb8aa3b, v77
	v_rcp_f32_e32 v85, v85
	v_exp_f32_e32 v81, v74
	v_pk_mul_f32 v[74:75], v[78:79], v[170:171] op_sel_hi:[1,0]
	v_mul_f32_e32 v73, v73, v85
	v_mul_f32_e32 v78, 0xbfb8aa3b, v75
	v_exp_f32_e32 v78, v78
	v_mul_f32_e32 v79, v72, v73
	v_add_f32_e32 v72, 1.0, v81
	v_rcp_f32_e32 v81, v72
	v_add_f32_e32 v72, 1.0, v78
	v_rcp_f32_e32 v78, v72
	v_mov_b32_e32 v72, v64
	v_mov_b32_e32 v73, v68
	v_pk_mul_f32 v[72:73], v[72:73], v[170:171] op_sel_hi:[1,0]
	v_mul_f32_e32 v68, v77, v81
	v_mul_f32_e32 v64, 0xbfb8aa3b, v73
	v_exp_f32_e32 v64, v64
	v_mul_f32_e32 v76, v76, v68
	v_mov_b32_e32 v68, v65
	v_mul_f32_e32 v75, v75, v78
	v_add_f32_e32 v64, 1.0, v64
	v_rcp_f32_e32 v77, v64
	v_pk_mul_f32 v[64:65], v[68:69], v[170:171] op_sel_hi:[1,0]
	v_mul_f32_e32 v74, v74, v75
	v_mul_f32_e32 v68, 0xbfb8aa3b, v65
	v_exp_f32_e32 v68, v68
	v_mul_f32_e32 v69, v73, v77
	v_mul_f32_e32 v72, v72, v69
	v_mov_b32_e32 v69, v70
	v_add_f32_e32 v68, 1.0, v68
	v_rcp_f32_e32 v73, v68
	v_mov_b32_e32 v68, v66
	v_pk_mul_f32 v[68:69], v[68:69], v[170:171] op_sel_hi:[1,0]
	v_mov_b32_e32 v70, v67
	v_mul_f32_e32 v66, 0xbfb8aa3b, v69
	v_exp_f32_e32 v75, v66
	v_pk_mul_f32 v[66:67], v[70:71], v[170:171] op_sel_hi:[1,0]
	v_mul_f32_e32 v65, v65, v73
	v_mul_f32_e32 v70, 0xbfb8aa3b, v67
	v_exp_f32_e32 v70, v70
	v_add_f32_e32 v71, 1.0, v75
	v_rcp_f32_e32 v71, v71
	v_mul_f32_e32 v73, v64, v65
	v_add_f32_e32 v70, 1.0, v70
	v_rcp_f32_e32 v70, v70
	v_mul_f32_e32 v64, v69, v71
	v_mul_f32_e32 v68, v68, v64
	v_mov_b32_e32 v71, v60
	v_mul_f32_e32 v64, v67, v70
	v_mov_b32_e32 v70, v56
	v_pk_mul_f32 v[70:71], v[70:71], v[168:169] op_sel_hi:[1,0]
	v_mul_f32_e32 v67, v66, v64
	v_mul_f32_e32 v56, 0xbfb8aa3b, v71
	v_cvt_pk_bf16_f32 v64, v80, v79
	v_cvt_pk_bf16_f32 v65, v76, v74
	v_cvt_pk_bf16_f32 v66, v72, v73
	v_exp_f32_e32 v72, v56
	v_mov_b32_e32 v60, v57
	v_pk_mul_f32 v[56:57], v[60:61], v[168:169] op_sel_hi:[1,0]
	v_cvt_pk_bf16_f32 v67, v68, v67
	v_mad_i64_i32 v[68:69], s[4:5], v154, s51, v[112:113]
	v_mul_f32_e32 v60, 0xbfb8aa3b, v57
	v_exp_f32_e32 v73, v60
	v_lshl_add_u64 v[60:61], v[68:69], 0, v[114:115]
	v_add_f32_e32 v68, 1.0, v72
	v_rcp_f32_e32 v68, v68
	global_store_dwordx4 v[60:61], v[64:67], off
	v_mov_b32_e32 v61, v62
	v_add_f32_e32 v69, 1.0, v73
	v_mul_f32_e32 v60, v71, v68
	v_mul_f32_e32 v64, v70, v60
	v_mov_b32_e32 v60, v58
	v_pk_mul_f32 v[60:61], v[60:61], v[168:169] op_sel_hi:[1,0]
	v_mov_b32_e32 v62, v59
	v_mul_f32_e32 v58, 0xbfb8aa3b, v61
	v_rcp_f32_e32 v69, v69
	v_exp_f32_e32 v65, v58
	v_pk_mul_f32 v[58:59], v[62:63], v[168:169] op_sel_hi:[1,0]
	v_mul_f32_e32 v57, v57, v69
	v_mul_f32_e32 v62, 0xbfb8aa3b, v59
	v_exp_f32_e32 v62, v62
	v_mul_f32_e32 v63, v56, v57
	v_add_f32_e32 v56, 1.0, v65
	v_rcp_f32_e32 v65, v56
	v_add_f32_e32 v56, 1.0, v62
	v_rcp_f32_e32 v62, v56
	v_mov_b32_e32 v56, v48
	v_mov_b32_e32 v57, v52
	v_pk_mul_f32 v[56:57], v[56:57], v[168:169] op_sel_hi:[1,0]
	v_mul_f32_e32 v52, v61, v65
	v_mul_f32_e32 v48, 0xbfb8aa3b, v57
	v_exp_f32_e32 v48, v48
	v_mul_f32_e32 v60, v60, v52
	v_mov_b32_e32 v52, v49
	v_mul_f32_e32 v59, v59, v62
	v_add_f32_e32 v48, 1.0, v48
	v_rcp_f32_e32 v61, v48
	v_pk_mul_f32 v[48:49], v[52:53], v[168:169] op_sel_hi:[1,0]
	v_mul_f32_e32 v58, v58, v59
	v_mul_f32_e32 v52, 0xbfb8aa3b, v49
	v_exp_f32_e32 v52, v52
	v_mul_f32_e32 v53, v57, v61
	v_mul_f32_e32 v56, v56, v53
	v_mov_b32_e32 v53, v54
	v_add_f32_e32 v52, 1.0, v52
	v_rcp_f32_e32 v57, v52
	v_mov_b32_e32 v52, v50
	v_pk_mul_f32 v[52:53], v[52:53], v[168:169] op_sel_hi:[1,0]
	v_mov_b32_e32 v54, v51
	v_mul_f32_e32 v50, 0xbfb8aa3b, v53
	v_exp_f32_e32 v59, v50
	v_pk_mul_f32 v[50:51], v[54:55], v[168:169] op_sel_hi:[1,0]
	v_mul_f32_e32 v49, v49, v57
	v_mul_f32_e32 v54, 0xbfb8aa3b, v51
	v_exp_f32_e32 v54, v54
	v_add_f32_e32 v55, 1.0, v59
	v_rcp_f32_e32 v55, v55
	v_mul_f32_e32 v57, v48, v49
	v_add_f32_e32 v54, 1.0, v54
	v_rcp_f32_e32 v54, v54
	v_mul_f32_e32 v48, v53, v55
	v_mul_f32_e32 v52, v52, v48
	v_mov_b32_e32 v55, v44
	v_mul_f32_e32 v48, v51, v54
	v_mov_b32_e32 v54, v40
	v_pk_mul_f32 v[54:55], v[54:55], v[166:167] op_sel_hi:[1,0]
	v_mul_f32_e32 v51, v50, v48
	v_mul_f32_e32 v40, 0xbfb8aa3b, v55
	v_cvt_pk_bf16_f32 v48, v64, v63
	v_cvt_pk_bf16_f32 v49, v60, v58
	v_cvt_pk_bf16_f32 v50, v56, v57
	v_exp_f32_e32 v56, v40
	v_mov_b32_e32 v44, v41
	v_pk_mul_f32 v[40:41], v[44:45], v[166:167] op_sel_hi:[1,0]
	v_cvt_pk_bf16_f32 v51, v52, v51
	v_mad_i64_i32 v[52:53], s[4:5], v148, s51, v[112:113]
	v_mul_f32_e32 v44, 0xbfb8aa3b, v41
	v_exp_f32_e32 v57, v44
	v_lshl_add_u64 v[44:45], v[52:53], 0, v[114:115]
	v_add_f32_e32 v52, 1.0, v56
	v_rcp_f32_e32 v52, v52
	global_store_dwordx4 v[44:45], v[48:51], off
	v_mov_b32_e32 v45, v46
	v_add_f32_e32 v53, 1.0, v57
	v_mul_f32_e32 v44, v55, v52
	v_mul_f32_e32 v48, v54, v44
	v_mov_b32_e32 v44, v42
	v_pk_mul_f32 v[44:45], v[44:45], v[166:167] op_sel_hi:[1,0]
	v_mov_b32_e32 v46, v43
	v_mul_f32_e32 v42, 0xbfb8aa3b, v45
	v_rcp_f32_e32 v53, v53
	v_exp_f32_e32 v49, v42
	v_pk_mul_f32 v[42:43], v[46:47], v[166:167] op_sel_hi:[1,0]
	v_mul_f32_e32 v41, v41, v53
	v_mul_f32_e32 v46, 0xbfb8aa3b, v43
	v_exp_f32_e32 v46, v46
	v_mul_f32_e32 v47, v40, v41
	v_add_f32_e32 v40, 1.0, v49
	v_rcp_f32_e32 v49, v40
	v_add_f32_e32 v40, 1.0, v46
	v_rcp_f32_e32 v46, v40
	v_mov_b32_e32 v40, v32
	v_mov_b32_e32 v41, v36
	v_pk_mul_f32 v[40:41], v[40:41], v[166:167] op_sel_hi:[1,0]
	v_mul_f32_e32 v36, v45, v49
	v_mul_f32_e32 v32, 0xbfb8aa3b, v41
	v_exp_f32_e32 v32, v32
	v_mul_f32_e32 v44, v44, v36
	v_mov_b32_e32 v36, v33
	v_mul_f32_e32 v43, v43, v46
	v_add_f32_e32 v32, 1.0, v32
	v_rcp_f32_e32 v45, v32
	v_pk_mul_f32 v[32:33], v[36:37], v[166:167] op_sel_hi:[1,0]
	v_mul_f32_e32 v42, v42, v43
	v_mul_f32_e32 v36, 0xbfb8aa3b, v33
	v_exp_f32_e32 v36, v36
	v_mul_f32_e32 v37, v41, v45
	v_mul_f32_e32 v40, v40, v37
	v_mov_b32_e32 v37, v38
	v_add_f32_e32 v36, 1.0, v36
	v_rcp_f32_e32 v41, v36
	v_mov_b32_e32 v36, v34
	v_pk_mul_f32 v[36:37], v[36:37], v[166:167] op_sel_hi:[1,0]
	v_mov_b32_e32 v38, v35
	v_mul_f32_e32 v34, 0xbfb8aa3b, v37
	v_exp_f32_e32 v43, v34
	v_pk_mul_f32 v[34:35], v[38:39], v[166:167] op_sel_hi:[1,0]
	v_mul_f32_e32 v33, v33, v41
	v_mul_f32_e32 v38, 0xbfb8aa3b, v35
	v_exp_f32_e32 v38, v38
	v_add_f32_e32 v39, 1.0, v43
	v_rcp_f32_e32 v39, v39
	v_mul_f32_e32 v41, v32, v33
	v_add_f32_e32 v38, 1.0, v38
	v_rcp_f32_e32 v38, v38
	v_mul_f32_e32 v32, v37, v39
	v_mul_f32_e32 v36, v36, v32
	v_mov_b32_e32 v39, v28
	v_mul_f32_e32 v32, v35, v38
	v_mov_b32_e32 v38, v24
	v_pk_mul_f32 v[38:39], v[38:39], v[164:165] op_sel_hi:[1,0]
	v_mul_f32_e32 v35, v34, v32
	v_mul_f32_e32 v24, 0xbfb8aa3b, v39
	v_cvt_pk_bf16_f32 v32, v48, v47
	v_cvt_pk_bf16_f32 v33, v44, v42
	v_cvt_pk_bf16_f32 v34, v40, v41
	v_exp_f32_e32 v40, v24
	v_mov_b32_e32 v28, v25
	v_pk_mul_f32 v[24:25], v[28:29], v[164:165] op_sel_hi:[1,0]
	v_cvt_pk_bf16_f32 v35, v36, v35
	v_mad_i64_i32 v[36:37], s[4:5], v152, s51, v[112:113]
	v_mul_f32_e32 v28, 0xbfb8aa3b, v25
	v_exp_f32_e32 v41, v28
	v_lshl_add_u64 v[28:29], v[36:37], 0, v[114:115]
	v_add_f32_e32 v36, 1.0, v40
	v_rcp_f32_e32 v36, v36
	global_store_dwordx4 v[28:29], v[32:35], off
	v_mov_b32_e32 v29, v30
	v_add_f32_e32 v37, 1.0, v41
	v_mul_f32_e32 v28, v39, v36
	v_mul_f32_e32 v32, v38, v28
	v_mov_b32_e32 v28, v26
	v_pk_mul_f32 v[28:29], v[28:29], v[164:165] op_sel_hi:[1,0]
	v_mov_b32_e32 v30, v27
	v_mul_f32_e32 v26, 0xbfb8aa3b, v29
	v_rcp_f32_e32 v37, v37
	v_exp_f32_e32 v33, v26
	v_pk_mul_f32 v[26:27], v[30:31], v[164:165] op_sel_hi:[1,0]
	v_mul_f32_e32 v25, v25, v37
	v_mul_f32_e32 v30, 0xbfb8aa3b, v27
	v_exp_f32_e32 v30, v30
	v_mul_f32_e32 v31, v24, v25
	v_add_f32_e32 v24, 1.0, v33
	v_rcp_f32_e32 v33, v24
	v_add_f32_e32 v24, 1.0, v30
	v_rcp_f32_e32 v30, v24
	v_mov_b32_e32 v24, v16
	v_mov_b32_e32 v25, v20
	v_pk_mul_f32 v[24:25], v[24:25], v[164:165] op_sel_hi:[1,0]
	v_mul_f32_e32 v20, v29, v33
	v_mul_f32_e32 v16, 0xbfb8aa3b, v25
	v_exp_f32_e32 v16, v16
	v_mul_f32_e32 v28, v28, v20
	v_mov_b32_e32 v20, v17
	v_mul_f32_e32 v27, v27, v30
	v_add_f32_e32 v16, 1.0, v16
	v_rcp_f32_e32 v29, v16
	v_pk_mul_f32 v[16:17], v[20:21], v[164:165] op_sel_hi:[1,0]
	v_mul_f32_e32 v26, v26, v27
	v_mul_f32_e32 v20, 0xbfb8aa3b, v17
	v_exp_f32_e32 v20, v20
	v_mul_f32_e32 v21, v25, v29
	v_mul_f32_e32 v24, v24, v21
	v_mov_b32_e32 v21, v22
	v_add_f32_e32 v20, 1.0, v20
	v_rcp_f32_e32 v25, v20
	v_mov_b32_e32 v20, v18
	v_pk_mul_f32 v[20:21], v[20:21], v[164:165] op_sel_hi:[1,0]
	v_mov_b32_e32 v22, v19
	v_mul_f32_e32 v18, 0xbfb8aa3b, v21
	v_exp_f32_e32 v27, v18
	v_pk_mul_f32 v[18:19], v[22:23], v[164:165] op_sel_hi:[1,0]
	v_mul_f32_e32 v17, v17, v25
	v_mul_f32_e32 v22, 0xbfb8aa3b, v19
	v_exp_f32_e32 v22, v22
	v_add_f32_e32 v23, 1.0, v27
	v_rcp_f32_e32 v23, v23
	v_mul_f32_e32 v25, v16, v17
	v_add_f32_e32 v22, 1.0, v22
	v_rcp_f32_e32 v22, v22
	v_mul_f32_e32 v16, v21, v23
	v_mul_f32_e32 v20, v20, v16
	v_mov_b32_e32 v23, v12
	v_mul_f32_e32 v16, v19, v22
	v_mov_b32_e32 v22, v8
	v_pk_mul_f32 v[22:23], v[22:23], v[158:159] op_sel_hi:[1,0]
	v_mul_f32_e32 v19, v18, v16
	v_mul_f32_e32 v8, 0xbfb8aa3b, v23
	v_cvt_pk_bf16_f32 v16, v32, v31
	v_cvt_pk_bf16_f32 v17, v28, v26
	v_cvt_pk_bf16_f32 v18, v24, v25
	v_exp_f32_e32 v24, v8
	v_mov_b32_e32 v12, v9
	v_pk_mul_f32 v[8:9], v[12:13], v[158:159] op_sel_hi:[1,0]
	v_cvt_pk_bf16_f32 v19, v20, v19
	v_mad_i64_i32 v[20:21], s[4:5], v150, s51, v[112:113]
	v_mul_f32_e32 v12, 0xbfb8aa3b, v9
	v_exp_f32_e32 v25, v12
	v_lshl_add_u64 v[12:13], v[20:21], 0, v[114:115]
	v_add_f32_e32 v20, 1.0, v24
	v_rcp_f32_e32 v20, v20
	global_store_dwordx4 v[12:13], v[16:19], off
	v_mov_b32_e32 v13, v14
	v_add_f32_e32 v21, 1.0, v25
	v_mul_f32_e32 v12, v23, v20
	v_mul_f32_e32 v16, v22, v12
	v_mov_b32_e32 v12, v10
	v_pk_mul_f32 v[12:13], v[12:13], v[158:159] op_sel_hi:[1,0]
	v_mov_b32_e32 v14, v11
	v_mul_f32_e32 v10, 0xbfb8aa3b, v13
	v_rcp_f32_e32 v21, v21
	v_exp_f32_e32 v17, v10
	v_pk_mul_f32 v[10:11], v[14:15], v[158:159] op_sel_hi:[1,0]
	v_mul_f32_e32 v9, v9, v21
	v_mul_f32_e32 v14, 0xbfb8aa3b, v11
	v_exp_f32_e32 v14, v14
	v_mul_f32_e32 v15, v8, v9
	v_add_f32_e32 v8, 1.0, v17
	v_rcp_f32_e32 v17, v8
	v_add_f32_e32 v8, 1.0, v14
	v_rcp_f32_e32 v14, v8
	v_mov_b32_e32 v8, v0
	v_mov_b32_e32 v9, v4
	v_pk_mul_f32 v[8:9], v[8:9], v[158:159] op_sel_hi:[1,0]
	v_mul_f32_e32 v4, v13, v17
	v_mul_f32_e32 v0, 0xbfb8aa3b, v9
	v_exp_f32_e32 v0, v0
	v_mul_f32_e32 v12, v12, v4
	v_mov_b32_e32 v4, v1
	v_mul_f32_e32 v11, v11, v14
	v_add_f32_e32 v0, 1.0, v0
	v_rcp_f32_e32 v13, v0
	v_pk_mul_f32 v[0:1], v[4:5], v[158:159] op_sel_hi:[1,0]
	v_mul_f32_e32 v10, v10, v11
	v_mul_f32_e32 v4, 0xbfb8aa3b, v1
	v_exp_f32_e32 v4, v4
	v_mul_f32_e32 v5, v9, v13
	v_mul_f32_e32 v8, v8, v5
	v_mov_b32_e32 v5, v6
	v_add_f32_e32 v4, 1.0, v4
	v_rcp_f32_e32 v9, v4
	v_mov_b32_e32 v4, v2
	v_pk_mul_f32 v[4:5], v[4:5], v[158:159] op_sel_hi:[1,0]
	v_mov_b32_e32 v6, v3
	v_mul_f32_e32 v2, 0xbfb8aa3b, v5
	v_exp_f32_e32 v11, v2
	v_pk_mul_f32 v[2:3], v[6:7], v[158:159] op_sel_hi:[1,0]
	v_mul_f32_e32 v1, v1, v9
	v_mul_f32_e32 v6, 0xbfb8aa3b, v3
	v_exp_f32_e32 v6, v6
	v_add_f32_e32 v7, 1.0, v11
	v_rcp_f32_e32 v7, v7
	v_mul_f32_e32 v9, v0, v1
	v_add_f32_e32 v6, 1.0, v6
	v_rcp_f32_e32 v6, v6
	v_mul_f32_e32 v0, v5, v7
	v_mul_f32_e32 v4, v4, v0
	v_mul_f32_e32 v0, v3, v6
	v_mul_f32_e32 v3, v2, v0
	v_cvt_pk_bf16_f32 v0, v16, v15
	v_cvt_pk_bf16_f32 v1, v12, v10
	v_cvt_pk_bf16_f32 v2, v8, v9
	v_cvt_pk_bf16_f32 v3, v4, v3
	v_mad_i64_i32 v[4:5], s[4:5], v146, s51, v[112:113]
	v_lshl_add_u64 v[4:5], v[4:5], 0, v[114:115]
	s_mov_b64 s[4:5], -1
	global_store_dwordx4 v[4:5], v[0:3], off
	s_cbranch_vccnz .LBB0_1044
	s_andn2_b64 vcc, exec, s[16:17]
	s_cbranch_vccnz .LBB0_1043
	s_barrier
	s_branch .LBB0_1043

.LBB0_1124:
	ds_read_b128 v[128:131], v189
	ds_read_b128 v[132:135], v189 offset:1024
	ds_read_b128 v[136:139], v189 offset:2048
	ds_read_b128 v[140:143], v189 offset:3072
	ds_read_b128 v[144:147], v190
	ds_read_b128 v[148:151], v190 offset:1024
	ds_read_b128 v[168:171], v190 offset:2048
	ds_read_b128 v[172:175], v190 offset:3072
	s_add_u32 s34, s30, 0x100
	s_addc_u32 s35, s31, 0
	s_cmp_eq_u32 s56, 40
	s_cselect_b32 s39, s9, s35
	s_cselect_b32 s38, s8, s34
	s_cselect_b32 s37, s29, s55
	s_cselect_b32 s36, s28, s54
	v_lshl_add_u64 v[184:185], s[30:31], 0, v[160:161]
	s_add_i32 m0, s42, 0xc000
	ds_read_b128 v[176:179], v191
	ds_read_b128 v[180:183], v191 offset:1024
	ds_read_b128 v[192:195], v191 offset:2048
	ds_read_b128 v[198:201], v191 offset:3072
	ds_read_b128 v[204:207], v191 offset:4096
	ds_read_b128 v[208:211], v191 offset:5120
	ds_read_b128 v[212:215], v191 offset:6144
	ds_read_b128 v[216:219], v191 offset:7168
	global_load_lds_dwordx4 v[184:185], off
	v_lshl_add_u64 v[184:185], s[30:31], 0, v[162:163]
	s_add_i32 m0, s42, 0xe000
	s_nop 0
	global_load_lds_dwordx4 v[184:185], off
	s_waitcnt vmcnt(8)
	s_waitcnt lgkmcnt(0)
	s_barrier
	s_setprio 0
	s_waitcnt lgkmcnt(0)
	v_mfma_f32_16x16x32_bf16 v[124:127], v[128:131], v[176:179], v[124:127]
	v_mfma_f32_16x16x32_bf16 v[120:123], v[136:139], v[176:179], v[120:123]
	v_mfma_f32_16x16x32_bf16 v[108:111], v[128:131], v[192:195], v[108:111]
	v_mfma_f32_16x16x32_bf16 v[104:107], v[136:139], v[192:195], v[104:107]
	v_mfma_f32_16x16x32_bf16 v[92:95], v[128:131], v[204:207], v[92:95]
	v_mfma_f32_16x16x32_bf16 v[88:91], v[136:139], v[204:207], v[88:91]
	v_mfma_f32_16x16x32_bf16 v[76:79], v[128:131], v[212:215], v[76:79]
	v_mfma_f32_16x16x32_bf16 v[72:75], v[136:139], v[212:215], v[72:75]
	v_mfma_f32_16x16x32_bf16 v[124:127], v[132:135], v[180:183], v[124:127]
	v_mfma_f32_16x16x32_bf16 v[120:123], v[140:143], v[180:183], v[120:123]
	v_mfma_f32_16x16x32_bf16 v[108:111], v[132:135], v[198:201], v[108:111]
	v_mfma_f32_16x16x32_bf16 v[104:107], v[140:143], v[198:201], v[104:107]
	v_mfma_f32_16x16x32_bf16 v[92:95], v[132:135], v[208:211], v[92:95]
	v_mfma_f32_16x16x32_bf16 v[88:91], v[140:143], v[208:211], v[88:91]
	v_mfma_f32_16x16x32_bf16 v[76:79], v[132:135], v[216:219], v[76:79]
	v_mfma_f32_16x16x32_bf16 v[72:75], v[140:143], v[216:219], v[72:75]
	v_mfma_f32_16x16x32_bf16 v[116:119], v[144:147], v[176:179], v[116:119]
	v_mfma_f32_16x16x32_bf16 v[112:115], v[168:171], v[176:179], v[112:115]
	v_mfma_f32_16x16x32_bf16 v[100:103], v[144:147], v[192:195], v[100:103]
	v_mfma_f32_16x16x32_bf16 v[96:99], v[168:171], v[192:195], v[96:99]
	v_mfma_f32_16x16x32_bf16 v[84:87], v[144:147], v[204:207], v[84:87]
	v_mfma_f32_16x16x32_bf16 v[80:83], v[168:171], v[204:207], v[80:83]
	v_mfma_f32_16x16x32_bf16 v[68:71], v[144:147], v[212:215], v[68:71]
	v_mfma_f32_16x16x32_bf16 v[64:67], v[168:171], v[212:215], v[64:67]
	v_mfma_f32_16x16x32_bf16 v[116:119], v[148:151], v[180:183], v[116:119]
	v_mfma_f32_16x16x32_bf16 v[112:115], v[172:175], v[180:183], v[112:115]
	v_mfma_f32_16x16x32_bf16 v[100:103], v[148:151], v[198:201], v[100:103]
	v_mfma_f32_16x16x32_bf16 v[96:99], v[172:175], v[198:201], v[96:99]
	v_mfma_f32_16x16x32_bf16 v[84:87], v[148:151], v[208:211], v[84:87]
	v_mfma_f32_16x16x32_bf16 v[80:83], v[172:175], v[208:211], v[80:83]
	v_mfma_f32_16x16x32_bf16 v[68:71], v[148:151], v[216:219], v[68:71]
	v_mfma_f32_16x16x32_bf16 v[64:67], v[172:175], v[216:219], v[64:67]
	s_setprio 1
	s_barrier
	s_add_i32 s30, s48, s41
	v_lshl_add_u64 v[184:185], s[36:37], 0, v[154:155]
	s_mov_b32 m0, s30
	ds_read_b128 v[176:179], v191 offset:16384
	ds_read_b128 v[180:183], v191 offset:17408
	ds_read_b128 v[192:195], v191 offset:18432
	ds_read_b128 v[198:201], v191 offset:19456
	ds_read_b128 v[204:207], v191 offset:20480
	ds_read_b128 v[208:211], v191 offset:21504
	ds_read_b128 v[212:215], v191 offset:22528
	ds_read_b128 v[216:219], v191 offset:23552
	global_load_lds_dwordx4 v[184:185], off
	s_add_i32 m0, s30, 0x2000
	s_add_u32 s30, s36, 0xb0000
	v_lshl_add_u64 v[220:221], s[36:37], 0, v[158:159]
	s_addc_u32 s31, s37, 0
	s_add_i32 s57, s49, s41
	global_load_lds_dwordx4 v[220:221], off
	v_lshl_add_u64 v[222:223], s[30:31], 0, v[154:155]
	s_mov_b32 m0, s57
	v_lshl_add_u64 v[224:225], s[38:39], 0, v[156:157]
	global_load_lds_dwordx4 v[222:223], off
	v_lshl_add_u64 v[222:223], s[30:31], 0, v[158:159]
	s_add_i32 m0, s57, 0x2000
	s_nop 0
	global_load_lds_dwordx4 v[222:223], off
	v_lshl_add_u64 v[222:223], s[38:39], 0, v[152:153]
	s_mov_b32 m0, s42
	s_nop 0
	global_load_lds_dwordx4 v[222:223], off
	s_mov_b32 m0, s33
	s_nop 0
	global_load_lds_dwordx4 v[224:225], off
	s_waitcnt vmcnt(8)
	s_waitcnt lgkmcnt(0)
	s_barrier
	s_setprio 0
	s_waitcnt lgkmcnt(0)
	v_mfma_f32_16x16x32_bf16 v[60:63], v[128:131], v[176:179], v[60:63]
	v_mfma_f32_16x16x32_bf16 v[56:59], v[136:139], v[176:179], v[56:59]
	v_mfma_f32_16x16x32_bf16 v[44:47], v[128:131], v[192:195], v[44:47]
	v_mfma_f32_16x16x32_bf16 v[40:43], v[136:139], v[192:195], v[40:43]
	v_mfma_f32_16x16x32_bf16 v[28:31], v[128:131], v[204:207], v[28:31]
	v_mfma_f32_16x16x32_bf16 v[24:27], v[136:139], v[204:207], v[24:27]
	v_mfma_f32_16x16x32_bf16 v[12:15], v[128:131], v[212:215], v[12:15]
	v_mfma_f32_16x16x32_bf16 v[8:11], v[136:139], v[212:215], v[8:11]
	v_mfma_f32_16x16x32_bf16 v[60:63], v[132:135], v[180:183], v[60:63]
	v_mfma_f32_16x16x32_bf16 v[56:59], v[140:143], v[180:183], v[56:59]
	v_mfma_f32_16x16x32_bf16 v[44:47], v[132:135], v[198:201], v[44:47]
	v_mfma_f32_16x16x32_bf16 v[40:43], v[140:143], v[198:201], v[40:43]
	v_mfma_f32_16x16x32_bf16 v[28:31], v[132:135], v[208:211], v[28:31]
	v_mfma_f32_16x16x32_bf16 v[24:27], v[140:143], v[208:211], v[24:27]
	v_mfma_f32_16x16x32_bf16 v[12:15], v[132:135], v[216:219], v[12:15]
	v_mfma_f32_16x16x32_bf16 v[8:11], v[140:143], v[216:219], v[8:11]
	v_mfma_f32_16x16x32_bf16 v[52:55], v[144:147], v[176:179], v[52:55]
	v_mfma_f32_16x16x32_bf16 v[48:51], v[168:171], v[176:179], v[48:51]
	v_mfma_f32_16x16x32_bf16 v[36:39], v[144:147], v[192:195], v[36:39]
	v_mfma_f32_16x16x32_bf16 v[32:35], v[168:171], v[192:195], v[32:35]
	v_mfma_f32_16x16x32_bf16 v[20:23], v[144:147], v[204:207], v[20:23]
	v_mfma_f32_16x16x32_bf16 v[16:19], v[168:171], v[204:207], v[16:19]
	v_mfma_f32_16x16x32_bf16 v[4:7], v[144:147], v[212:215], v[4:7]
	v_mfma_f32_16x16x32_bf16 v[0:3], v[168:171], v[212:215], v[0:3]
	v_mfma_f32_16x16x32_bf16 v[52:55], v[148:151], v[180:183], v[52:55]
	v_mfma_f32_16x16x32_bf16 v[48:51], v[172:175], v[180:183], v[48:51]
	v_mfma_f32_16x16x32_bf16 v[36:39], v[148:151], v[198:201], v[36:39]
	v_mfma_f32_16x16x32_bf16 v[32:35], v[172:175], v[198:201], v[32:35]
	v_mfma_f32_16x16x32_bf16 v[20:23], v[148:151], v[208:211], v[20:23]
	v_mfma_f32_16x16x32_bf16 v[16:19], v[172:175], v[208:211], v[16:19]
	v_mfma_f32_16x16x32_bf16 v[4:7], v[148:151], v[216:219], v[4:7]
	v_mfma_f32_16x16x32_bf16 v[0:3], v[172:175], v[216:219], v[0:3]
	s_setprio 1
	s_barrier
	s_add_i32 s57, 0, 0x18000
	s_add_i32 s58, 0, 0x1c000
	v_add_u32_e32 v140, s57, v187
	v_add_u32_e32 v172, s58, v187
	ds_read_b128 v[128:131], v140
	ds_read_b128 v[132:135], v140 offset:1024
	ds_read_b128 v[136:139], v140 offset:2048
	ds_read_b128 v[140:143], v140 offset:3072
	ds_read_b128 v[144:147], v172
	ds_read_b128 v[148:151], v172 offset:1024
	ds_read_b128 v[168:171], v172 offset:2048
	ds_read_b128 v[172:175], v172 offset:3072
	s_add_u32 s30, s38, 0xb0000
	s_addc_u32 s31, s39, 0
	s_mov_b32 m0, s43
	v_lshl_add_u64 v[226:227], s[30:31], 0, v[152:153]
	ds_read_b128 v[176:179], v191 offset:32768
	ds_read_b128 v[180:183], v191 offset:33792
	ds_read_b128 v[192:195], v191 offset:34816
	ds_read_b128 v[198:201], v191 offset:35840
	ds_read_b128 v[204:207], v191 offset:36864
	ds_read_b128 v[208:211], v191 offset:37888
	ds_read_b128 v[212:215], v191 offset:38912
	ds_read_b128 v[216:219], v191 offset:39936
	global_load_lds_dwordx4 v[226:227], off
	v_lshl_add_u64 v[226:227], s[30:31], 0, v[156:157]
	s_mov_b32 m0, s44
	s_nop 0
	global_load_lds_dwordx4 v[226:227], off
	s_waitcnt vmcnt(8)
	s_waitcnt lgkmcnt(0)
	s_barrier
	s_setprio 0
	s_waitcnt lgkmcnt(0)
	v_mfma_f32_16x16x32_bf16 v[124:127], v[128:131], v[176:179], v[124:127]
	v_mfma_f32_16x16x32_bf16 v[120:123], v[136:139], v[176:179], v[120:123]
	v_mfma_f32_16x16x32_bf16 v[108:111], v[128:131], v[192:195], v[108:111]
	v_mfma_f32_16x16x32_bf16 v[104:107], v[136:139], v[192:195], v[104:107]
	v_mfma_f32_16x16x32_bf16 v[92:95], v[128:131], v[204:207], v[92:95]
	v_mfma_f32_16x16x32_bf16 v[88:91], v[136:139], v[204:207], v[88:91]
	v_mfma_f32_16x16x32_bf16 v[76:79], v[128:131], v[212:215], v[76:79]
	v_mfma_f32_16x16x32_bf16 v[72:75], v[136:139], v[212:215], v[72:75]
	v_mfma_f32_16x16x32_bf16 v[124:127], v[132:135], v[180:183], v[124:127]
	v_mfma_f32_16x16x32_bf16 v[120:123], v[140:143], v[180:183], v[120:123]
	v_mfma_f32_16x16x32_bf16 v[108:111], v[132:135], v[198:201], v[108:111]
	v_mfma_f32_16x16x32_bf16 v[104:107], v[140:143], v[198:201], v[104:107]
	v_mfma_f32_16x16x32_bf16 v[92:95], v[132:135], v[208:211], v[92:95]
	v_mfma_f32_16x16x32_bf16 v[88:91], v[140:143], v[208:211], v[88:91]
	v_mfma_f32_16x16x32_bf16 v[76:79], v[132:135], v[216:219], v[76:79]
	v_mfma_f32_16x16x32_bf16 v[72:75], v[140:143], v[216:219], v[72:75]
	v_mfma_f32_16x16x32_bf16 v[116:119], v[144:147], v[176:179], v[116:119]
	v_mfma_f32_16x16x32_bf16 v[112:115], v[168:171], v[176:179], v[112:115]
	v_mfma_f32_16x16x32_bf16 v[100:103], v[144:147], v[192:195], v[100:103]
	v_mfma_f32_16x16x32_bf16 v[96:99], v[168:171], v[192:195], v[96:99]
	v_mfma_f32_16x16x32_bf16 v[84:87], v[144:147], v[204:207], v[84:87]
	v_mfma_f32_16x16x32_bf16 v[80:83], v[168:171], v[204:207], v[80:83]
	v_mfma_f32_16x16x32_bf16 v[68:71], v[144:147], v[212:215], v[68:71]
	v_mfma_f32_16x16x32_bf16 v[64:67], v[168:171], v[212:215], v[64:67]
	v_mfma_f32_16x16x32_bf16 v[116:119], v[148:151], v[180:183], v[116:119]
	v_mfma_f32_16x16x32_bf16 v[112:115], v[172:175], v[180:183], v[112:115]
	v_mfma_f32_16x16x32_bf16 v[100:103], v[148:151], v[198:201], v[100:103]
	v_mfma_f32_16x16x32_bf16 v[96:99], v[172:175], v[198:201], v[96:99]
	v_mfma_f32_16x16x32_bf16 v[84:87], v[148:151], v[208:211], v[84:87]
	v_mfma_f32_16x16x32_bf16 v[80:83], v[172:175], v[208:211], v[80:83]
	v_mfma_f32_16x16x32_bf16 v[68:71], v[148:151], v[216:219], v[68:71]
	v_mfma_f32_16x16x32_bf16 v[64:67], v[172:175], v[216:219], v[64:67]
	s_setprio 1
	s_barrier
	s_add_i32 s30, s57, s41
	v_lshl_add_u64 v[184:185], v[184:185], 0, s[24:25]
	s_mov_b32 m0, s30
	ds_read_b128 v[176:179], v191 offset:49152
	ds_read_b128 v[180:183], v191 offset:50176
	ds_read_b128 v[192:195], v191 offset:51200
	ds_read_b128 v[198:201], v191 offset:52224
	ds_read_b128 v[204:207], v191 offset:53248
	ds_read_b128 v[208:211], v191 offset:54272
	ds_read_b128 v[212:215], v191 offset:55296
	ds_read_b128 v[216:219], v191 offset:56320
	global_load_lds_dwordx4 v[184:185], off
	s_add_i32 m0, s30, 0x2000
	s_add_u32 s30, s36, 0xb0080
	v_lshl_add_u64 v[184:185], v[220:221], 0, s[24:25]
	s_addc_u32 s31, s37, 0
	s_add_i32 s36, s58, s41
	global_load_lds_dwordx4 v[184:185], off
	v_lshl_add_u64 v[184:185], s[30:31], 0, v[154:155]
	s_mov_b32 m0, s36
	s_nop 0
	global_load_lds_dwordx4 v[184:185], off
	v_lshl_add_u64 v[184:185], s[30:31], 0, v[158:159]
	s_add_i32 m0, s36, 0x2000
	s_nop 0
	global_load_lds_dwordx4 v[184:185], off
	v_lshl_add_u64 v[184:185], v[222:223], 0, s[24:25]
	s_mov_b32 m0, s46
	s_nop 0
	global_load_lds_dwordx4 v[184:185], off
	v_lshl_add_u64 v[184:185], v[224:225], 0, s[24:25]
	s_mov_b32 m0, s47
	s_nop 0
	global_load_lds_dwordx4 v[184:185], off
	s_waitcnt vmcnt(8)
	s_waitcnt lgkmcnt(0)
	s_barrier
	s_setprio 0
	s_waitcnt lgkmcnt(0)
	v_mfma_f32_16x16x32_bf16 v[60:63], v[128:131], v[176:179], v[60:63]
	v_mfma_f32_16x16x32_bf16 v[56:59], v[136:139], v[176:179], v[56:59]
	v_mfma_f32_16x16x32_bf16 v[44:47], v[128:131], v[192:195], v[44:47]
	v_mfma_f32_16x16x32_bf16 v[40:43], v[136:139], v[192:195], v[40:43]
	v_mfma_f32_16x16x32_bf16 v[28:31], v[128:131], v[204:207], v[28:31]
	v_mfma_f32_16x16x32_bf16 v[24:27], v[136:139], v[204:207], v[24:27]
	v_mfma_f32_16x16x32_bf16 v[12:15], v[128:131], v[212:215], v[12:15]
	v_mfma_f32_16x16x32_bf16 v[8:11], v[136:139], v[212:215], v[8:11]
	v_mfma_f32_16x16x32_bf16 v[60:63], v[132:135], v[180:183], v[60:63]
	v_mfma_f32_16x16x32_bf16 v[56:59], v[140:143], v[180:183], v[56:59]
	v_mfma_f32_16x16x32_bf16 v[44:47], v[132:135], v[198:201], v[44:47]
	v_mfma_f32_16x16x32_bf16 v[40:43], v[140:143], v[198:201], v[40:43]
	v_mfma_f32_16x16x32_bf16 v[28:31], v[132:135], v[208:211], v[28:31]
	v_mfma_f32_16x16x32_bf16 v[24:27], v[140:143], v[208:211], v[24:27]
	v_mfma_f32_16x16x32_bf16 v[12:15], v[132:135], v[216:219], v[12:15]
	v_mfma_f32_16x16x32_bf16 v[8:11], v[140:143], v[216:219], v[8:11]
	v_mfma_f32_16x16x32_bf16 v[52:55], v[144:147], v[176:179], v[52:55]
	v_mfma_f32_16x16x32_bf16 v[48:51], v[168:171], v[176:179], v[48:51]
	v_mfma_f32_16x16x32_bf16 v[36:39], v[144:147], v[192:195], v[36:39]
	v_mfma_f32_16x16x32_bf16 v[32:35], v[168:171], v[192:195], v[32:35]
	v_mfma_f32_16x16x32_bf16 v[20:23], v[144:147], v[204:207], v[20:23]
	v_mfma_f32_16x16x32_bf16 v[16:19], v[168:171], v[204:207], v[16:19]
	v_mfma_f32_16x16x32_bf16 v[4:7], v[144:147], v[212:215], v[4:7]
	v_mfma_f32_16x16x32_bf16 v[0:3], v[168:171], v[212:215], v[0:3]
	v_mfma_f32_16x16x32_bf16 v[52:55], v[148:151], v[180:183], v[52:55]
	v_mfma_f32_16x16x32_bf16 v[48:51], v[172:175], v[180:183], v[48:51]
	v_mfma_f32_16x16x32_bf16 v[36:39], v[148:151], v[198:201], v[36:39]
	v_mfma_f32_16x16x32_bf16 v[32:35], v[172:175], v[198:201], v[32:35]
	v_mfma_f32_16x16x32_bf16 v[20:23], v[148:151], v[208:211], v[20:23]
	v_mfma_f32_16x16x32_bf16 v[16:19], v[172:175], v[208:211], v[16:19]
	v_mfma_f32_16x16x32_bf16 v[4:7], v[148:151], v[216:219], v[4:7]
	v_mfma_f32_16x16x32_bf16 v[0:3], v[172:175], v[216:219], v[0:3]
	s_setprio 1
	s_barrier
	s_add_i32 s56, s56, 2
	s_add_u32 s54, s54, 0x100
	s_addc_u32 s55, s55, 0
	s_cmp_gt_u32 s56, 41
	s_mov_b64 s[30:31], s[34:35]
	s_cbranch_scc0 .LBB0_1124
	s_and_b64 vcc, exec, s[26:27]
	s_cbranch_vccz .LBB0_1127
	s_barrier
.LBB0_1127:
	s_setprio 0
	v_lshl_or_b32 v168, s10, 8, v188
	v_lshl_add_u32 v172, s53, 8, v186
	v_ashrrev_i32_e32 v169, 31, v168
	v_lshlrev_b64 v[204:205], 1, v[168:169]
	v_ashrrev_i32_e32 v173, 31, v172
	v_lshl_add_u64 v[170:171], s[16:17], 0, v[204:205]
	v_lshlrev_b64 v[206:207], 11, v[172:173]
	v_lshl_add_u64 v[128:129], v[170:171], 0, v[206:207]
	global_load_dwordx4 v[192:195], v[128:129], off
	global_load_dwordx4 v[198:201], v[128:129], off offset:256
	v_or_b32_e32 v182, 16, v172
	v_or_b32_e32 v178, 32, v172
	v_or_b32_e32 v174, 48, v172
	v_ashrrev_i32_e32 v183, 31, v182
	v_ashrrev_i32_e32 v179, 31, v178
	v_ashrrev_i32_e32 v175, 31, v174
	v_lshlrev_b64 v[184:185], 11, v[182:183]
	v_lshlrev_b64 v[180:181], 11, v[178:179]
	v_lshlrev_b64 v[176:177], 11, v[174:175]
	v_lshl_add_u64 v[128:129], v[170:171], 0, v[184:185]
	v_lshl_add_u64 v[130:131], v[170:171], 0, v[180:181]
	v_lshl_add_u64 v[208:209], v[170:171], 0, v[176:177]
	global_load_dwordx4 v[148:151], v[128:129], off
	global_load_dwordx4 v[144:147], v[128:129], off offset:256
	global_load_dwordx4 v[140:143], v[130:131], off
	global_load_dwordx4 v[136:139], v[130:131], off offset:256
	global_load_dwordx4 v[132:135], v[208:209], off
	s_nop 0
	global_load_dwordx4 v[128:131], v[208:209], off offset:256
	s_lshl_b32 s30, s10, 2
	s_ashr_i32 s31, s30, 31
	s_waitcnt vmcnt(0)
	v_lshlrev_b32_e32 v208, 16, v192
	v_and_b32_e32 v209, 0xffff0000, v192
	v_lshlrev_b32_e32 v192, 16, v193
	v_and_b32_e32 v193, 0xffff0000, v193
	v_lshlrev_b32_e32 v210, 16, v194
	v_and_b32_e32 v211, 0xffff0000, v194
	v_lshlrev_b32_e32 v194, 16, v195
	v_and_b32_e32 v195, 0xffff0000, v195
	v_lshlrev_b32_e32 v212, 16, v198
	v_and_b32_e32 v213, 0xffff0000, v198
	v_lshlrev_b32_e32 v198, 16, v199
	v_and_b32_e32 v199, 0xffff0000, v199
	v_lshlrev_b32_e32 v214, 16, v200
	v_and_b32_e32 v215, 0xffff0000, v200
	v_lshlrev_b32_e32 v200, 16, v201
	v_and_b32_e32 v201, 0xffff0000, v201
	v_pk_add_f32 v[126:127], v[126:127], v[192:193]
	v_pk_add_f32 v[124:125], v[124:125], v[208:209]
	v_pk_add_f32 v[122:123], v[122:123], v[194:195]
	v_pk_add_f32 v[120:121], v[120:121], v[210:211]
	v_pk_add_f32 v[118:119], v[118:119], v[198:199]
	v_pk_add_f32 v[116:117], v[116:117], v[212:213]
	v_pk_add_f32 v[192:193], v[114:115], v[200:201]
	v_pk_add_f32 v[194:195], v[112:113], v[214:215]
	v_mul_f32_e32 v198, v125, v125
	v_mul_f32_e32 v199, v127, v127
	v_mul_f32_e32 v200, v121, v121
	v_mul_f32_e32 v201, v123, v123
	v_cvt_pk_bf16_f32 v112, v124, v125
	v_cvt_pk_bf16_f32 v113, v126, v127
	v_cvt_pk_bf16_f32 v114, v120, v121
	v_cvt_pk_bf16_f32 v115, v122, v123
	v_mul_f32_e32 v121, v117, v117
	v_mul_f32_e32 v123, v119, v119
	v_mul_f32_e32 v125, v195, v195
	v_mul_f32_e32 v127, v193, v193
	v_fmac_f32_e32 v198, v124, v124
	v_fmac_f32_e32 v199, v126, v126
	v_fmac_f32_e32 v200, v120, v120
	v_fmac_f32_e32 v201, v122, v122
	v_fmac_f32_e32 v121, v116, v116
	v_fmac_f32_e32 v123, v118, v118
	v_fmac_f32_e32 v125, v194, v194
	v_fmac_f32_e32 v127, v192, v192
	v_add_f32_e32 v120, v198, v199
	v_add_f32_e32 v122, v200, v201
	v_add_f32_e32 v121, v121, v123
	v_add_f32_e32 v123, v125, v127
	v_add_f32_e32 v120, v120, v122
	v_add_f32_e32 v121, v121, v123
	v_add_f32_e32 v122, v120, v121
	ds_bpermute_b32 v123, v196, v122
	v_lshl_add_u64 v[120:121], s[16:17], 0, v[206:207]
	v_lshl_add_u64 v[120:121], v[120:121], 0, v[204:205]
	global_store_dwordx4 v[120:121], v[112:115], off
	s_waitcnt lgkmcnt(0)
	s_nop 0
	v_add_f32_e32 v112, v122, v123
	ds_bpermute_b32 v113, v197, v112
	v_cvt_pk_bf16_f32 v114, v116, v117
	v_cvt_pk_bf16_f32 v115, v118, v119
	v_cvt_pk_bf16_f32 v116, v194, v195
	v_cvt_pk_bf16_f32 v117, v192, v193
	global_store_dwordx4 v[120:121], v[114:117], off offset:256
	s_and_saveexec_b64 s[34:35], s[4:5]
	s_cbranch_execz .LBB0_1129
	v_lshlrev_b64 v[114:115], 6, v[172:173]
	v_lshl_add_u64 v[114:115], s[22:23], 0, v[114:115]
	v_lshl_add_u64 v[114:115], s[30:31], 2, v[114:115]
	s_lshl_b32 s10, s45, 2
	v_lshl_add_u64 v[114:115], v[114:115], 0, s[10:11]
	s_waitcnt lgkmcnt(0)
	v_add_f32_e32 v112, v112, v113
	global_store_dword v[114:115], v112, off
